# GEMM K-loops: 44 LDS-DMA loads use the SGPR-base + 32-bit lane offset form instead of a 64-bit VALU address add before each load
# baseline (speedup 1.0000x reference)
; __device__ __forceinline__ int ltid(int wv) { int l; asm volatile("v_mbcnt_lo_u32_b32 %0, -1, 0\n\tv_mbcnt_hi_u32_b32 %0, -1, %0" : "=v"(l)); asm volatile("" : "+s"(wv)); return (wv << 6) | l; }
; #define PG8_STAGE(bufoff, gbase, voff) do { _Pragma("unroll") for (int _i = 0; _i < 2; ++_i) \
;         __builtin_amdgcn_global_load_lds((const unsigned*)((const char*)(gbase) + (voff)[_i]), (PG8_LAS unsigned*)(lds + (bufoff) + ldsw + _i * 8192), 16, 0, 0); } while (0)
; #define PG8_WAIT_V(n) asm volatile("s_waitcnt vmcnt(" #n ")" ::: "memory")
; #define PG8_BAR __builtin_amdgcn_s_barrier()
; template <class Epi, class Sched, bool ALIGN_EPI = false, bool SP2 = false>
; __device__ __forceinline__ void gemm_phase(PG8_LAS unsigned char* lds, const Gemm g, const Sched& S, const Epi& E, int wv) {
;     const int tid = ltid(wv), wid = __builtin_amdgcn_readfirstlane(tid >> 6), lane = tid & 63, wr = wid >> 2, wc = wid & 3, fr = lane & 15, fq = lane >> 4;
;     const int K = g.K, nt = K / BK;
;     unsigned voffA[2], voffB[2];
; #pragma unroll
;     for (int i = 0; i < 2; ++i) { int R, C; stage_rc(tid * 16 + i * 8192, R, C); const int Rb = Epi::PERM ? ((R & ~31) + perm32(R & 31)) : R;
;         voffA[i] = (unsigned)(R * g.lda + C) * 2u; voffB[i] = (unsigned)(Rb * K + C) * 2u; }
;     const size_t kstep = (size_t)(BK * 2);
;     const size_t hstepA = (size_t)HALF * g.lda * 2, hstepB = (size_t)HALF * K * 2;
;     const size_t tstepA = 2 * hstepA, tstepB = 2 * hstepB;
;     const unsigned ldsw = (unsigned)wid * 1024u;
;     const int aoff = lds_byte(wr * 64 + fr, fq * 8), boff = lds_byte(wc * 32 + fr, fq * 8);
;     ...
;         PG8_STAGE(PG8_SB(0, 0), cB, voffB); PG8_STAGE(PG8_SB(0, 1), cB + hstepB, voffB); PG8_STAGE(PG8_SA(0, 0), cA, voffA); PG8_STAGE(PG8_SA(0, 1), cA + hstepA, voffA);
;         if (wr == 1) PG8_BAR;
;         PG8_WAIT_V(2); PG8_BAR;
;         PG8_STAGE(PG8_SB(1, 0), cB + kstep, voffB); PG8_STAGE(PG8_SA(1, 0), cA + kstep, voffA); PG8_STAGE(PG8_SB(1, 1), cB + hstepB + kstep, voffB);
;         PG8_WAIT_V(6); PG8_BAR;
.LBB0_657:
	s_add_u32 s24, s16, 0x6800000
	s_addc_u32 s25, s17, 0
	s_add_u32 s26, s16, 0x2500000
	s_addc_u32 s27, s17, 0
	s_and_b32 s19, s28, 3
	s_add_i32 m0, s21, 0x18000
	v_lshl_add_u64 v[6:7], v[6:7], 0, s[62:63]
	s_lshl_b32 s87, s29, 6
	s_lshl_b32 s22, s29, 13
	s_lshl_b32 s90, s19, 5
	s_lshl_b32 s23, s19, 12
	s_waitcnt vmcnt(2)
	s_barrier
	global_load_lds_dwordx4 v[6:7], off
	v_lshl_add_u64 v[4:5], v[4:5], 0, s[62:63]
	s_add_i32 m0, s21, 0x1a000
	s_add_i32 s91, s21, 0x8000
	s_add_i32 s92, s21, 0xa000
	global_load_lds_dwordx4 v[4:5], off
	v_lshl_add_u64 v[2:3], v[2:3], 0, s[62:63]
	s_mov_b32 m0, s91
	s_add_u32 s28, s2, 0x40080
	global_load_lds_dwordx4 v[2:3], off
	v_lshl_add_u64 v[2:3], v[8:9], 0, s[62:63]
	s_mov_b32 m0, s92
	s_addc_u32 s29, s3, 0
	global_load_lds_dwordx4 v[2:3], off
	s_add_i32 m0, s21, 0x1c000
	s_nop 0
	global_load_lds_dwordx4 v0, s[28:29]
	v_lshl_add_u64 v[2:3], s[28:29], 0, v[134:135]
	s_add_i32 m0, s21, 0x1e000
	v_bfe_u32 v145, v10, 4, 2
	global_load_lds_dwordx4 v[2:3], off
	v_and_b32_e32 v144, 15, v10
	v_lshlrev_b32_e32 v2, 4, v145
	v_lshlrev_b32_e32 v3, 2, v10
	v_lshl_or_b32 v2, v144, 6, v2
	v_and_b32_e32 v3, 32, v3
	v_bitop3_b32 v4, v2, s22, v3 bitop3:0xde
	v_bitop3_b32 v146, v2, s23, v3 bitop3:0xde
	s_cmpk_lt_u32 s15, 0x100
	v_lshlrev_b32_e32 v2, 14, v11
	s_cselect_b64 s[28:29], -1, 0
	s_cmp_eq_u32 s19, 0
	v_and_b32_e32 v2, 0xffff8000, v2
	s_cselect_b64 s[36:37], -1, 0
	s_ashr_i32 s94, s12, 31
	s_ashr_i32 s95, s7, 31
	s_lshl_b32 s15, s19, 2
	v_lshl_add_u32 v2, v12, 11, v2
	v_and_b32_e32 v3, 1, v11
	s_add_u32 s15, s16, s15
	v_lshl_or_b32 v2, v3, 6, v2
	s_addc_u32 s16, s17, 0
	v_lshl_add_u32 v136, v13, 1, v2
	v_lshlrev_b32_e32 v2, 14, v14
	s_add_u32 s38, s15, 0x2600000
	v_and_b32_e32 v2, 0xffff8000, v2
	s_waitcnt vmcnt(6)
	s_addc_u32 s39, s16, 0
	v_lshl_add_u32 v2, v15, 11, v2
	v_and_b32_e32 v3, 1, v14
	s_add_u32 s40, s15, 0x2580000
	v_lshl_or_b32 v2, v3, 6, v2
	s_mov_b32 s93, 0
	s_addc_u32 s41, s16, 0
	v_mov_b32_e32 v137, v1
	v_lshl_add_u32 v138, v16, 1, v2
	v_mov_b32_e32 v139, v1
	v_add_u32_e32 v147, 0, v4
	s_barrier
	s_branch .LBB0_660

; #define PG8_STAGE(bufoff, gbase, voff) do { _Pragma("unroll") for (int _i = 0; _i < 2; ++_i) \
;         __builtin_amdgcn_global_load_lds((const unsigned*)((const char*)(gbase) + (voff)[_i]), (PG8_LAS unsigned*)(lds + (bufoff) + ldsw + _i * 8192), 16, 0, 0); } while (0)
; #define PG8_LDA(dst, b, h) do { _Pragma("unroll") for (int m = 0; m < 4; ++m) _Pragma("unroll") for (int k = 0; k < 2; ++k) dst[m][k] = *(const PG8_LAS bf16x8*)(lds + PG8_SA(b, h) + aoff + m * 2048 + k * 1024); } while (0)
; #define PG8_LDB(dst, b, h) do { _Pragma("unroll") for (int n = 0; n < 2; ++n) _Pragma("unroll") for (int k = 0; k < 2; ++k) dst[n][k] = *(const PG8_LAS bf16x8*)(lds + PG8_SB(b, h) + boff + n * 2048 + k * 1024); } while (0)
; #define PG8_MMA(ai, bj, At, Bt) do { __builtin_amdgcn_s_setprio(1); _Pragma("unroll") for (int m = 0; m < 4; ++m) _Pragma("unroll") for (int n = 0; n < 2; ++n) _Pragma("unroll") for (int k = 0; k < 2; ++k) \
;         acc[ai][bj][m][n] = __builtin_amdgcn_mfma_f32_16x16x32_bf16(Bt[n][k], At[m][k], acc[ai][bj][m][n], 0, 0, 0); __builtin_amdgcn_s_setprio(0); } while (0)
; #define PG8_WAIT_V(n) asm volatile("s_waitcnt vmcnt(" #n ")" ::: "memory")
; #define PG8_WAIT_L(n) asm volatile("s_waitcnt lgkmcnt(" #n ")" ::: "memory")
; #define PG8_BAR __builtin_amdgcn_s_barrier()
; #define PG8_SCHED __builtin_amdgcn_sched_barrier(0)
; template <class Epi, class Sched, bool ALIGN_EPI = false, bool SP2 = false>
; __device__ __forceinline__ void gemm_phase(PG8_LAS unsigned char* lds, const Gemm g, const Sched& S, const Epi& E, int wv) {
;     ...
;             const char* a2 = last ? nA : cA + (size_t)(t + 2) * kstep; const char* b2 = last ? nB : cB + (size_t)(t + 2) * kstep;
;             const char* a3 = a2 + kstep; const char* b3 = b2 + kstep;
;             if (last && has_next) S.a_ready(nxt);
;             if constexpr (SP2) {
;             PG8_LDB(B0, 0, 0); PG8_LDB(B1, 0, 1); PG8_SCHED; PG8_LDA(At, 0, 0); PG8_STAGE(PG8_SA(1, 1), a1 + hstepA, voffA);
;             PG8_WAIT_V(8); PG8_WAIT_L(0); PG8_BAR; PG8_MMA(0, 0, At, B0); PG8_MMA(0, 1, At, B1); PG8_BAR; PG8_SCHED;
;             PG8_LDA(At, 0, 1); PG8_STAGE(PG8_SB(0, 0), b2, voffB); PG8_STAGE(PG8_SB(0, 1), b2 + hstepB, voffB); PG8_STAGE(PG8_SA(0, 0), a2, voffA);
;             PG8_WAIT_V(8); PG8_WAIT_L(0); PG8_BAR; PG8_MMA(1, 0, At, B0); PG8_MMA(1, 1, At, B1); PG8_BAR; PG8_SCHED;
.LBB0_663:
	s_add_u32 s2, s34, 0xfffc0080
	s_addc_u32 s3, s35, -1
	s_add_i32 s22, 0, 0x10000
	s_cmp_eq_u32 vcc_lo, 12
	s_cselect_b32 s51, s15, s3
	s_cselect_b32 s50, s19, s2
	s_cselect_b32 s3, s43, s97
	s_cselect_b32 s2, s45, s96
	s_add_i32 s60, 0, 0x14000
	v_add_u32_e32 v156, s22, v146
	v_add_u32_e32 v172, s60, v146
	ds_read_b128 v[140:143], v156
	ds_read_b128 v[148:151], v156 offset:1024
	ds_read_b128 v[152:155], v156 offset:2048
	ds_read_b128 v[156:159], v156 offset:3072
	ds_read_b128 v[160:163], v172
	ds_read_b128 v[164:167], v172 offset:1024
	ds_read_b128 v[168:171], v172 offset:2048
	ds_read_b128 v[172:175], v172 offset:3072
	s_add_i32 m0, s21, 0xc000
	ds_read_b128 v[176:179], v147
	ds_read_b128 v[180:183], v147 offset:1024
	ds_read_b128 v[184:187], v147 offset:2048
	ds_read_b128 v[242:245], v147 offset:3072
	ds_read_b128 v[246:249], v147 offset:4096
	ds_read_b128 v[250:253], v147 offset:5120
	ds_read_b128 v[220:223], v147 offset:6144
	ds_read_b128 v[224:227], v147 offset:7168
	global_load_lds_dwordx4 v136, s[34:35]
	s_add_i32 m0, s21, 0xe000
	s_nop 0
	global_load_lds_dwordx4 v138, s[34:35]
	s_waitcnt vmcnt(8)
	s_waitcnt lgkmcnt(0)
	s_barrier
	s_setprio 1
	s_waitcnt lgkmcnt(0)
	v_mfma_f32_16x16x32_bf16 v[126:129], v[140:143], v[176:179], v[126:129]
	v_mfma_f32_16x16x32_bf16 v[122:125], v[152:155], v[176:179], v[122:125]
	v_mfma_f32_16x16x32_bf16 v[110:113], v[140:143], v[184:187], v[110:113]
	v_mfma_f32_16x16x32_bf16 v[106:109], v[152:155], v[184:187], v[106:109]
	v_mfma_f32_16x16x32_bf16 v[94:97], v[140:143], v[246:249], v[94:97]
	v_mfma_f32_16x16x32_bf16 v[90:93], v[152:155], v[246:249], v[90:93]
	v_mfma_f32_16x16x32_bf16 v[78:81], v[140:143], v[220:223], v[78:81]
	v_mfma_f32_16x16x32_bf16 v[74:77], v[152:155], v[220:223], v[74:77]
	v_mfma_f32_16x16x32_bf16 v[126:129], v[148:151], v[180:183], v[126:129]
	v_mfma_f32_16x16x32_bf16 v[122:125], v[156:159], v[180:183], v[122:125]
	v_mfma_f32_16x16x32_bf16 v[110:113], v[148:151], v[242:245], v[110:113]
	v_mfma_f32_16x16x32_bf16 v[106:109], v[156:159], v[242:245], v[106:109]
	v_mfma_f32_16x16x32_bf16 v[94:97], v[148:151], v[250:253], v[94:97]
	v_mfma_f32_16x16x32_bf16 v[90:93], v[156:159], v[250:253], v[90:93]
	v_mfma_f32_16x16x32_bf16 v[78:81], v[148:151], v[224:227], v[78:81]
	v_mfma_f32_16x16x32_bf16 v[74:77], v[156:159], v[224:227], v[74:77]
	s_setprio 0
	s_setprio 1
	v_mfma_f32_16x16x32_bf16 v[118:121], v[160:163], v[176:179], v[118:121]
	v_mfma_f32_16x16x32_bf16 v[114:117], v[168:171], v[176:179], v[114:117]
	v_mfma_f32_16x16x32_bf16 v[102:105], v[160:163], v[184:187], v[102:105]
	v_mfma_f32_16x16x32_bf16 v[98:101], v[168:171], v[184:187], v[98:101]
	v_mfma_f32_16x16x32_bf16 v[86:89], v[160:163], v[246:249], v[86:89]
	v_mfma_f32_16x16x32_bf16 v[82:85], v[168:171], v[246:249], v[82:85]
	v_mfma_f32_16x16x32_bf16 v[70:73], v[160:163], v[220:223], v[70:73]
	v_mfma_f32_16x16x32_bf16 v[66:69], v[168:171], v[220:223], v[66:69]
	v_mfma_f32_16x16x32_bf16 v[118:121], v[164:167], v[180:183], v[118:121]
	v_mfma_f32_16x16x32_bf16 v[114:117], v[172:175], v[180:183], v[114:117]
	v_mfma_f32_16x16x32_bf16 v[102:105], v[164:167], v[242:245], v[102:105]
	v_mfma_f32_16x16x32_bf16 v[98:101], v[172:175], v[242:245], v[98:101]
	v_mfma_f32_16x16x32_bf16 v[86:89], v[164:167], v[250:253], v[86:89]
	v_mfma_f32_16x16x32_bf16 v[82:85], v[172:175], v[250:253], v[82:85]
	v_mfma_f32_16x16x32_bf16 v[70:73], v[164:167], v[224:227], v[70:73]
	v_mfma_f32_16x16x32_bf16 v[66:69], v[172:175], v[224:227], v[66:69]
	s_setprio 0
	s_barrier
	s_add_i32 s22, s22, s55
	v_lshl_add_u64 v[196:197], s[2:3], 0, v[0:1]
	s_mov_b32 m0, s22
	ds_read_b128 v[176:179], v147 offset:16384
	ds_read_b128 v[180:183], v147 offset:17408
	ds_read_b128 v[184:187], v147 offset:18432
	ds_read_b128 v[220:223], v147 offset:19456
	ds_read_b128 v[224:227], v147 offset:20480
	ds_read_b128 v[242:245], v147 offset:21504
	ds_read_b128 v[246:249], v147 offset:22528
	ds_read_b128 v[250:253], v147 offset:23552
	global_load_lds_dwordx4 v[196:197], off
	s_add_i32 m0, s22, 0x2000
	s_add_u32 s22, s2, 0x40000
	v_lshl_add_u64 v[228:229], s[2:3], 0, v[134:135]
	s_addc_u32 s23, s3, 0
	s_add_i32 s60, s60, s55
	global_load_lds_dwordx4 v[228:229], off
	s_mov_b32 m0, s60
	v_lshl_add_u64 v[232:233], s[50:51], 0, v[132:133]
	global_load_lds_dwordx4 v0, s[22:23]
	s_add_i32 m0, s60, 0x2000
	s_nop 0
	global_load_lds_dwordx4 v134, s[22:23]
	v_lshl_add_u64 v[230:231], s[50:51], 0, v[130:131]
	s_mov_b32 m0, s21
	s_nop 0
	global_load_lds_dwordx4 v[230:231], off
	s_mov_b32 m0, s58
	s_nop 0
	global_load_lds_dwordx4 v[232:233], off
	s_waitcnt vmcnt(8)
	s_waitcnt lgkmcnt(0)
	s_barrier
; #define PG8_STAGE(bufoff, gbase, voff) do { _Pragma("unroll") for (int _i = 0; _i < 2; ++_i) \
;         __builtin_amdgcn_global_load_lds((const unsigned*)((const char*)(gbase) + (voff)[_i]), (PG8_LAS unsigned*)(lds + (bufoff) + ldsw + _i * 8192), 16, 0, 0); } while (0)
; #define PG8_LDA(dst, b, h) do { _Pragma("unroll") for (int m = 0; m < 4; ++m) _Pragma("unroll") for (int k = 0; k < 2; ++k) dst[m][k] = *(const PG8_LAS bf16x8*)(lds + PG8_SA(b, h) + aoff + m * 2048 + k * 1024); } while (0)
; #define PG8_LDB(dst, b, h) do { _Pragma("unroll") for (int n = 0; n < 2; ++n) _Pragma("unroll") for (int k = 0; k < 2; ++k) dst[n][k] = *(const PG8_LAS bf16x8*)(lds + PG8_SB(b, h) + boff + n * 2048 + k * 1024); } while (0)
; #define PG8_MMA(ai, bj, At, Bt) do { __builtin_amdgcn_s_setprio(1); _Pragma("unroll") for (int m = 0; m < 4; ++m) _Pragma("unroll") for (int n = 0; n < 2; ++n) _Pragma("unroll") for (int k = 0; k < 2; ++k) \
;         acc[ai][bj][m][n] = __builtin_amdgcn_mfma_f32_16x16x32_bf16(Bt[n][k], At[m][k], acc[ai][bj][m][n], 0, 0, 0); __builtin_amdgcn_s_setprio(0); } while (0)
; #define PG8_WAIT_V(n) asm volatile("s_waitcnt vmcnt(" #n ")" ::: "memory")
; #define PG8_WAIT_L(n) asm volatile("s_waitcnt lgkmcnt(" #n ")" ::: "memory")
; #define PG8_BAR __builtin_amdgcn_s_barrier()
; #define PG8_SCHED __builtin_amdgcn_sched_barrier(0)
; template <class Epi, class Sched, bool ALIGN_EPI = false, bool SP2 = false>
; __device__ __forceinline__ void gemm_phase(PG8_LAS unsigned char* lds, const Gemm g, const Sched& S, const Epi& E, int wv) {
;     ...
;             PG8_WAIT_V(8); PG8_WAIT_L(0); PG8_BAR; PG8_MMA(1, 0, At, B0); PG8_MMA(1, 1, At, B1); PG8_BAR; PG8_SCHED;
;             PG8_LDB(B0, 1, 0); PG8_LDB(B1, 1, 1); PG8_SCHED; PG8_LDA(At, 1, 0); PG8_STAGE(PG8_SA(0, 1), a2 + hstepA, voffA);
;             PG8_WAIT_V(8); PG8_WAIT_L(0); PG8_BAR; PG8_MMA(0, 0, At, B0); PG8_MMA(0, 1, At, B1); PG8_BAR; PG8_SCHED;
	s_setprio 1
	s_waitcnt lgkmcnt(0)
	v_mfma_f32_16x16x32_bf16 v[62:65], v[140:143], v[176:179], v[62:65]
	v_mfma_f32_16x16x32_bf16 v[58:61], v[152:155], v[176:179], v[58:61]
	v_mfma_f32_16x16x32_bf16 v[46:49], v[140:143], v[184:187], v[46:49]
	v_mfma_f32_16x16x32_bf16 v[42:45], v[152:155], v[184:187], v[42:45]
	v_mfma_f32_16x16x32_bf16 v[30:33], v[140:143], v[224:227], v[30:33]
	v_mfma_f32_16x16x32_bf16 v[26:29], v[152:155], v[224:227], v[26:29]
	v_mfma_f32_16x16x32_bf16 v[14:17], v[140:143], v[246:249], v[14:17]
	v_mfma_f32_16x16x32_bf16 v[10:13], v[152:155], v[246:249], v[10:13]
	v_mfma_f32_16x16x32_bf16 v[62:65], v[148:151], v[180:183], v[62:65]
	v_mfma_f32_16x16x32_bf16 v[58:61], v[156:159], v[180:183], v[58:61]
	v_mfma_f32_16x16x32_bf16 v[46:49], v[148:151], v[220:223], v[46:49]
	v_mfma_f32_16x16x32_bf16 v[42:45], v[156:159], v[220:223], v[42:45]
	v_mfma_f32_16x16x32_bf16 v[30:33], v[148:151], v[242:245], v[30:33]
	v_mfma_f32_16x16x32_bf16 v[26:29], v[156:159], v[242:245], v[26:29]
	v_mfma_f32_16x16x32_bf16 v[14:17], v[148:151], v[250:253], v[14:17]
	v_mfma_f32_16x16x32_bf16 v[10:13], v[156:159], v[250:253], v[10:13]
	s_setprio 0
	s_setprio 1
	v_mfma_f32_16x16x32_bf16 v[54:57], v[160:163], v[176:179], v[54:57]
	v_mfma_f32_16x16x32_bf16 v[50:53], v[168:171], v[176:179], v[50:53]
	v_mfma_f32_16x16x32_bf16 v[38:41], v[160:163], v[184:187], v[38:41]
	v_mfma_f32_16x16x32_bf16 v[34:37], v[168:171], v[184:187], v[34:37]
	v_mfma_f32_16x16x32_bf16 v[22:25], v[160:163], v[224:227], v[22:25]
	v_mfma_f32_16x16x32_bf16 v[18:21], v[168:171], v[224:227], v[18:21]
	v_mfma_f32_16x16x32_bf16 v[6:9], v[160:163], v[246:249], v[6:9]
	v_mfma_f32_16x16x32_bf16 v[2:5], v[168:171], v[246:249], v[2:5]
	v_mfma_f32_16x16x32_bf16 v[54:57], v[164:167], v[180:183], v[54:57]
	v_mfma_f32_16x16x32_bf16 v[50:53], v[172:175], v[180:183], v[50:53]
	v_mfma_f32_16x16x32_bf16 v[38:41], v[164:167], v[220:223], v[38:41]
	v_mfma_f32_16x16x32_bf16 v[34:37], v[172:175], v[220:223], v[34:37]
	v_mfma_f32_16x16x32_bf16 v[22:25], v[164:167], v[242:245], v[22:25]
	v_mfma_f32_16x16x32_bf16 v[18:21], v[172:175], v[242:245], v[18:21]
	v_mfma_f32_16x16x32_bf16 v[6:9], v[164:167], v[250:253], v[6:9]
	v_mfma_f32_16x16x32_bf16 v[2:5], v[172:175], v[250:253], v[2:5]
	s_setprio 0
	s_barrier
	s_add_i32 s60, 0, 0x18000
	s_add_i32 s88, 0, 0x1c000
	v_add_u32_e32 v156, s60, v146
	v_add_u32_e32 v172, s88, v146
	ds_read_b128 v[140:143], v156
	ds_read_b128 v[148:151], v156 offset:1024
	ds_read_b128 v[152:155], v156 offset:2048
	ds_read_b128 v[156:159], v156 offset:3072
	ds_read_b128 v[160:163], v172
	ds_read_b128 v[164:167], v172 offset:1024
	ds_read_b128 v[168:171], v172 offset:2048
	ds_read_b128 v[172:175], v172 offset:3072
	s_add_u32 s22, s50, 0x40000
	s_addc_u32 s23, s51, 0
	s_mov_b32 m0, s82
	ds_read_b128 v[176:179], v147 offset:32768
	ds_read_b128 v[180:183], v147 offset:33792
	ds_read_b128 v[184:187], v147 offset:34816
	ds_read_b128 v[220:223], v147 offset:35840
	ds_read_b128 v[224:227], v147 offset:36864
	ds_read_b128 v[242:245], v147 offset:37888
	ds_read_b128 v[246:249], v147 offset:38912
	ds_read_b128 v[250:253], v147 offset:39936
	global_load_lds_dwordx4 v130, s[22:23]
	v_lshl_add_u64 v[234:235], s[22:23], 0, v[132:133]
	s_mov_b32 m0, s83
	s_nop 0
	global_load_lds_dwordx4 v[234:235], off
	s_waitcnt vmcnt(8)
	s_waitcnt lgkmcnt(0)
	s_barrier
	s_setprio 1
	s_waitcnt lgkmcnt(0)
	v_mfma_f32_16x16x32_bf16 v[126:129], v[140:143], v[176:179], v[126:129]
	v_mfma_f32_16x16x32_bf16 v[122:125], v[152:155], v[176:179], v[122:125]
	v_mfma_f32_16x16x32_bf16 v[110:113], v[140:143], v[184:187], v[110:113]
	v_mfma_f32_16x16x32_bf16 v[106:109], v[152:155], v[184:187], v[106:109]
	v_mfma_f32_16x16x32_bf16 v[94:97], v[140:143], v[224:227], v[94:97]
	v_mfma_f32_16x16x32_bf16 v[90:93], v[152:155], v[224:227], v[90:93]
	v_mfma_f32_16x16x32_bf16 v[78:81], v[140:143], v[246:249], v[78:81]
	v_mfma_f32_16x16x32_bf16 v[74:77], v[152:155], v[246:249], v[74:77]
	v_mfma_f32_16x16x32_bf16 v[126:129], v[148:151], v[180:183], v[126:129]
	v_mfma_f32_16x16x32_bf16 v[122:125], v[156:159], v[180:183], v[122:125]
	v_mfma_f32_16x16x32_bf16 v[110:113], v[148:151], v[220:223], v[110:113]
	v_mfma_f32_16x16x32_bf16 v[106:109], v[156:159], v[220:223], v[106:109]
	v_mfma_f32_16x16x32_bf16 v[94:97], v[148:151], v[242:245], v[94:97]
	v_mfma_f32_16x16x32_bf16 v[90:93], v[156:159], v[242:245], v[90:93]
	v_mfma_f32_16x16x32_bf16 v[78:81], v[148:151], v[250:253], v[78:81]
	v_mfma_f32_16x16x32_bf16 v[74:77], v[156:159], v[250:253], v[74:77]
	s_setprio 0
	s_setprio 1
	v_mfma_f32_16x16x32_bf16 v[118:121], v[160:163], v[176:179], v[118:121]
	v_mfma_f32_16x16x32_bf16 v[114:117], v[168:171], v[176:179], v[114:117]
	v_mfma_f32_16x16x32_bf16 v[102:105], v[160:163], v[184:187], v[102:105]
	v_mfma_f32_16x16x32_bf16 v[98:101], v[168:171], v[184:187], v[98:101]
	v_mfma_f32_16x16x32_bf16 v[86:89], v[160:163], v[224:227], v[86:89]
	v_mfma_f32_16x16x32_bf16 v[82:85], v[168:171], v[224:227], v[82:85]
	v_mfma_f32_16x16x32_bf16 v[70:73], v[160:163], v[246:249], v[70:73]
	v_mfma_f32_16x16x32_bf16 v[66:69], v[168:171], v[246:249], v[66:69]
	v_mfma_f32_16x16x32_bf16 v[118:121], v[164:167], v[180:183], v[118:121]
	v_mfma_f32_16x16x32_bf16 v[114:117], v[172:175], v[180:183], v[114:117]
	v_mfma_f32_16x16x32_bf16 v[102:105], v[164:167], v[220:223], v[102:105]
	v_mfma_f32_16x16x32_bf16 v[98:101], v[172:175], v[220:223], v[98:101]
	v_mfma_f32_16x16x32_bf16 v[86:89], v[164:167], v[242:245], v[86:89]
	v_mfma_f32_16x16x32_bf16 v[82:85], v[172:175], v[242:245], v[82:85]
	v_mfma_f32_16x16x32_bf16 v[70:73], v[164:167], v[250:253], v[70:73]
	v_mfma_f32_16x16x32_bf16 v[66:69], v[172:175], v[250:253], v[66:69]
	s_setprio 0
	s_barrier
; #define PG8_STAGE(bufoff, gbase, voff) do { _Pragma("unroll") for (int _i = 0; _i < 2; ++_i) \
;         __builtin_amdgcn_global_load_lds((const unsigned*)((const char*)(gbase) + (voff)[_i]), (PG8_LAS unsigned*)(lds + (bufoff) + ldsw + _i * 8192), 16, 0, 0); } while (0)
; #define PG8_LDA(dst, b, h) do { _Pragma("unroll") for (int m = 0; m < 4; ++m) _Pragma("unroll") for (int k = 0; k < 2; ++k) dst[m][k] = *(const PG8_LAS bf16x8*)(lds + PG8_SA(b, h) + aoff + m * 2048 + k * 1024); } while (0)
; #define PG8_MMA(ai, bj, At, Bt) do { __builtin_amdgcn_s_setprio(1); _Pragma("unroll") for (int m = 0; m < 4; ++m) _Pragma("unroll") for (int n = 0; n < 2; ++n) _Pragma("unroll") for (int k = 0; k < 2; ++k) \
;         acc[ai][bj][m][n] = __builtin_amdgcn_mfma_f32_16x16x32_bf16(Bt[n][k], At[m][k], acc[ai][bj][m][n], 0, 0, 0); __builtin_amdgcn_s_setprio(0); } while (0)
; #define PG8_WAIT_V(n) asm volatile("s_waitcnt vmcnt(" #n ")" ::: "memory")
; #define PG8_WAIT_L(n) asm volatile("s_waitcnt lgkmcnt(" #n ")" ::: "memory")
; #define PG8_BAR __builtin_amdgcn_s_barrier()
; #define PG8_SCHED __builtin_amdgcn_sched_barrier(0)
; template <class Epi, class Sched, bool ALIGN_EPI = false, bool SP2 = false>
; __device__ __forceinline__ void gemm_phase(PG8_LAS unsigned char* lds, const Gemm g, const Sched& S, const Epi& E, int wv) {
;     ...
;         for (int t = 0; t < nt; t += 2) {
;     ...
;             PG8_WAIT_V(8); PG8_WAIT_L(0); PG8_BAR; PG8_MMA(0, 0, At, B0); PG8_MMA(0, 1, At, B1); PG8_BAR; PG8_SCHED;
;             PG8_LDA(At, 1, 1); PG8_STAGE(PG8_SB(1, 0), b3, voffB); PG8_STAGE(PG8_SB(1, 1), b3 + hstepB, voffB); PG8_STAGE(PG8_SA(1, 0), a3, voffA);
;             PG8_WAIT_V(8); PG8_WAIT_L(0); PG8_BAR; PG8_MMA(1, 0, At, B0); PG8_MMA(1, 1, At, B1); PG8_BAR; PG8_SCHED;
	s_add_i32 s22, s60, s55
	v_lshl_add_u64 v[196:197], v[196:197], 0, s[62:63]
	s_mov_b32 m0, s22
	ds_read_b128 v[176:179], v147 offset:49152
	ds_read_b128 v[180:183], v147 offset:50176
	ds_read_b128 v[184:187], v147 offset:51200
	ds_read_b128 v[220:223], v147 offset:52224
	ds_read_b128 v[224:227], v147 offset:53248
	ds_read_b128 v[242:245], v147 offset:54272
	ds_read_b128 v[246:249], v147 offset:55296
	ds_read_b128 v[250:253], v147 offset:56320
	global_load_lds_dwordx4 v[196:197], off
	s_add_i32 m0, s22, 0x2000
	s_add_u32 s2, s2, 0x40080
	v_lshl_add_u64 v[196:197], v[228:229], 0, s[62:63]
	s_addc_u32 s3, s3, 0
	s_add_i32 s22, s88, s55
	global_load_lds_dwordx4 v[196:197], off
	s_mov_b32 m0, s22
	s_nop 0
	global_load_lds_dwordx4 v0, s[2:3]
	s_add_i32 m0, s22, 0x2000
	s_nop 0
	global_load_lds_dwordx4 v134, s[2:3]
	v_lshl_add_u64 v[196:197], v[230:231], 0, s[62:63]
	s_mov_b32 m0, s91
	s_nop 0
	global_load_lds_dwordx4 v[196:197], off
	v_lshl_add_u64 v[196:197], v[232:233], 0, s[62:63]
	s_mov_b32 m0, s92
	s_nop 0
	global_load_lds_dwordx4 v[196:197], off
	s_waitcnt vmcnt(8)
	s_waitcnt lgkmcnt(0)
	s_barrier
	s_setprio 1
	s_waitcnt lgkmcnt(0)
	v_mfma_f32_16x16x32_bf16 v[62:65], v[140:143], v[176:179], v[62:65]
	v_mfma_f32_16x16x32_bf16 v[58:61], v[152:155], v[176:179], v[58:61]
	v_mfma_f32_16x16x32_bf16 v[46:49], v[140:143], v[184:187], v[46:49]
	v_mfma_f32_16x16x32_bf16 v[42:45], v[152:155], v[184:187], v[42:45]
	v_mfma_f32_16x16x32_bf16 v[30:33], v[140:143], v[224:227], v[30:33]
	v_mfma_f32_16x16x32_bf16 v[26:29], v[152:155], v[224:227], v[26:29]
	v_mfma_f32_16x16x32_bf16 v[14:17], v[140:143], v[246:249], v[14:17]
	v_mfma_f32_16x16x32_bf16 v[10:13], v[152:155], v[246:249], v[10:13]
	v_mfma_f32_16x16x32_bf16 v[62:65], v[148:151], v[180:183], v[62:65]
	v_mfma_f32_16x16x32_bf16 v[58:61], v[156:159], v[180:183], v[58:61]
	v_mfma_f32_16x16x32_bf16 v[46:49], v[148:151], v[220:223], v[46:49]
	v_mfma_f32_16x16x32_bf16 v[42:45], v[156:159], v[220:223], v[42:45]
	v_mfma_f32_16x16x32_bf16 v[30:33], v[148:151], v[242:245], v[30:33]
	v_mfma_f32_16x16x32_bf16 v[26:29], v[156:159], v[242:245], v[26:29]
	v_mfma_f32_16x16x32_bf16 v[14:17], v[148:151], v[250:253], v[14:17]
	v_mfma_f32_16x16x32_bf16 v[10:13], v[156:159], v[250:253], v[10:13]
	s_setprio 0
	s_setprio 1
	v_mfma_f32_16x16x32_bf16 v[54:57], v[160:163], v[176:179], v[54:57]
	v_mfma_f32_16x16x32_bf16 v[50:53], v[168:171], v[176:179], v[50:53]
	v_mfma_f32_16x16x32_bf16 v[38:41], v[160:163], v[184:187], v[38:41]
	v_mfma_f32_16x16x32_bf16 v[34:37], v[168:171], v[184:187], v[34:37]
	v_mfma_f32_16x16x32_bf16 v[22:25], v[160:163], v[224:227], v[22:25]
	v_mfma_f32_16x16x32_bf16 v[18:21], v[168:171], v[224:227], v[18:21]
	v_mfma_f32_16x16x32_bf16 v[6:9], v[160:163], v[246:249], v[6:9]
	v_mfma_f32_16x16x32_bf16 v[2:5], v[168:171], v[246:249], v[2:5]
	v_mfma_f32_16x16x32_bf16 v[54:57], v[164:167], v[180:183], v[54:57]
	v_mfma_f32_16x16x32_bf16 v[50:53], v[172:175], v[180:183], v[50:53]
	v_mfma_f32_16x16x32_bf16 v[38:41], v[164:167], v[220:223], v[38:41]
	v_mfma_f32_16x16x32_bf16 v[34:37], v[172:175], v[220:223], v[34:37]
	v_mfma_f32_16x16x32_bf16 v[22:25], v[164:167], v[242:245], v[22:25]
	v_mfma_f32_16x16x32_bf16 v[18:21], v[172:175], v[242:245], v[18:21]
	v_mfma_f32_16x16x32_bf16 v[6:9], v[164:167], v[250:253], v[6:9]
	v_mfma_f32_16x16x32_bf16 v[2:5], v[172:175], v[250:253], v[2:5]
	s_setprio 0
	s_barrier
	s_add_i32 vcc_lo, vcc_lo, 2
	s_add_u32 s34, s34, 0x100
	s_addc_u32 s35, s35, 0
	s_add_u32 s96, s96, 0x100
	s_addc_u32 s97, s97, 0
	s_cmp_gt_u32 vcc_lo, 13
	s_cbranch_scc0 .LBB0_663
	s_and_b64 vcc, exec, s[28:29]
	s_cbranch_vccz .LBB0_666
	s_barrier

; __device__ __forceinline__ int ltid(int wv) { int l; asm volatile("v_mbcnt_lo_u32_b32 %0, -1, 0\n\tv_mbcnt_hi_u32_b32 %0, -1, %0" : "=v"(l)); asm volatile("" : "+s"(wv)); return (wv << 6) | l; }
; #define PG8_STAGE(bufoff, gbase, voff) do { _Pragma("unroll") for (int _i = 0; _i < 2; ++_i) \
;         __builtin_amdgcn_global_load_lds((const unsigned*)((const char*)(gbase) + (voff)[_i]), (PG8_LAS unsigned*)(lds + (bufoff) + ldsw + _i * 8192), 16, 0, 0); } while (0)
; #define PG8_WAIT_V(n) asm volatile("s_waitcnt vmcnt(" #n ")" ::: "memory")
; #define PG8_BAR __builtin_amdgcn_s_barrier()
; template <class Epi, class Sched, bool ALIGN_EPI = false, bool SP2 = false>
; __device__ __forceinline__ void gemm_phase(PG8_LAS unsigned char* lds, const Gemm g, const Sched& S, const Epi& E, int wv) {
;     const int tid = ltid(wv), wid = __builtin_amdgcn_readfirstlane(tid >> 6), lane = tid & 63, wr = wid >> 2, wc = wid & 3, fr = lane & 15, fq = lane >> 4;
;     const int K = g.K, nt = K / BK;
;     unsigned voffA[2], voffB[2];
; #pragma unroll
;     for (int i = 0; i < 2; ++i) { int R, C; stage_rc(tid * 16 + i * 8192, R, C); const int Rb = Epi::PERM ? ((R & ~31) + perm32(R & 31)) : R;
;         voffA[i] = (unsigned)(R * g.lda + C) * 2u; voffB[i] = (unsigned)(Rb * K + C) * 2u; }
;     const size_t kstep = (size_t)(BK * 2);
;     const size_t hstepA = (size_t)HALF * g.lda * 2, hstepB = (size_t)HALF * K * 2;
;     const size_t tstepA = 2 * hstepA, tstepB = 2 * hstepB;
;     const unsigned ldsw = (unsigned)wid * 1024u;
;     const int aoff = lds_byte(wr * 64 + fr, fq * 8), boff = lds_byte(wc * 32 + fr, fq * 8);
;     ...
;         PG8_STAGE(PG8_SB(0, 0), cB, voffB); PG8_STAGE(PG8_SB(0, 1), cB + hstepB, voffB); PG8_STAGE(PG8_SA(0, 0), cA, voffA); PG8_STAGE(PG8_SA(0, 1), cA + hstepA, voffA);
;         if (wr == 1) PG8_BAR;
;         PG8_WAIT_V(2); PG8_BAR;
;         PG8_STAGE(PG8_SB(1, 0), cB + kstep, voffB); PG8_STAGE(PG8_SA(1, 0), cA + kstep, voffA); PG8_STAGE(PG8_SB(1, 1), cB + hstepB + kstep, voffB);
;         PG8_WAIT_V(6); PG8_BAR;
.LBB0_876:
	s_add_u32 s26, s22, 0x6800000
	s_addc_u32 s27, s23, 0
	s_add_u32 s28, s22, 0x2600000
	s_addc_u32 s29, s23, 0
	s_add_u32 s22, s22, 0x1b00000
	s_addc_u32 s23, s23, 0
	s_and_b32 s2, s2, 3
	s_lshl_b32 s7, s3, 6
	s_add_i32 m0, s61, 0x18000
	v_lshl_add_u64 v[6:7], v[6:7], 0, s[62:63]
	v_writelane_b32 v255, s7, 5
	s_lshl_b32 s7, s3, 13
	s_lshl_b32 s3, s2, 5
	s_lshl_b32 s16, s2, 12
	s_waitcnt vmcnt(2)
	s_barrier
	global_load_lds_dwordx4 v[6:7], off
	v_lshl_add_u64 v[4:5], v[4:5], 0, s[62:63]
	s_add_i32 m0, s61, 0x1a000
	s_add_i32 s25, s61, 0x8000
	s_add_i32 s13, s61, 0xa000
	global_load_lds_dwordx4 v[4:5], off
	v_lshl_add_u64 v[2:3], v[2:3], 0, s[62:63]
	s_mov_b32 m0, s25
	s_add_u32 s2, s34, 0x10080
	v_writelane_b32 v255, s3, 7
	global_load_lds_dwordx4 v[2:3], off
	v_lshl_add_u64 v[2:3], v[8:9], 0, s[62:63]
	s_mov_b32 m0, s13
	s_addc_u32 s3, s35, 0
	global_load_lds_dwordx4 v[2:3], off
	s_add_i32 m0, s61, 0x1c000
	s_nop 0
	global_load_lds_dwordx4 v0, s[2:3]
	v_lshl_add_u64 v[2:3], s[2:3], 0, v[134:135]
	s_add_i32 m0, s61, 0x1e000
	s_cmpk_lt_u32 s14, 0x100
	global_load_lds_dwordx4 v[2:3], off
	s_cselect_b64 s[2:3], -1, 0
	v_writelane_b32 v255, s2, 8
	s_bitcmp0_b32 s14, 6
	v_bfe_u32 v153, v10, 4, 2
	v_writelane_b32 v255, s3, 9
	s_cselect_b64 s[2:3], -1, 0
	v_writelane_b32 v255, s2, 10
	v_and_b32_e32 v152, 15, v10
	v_lshlrev_b32_e32 v2, 4, v153
	v_lshlrev_b32_e32 v3, 2, v10
	v_writelane_b32 v255, s3, 11
	s_ashr_i32 s2, s12, 31
	v_lshl_or_b32 v2, v152, 6, v2
	v_and_b32_e32 v3, 32, v3
	s_waitcnt vmcnt(6)
	v_writelane_b32 v255, s2, 12
	v_readlane_b32 s2, v254, 58
	v_bitop3_b32 v4, v2, s7, v3 bitop3:0xde
	s_ashr_i32 s2, s2, 31
	v_bitop3_b32 v154, v2, s16, v3 bitop3:0xde
	s_mov_b32 s14, 0
	v_writelane_b32 v255, s2, 13
	v_add_u32_e32 v155, 0, v4
	s_barrier
	s_branch .LBB0_879

; #define PG8_STAGE(bufoff, gbase, voff) do { _Pragma("unroll") for (int _i = 0; _i < 2; ++_i) \
;         __builtin_amdgcn_global_load_lds((const unsigned*)((const char*)(gbase) + (voff)[_i]), (PG8_LAS unsigned*)(lds + (bufoff) + ldsw + _i * 8192), 16, 0, 0); } while (0)
; #define PG8_LDA(dst, b, h) do { _Pragma("unroll") for (int m = 0; m < 4; ++m) _Pragma("unroll") for (int k = 0; k < 2; ++k) dst[m][k] = *(const PG8_LAS bf16x8*)(lds + PG8_SA(b, h) + aoff + m * 2048 + k * 1024); } while (0)
; #define PG8_LDB(dst, b, h) do { _Pragma("unroll") for (int n = 0; n < 2; ++n) _Pragma("unroll") for (int k = 0; k < 2; ++k) dst[n][k] = *(const PG8_LAS bf16x8*)(lds + PG8_SB(b, h) + boff + n * 2048 + k * 1024); } while (0)
; #define PG8_MMA(ai, bj, At, Bt) do { __builtin_amdgcn_s_setprio(1); _Pragma("unroll") for (int m = 0; m < 4; ++m) _Pragma("unroll") for (int n = 0; n < 2; ++n) _Pragma("unroll") for (int k = 0; k < 2; ++k) \
;         acc[ai][bj][m][n] = __builtin_amdgcn_mfma_f32_16x16x32_bf16(Bt[n][k], At[m][k], acc[ai][bj][m][n], 0, 0, 0); __builtin_amdgcn_s_setprio(0); } while (0)
; #define PG8_WAIT_V(n) asm volatile("s_waitcnt vmcnt(" #n ")" ::: "memory")
; #define PG8_WAIT_L(n) asm volatile("s_waitcnt lgkmcnt(" #n ")" ::: "memory")
; #define PG8_BAR __builtin_amdgcn_s_barrier()
; #define PG8_SCHED __builtin_amdgcn_sched_barrier(0)
; template <class Epi, class Sched, bool ALIGN_EPI = false, bool SP2 = false>
; __device__ __forceinline__ void gemm_phase(PG8_LAS unsigned char* lds, const Gemm g, const Sched& S, const Epi& E, int wv) {
;     ...
;             const char* a2 = last ? nA : cA + (size_t)(t + 2) * kstep; const char* b2 = last ? nB : cB + (size_t)(t + 2) * kstep;
;             const char* a3 = a2 + kstep; const char* b3 = b2 + kstep;
;             if (last && has_next) S.a_ready(nxt);
;             if constexpr (SP2) {
;             PG8_LDB(B0, 0, 0); PG8_LDB(B1, 0, 1); PG8_SCHED; PG8_LDA(At, 0, 0); PG8_STAGE(PG8_SA(1, 1), a1 + hstepA, voffA);
;             PG8_WAIT_V(8); PG8_WAIT_L(0); PG8_BAR; PG8_MMA(0, 0, At, B0); PG8_MMA(0, 1, At, B1); PG8_BAR; PG8_SCHED;
;             PG8_LDA(At, 0, 1); PG8_STAGE(PG8_SB(0, 0), b2, voffB); PG8_STAGE(PG8_SB(0, 1), b2 + hstepB, voffB); PG8_STAGE(PG8_SA(0, 0), a2, voffA);
;             PG8_WAIT_V(8); PG8_WAIT_L(0); PG8_BAR; PG8_MMA(1, 0, At, B0); PG8_MMA(1, 1, At, B1); PG8_BAR; PG8_SCHED;
.LBB0_888:
	s_add_u32 s7, s40, s50
	s_addc_u32 s38, s41, s51
	s_add_u32 s39, s7, 0x100
	s_addc_u32 s52, s38, 0
	s_and_b64 s[36:37], s[2:3], exec
	s_cselect_b32 s53, s45, s52
	s_cselect_b32 s52, s44, s39
	s_add_u32 s36, s34, s50
	s_addc_u32 s37, s35, s51
	s_add_u32 s36, s36, 0x100
	s_addc_u32 s37, s37, 0
	s_add_i32 s60, 0, 0x10000
	s_and_b64 s[2:3], s[2:3], exec
	s_cselect_b32 s83, s43, s37
	s_cselect_b32 s82, s24, s36
	s_add_i32 s3, 0, 0x14000
	s_add_u32 s92, s7, 0xc0080
	s_addc_u32 s93, s38, 0
	s_add_i32 s38, s60, s87
	s_add_i32 m0, s61, 0xc000
	s_add_i32 s49, s61, 0xe000
	s_add_i32 s58, s38, 0x2000
	s_add_u32 s90, s82, 0x10000
	v_add_u32_e32 v148, s60, v154
	v_add_u32_e32 v168, s3, v154
	s_addc_u32 s91, s83, 0
	s_add_i32 s39, s3, s87
	ds_read_b128 v[136:139], v148
	ds_read_b128 v[140:143], v148 offset:1024
	ds_read_b128 v[144:147], v148 offset:2048
	ds_read_b128 v[148:151], v148 offset:3072
	ds_read_b128 v[156:159], v168
	ds_read_b128 v[160:163], v168 offset:1024
	ds_read_b128 v[164:167], v168 offset:2048
	ds_read_b128 v[168:171], v168 offset:3072
	s_add_i32 s55, s39, 0x2000
	s_add_i32 s37, 0, 0x18000
	s_add_i32 s36, 0, 0x1c000
	s_add_u32 s50, s52, 0xc0000
	s_addc_u32 s51, s53, 0
	s_add_i32 vcc_hi, s37, s87
	s_add_i32 vcc_lo, vcc_hi, 0x2000
	s_add_u32 s2, s82, 0x10080
	s_addc_u32 s3, s83, 0
	s_add_i32 s88, s36, s87
	s_add_i32 s7, s88, 0x2000
	ds_read_b128 v[172:175], v155
	ds_read_b128 v[176:179], v155 offset:1024
	ds_read_b128 v[180:183], v155 offset:2048
	ds_read_b128 v[184:187], v155 offset:3072
	ds_read_b128 v[220:223], v155 offset:4096
	ds_read_b128 v[224:227], v155 offset:5120
	ds_read_b128 v[242:245], v155 offset:6144
	ds_read_b128 v[246:249], v155 offset:7168
	global_load_lds_dwordx4 v130, s[92:93]
	s_mov_b32 m0, s49
	s_nop 0
	global_load_lds_dwordx4 v132, s[92:93]
	s_waitcnt vmcnt(8)
	s_waitcnt lgkmcnt(0)
	s_barrier
	s_setprio 1
	s_waitcnt lgkmcnt(0)
	v_mfma_f32_16x16x32_bf16 v[126:129], v[136:139], v[172:175], v[126:129]
	v_mfma_f32_16x16x32_bf16 v[122:125], v[144:147], v[172:175], v[122:125]
	v_mfma_f32_16x16x32_bf16 v[110:113], v[136:139], v[180:183], v[110:113]
	v_mfma_f32_16x16x32_bf16 v[106:109], v[144:147], v[180:183], v[106:109]
	v_mfma_f32_16x16x32_bf16 v[94:97], v[136:139], v[220:223], v[94:97]
	v_mfma_f32_16x16x32_bf16 v[90:93], v[144:147], v[220:223], v[90:93]
	v_mfma_f32_16x16x32_bf16 v[78:81], v[136:139], v[242:245], v[78:81]
	v_mfma_f32_16x16x32_bf16 v[74:77], v[144:147], v[242:245], v[74:77]
	v_mfma_f32_16x16x32_bf16 v[126:129], v[140:143], v[176:179], v[126:129]
	v_mfma_f32_16x16x32_bf16 v[122:125], v[148:151], v[176:179], v[122:125]
	v_mfma_f32_16x16x32_bf16 v[110:113], v[140:143], v[184:187], v[110:113]
	v_mfma_f32_16x16x32_bf16 v[106:109], v[148:151], v[184:187], v[106:109]
	v_mfma_f32_16x16x32_bf16 v[94:97], v[140:143], v[224:227], v[94:97]
	v_mfma_f32_16x16x32_bf16 v[90:93], v[148:151], v[224:227], v[90:93]
	v_mfma_f32_16x16x32_bf16 v[78:81], v[140:143], v[246:249], v[78:81]
	v_mfma_f32_16x16x32_bf16 v[74:77], v[148:151], v[246:249], v[74:77]
	s_setprio 0
	s_setprio 1
	v_mfma_f32_16x16x32_bf16 v[118:121], v[156:159], v[172:175], v[118:121]
	v_mfma_f32_16x16x32_bf16 v[114:117], v[164:167], v[172:175], v[114:117]
	v_mfma_f32_16x16x32_bf16 v[102:105], v[156:159], v[180:183], v[102:105]
	v_mfma_f32_16x16x32_bf16 v[98:101], v[164:167], v[180:183], v[98:101]
	v_mfma_f32_16x16x32_bf16 v[86:89], v[156:159], v[220:223], v[86:89]
	v_mfma_f32_16x16x32_bf16 v[82:85], v[164:167], v[220:223], v[82:85]
	v_mfma_f32_16x16x32_bf16 v[70:73], v[156:159], v[242:245], v[70:73]
	v_mfma_f32_16x16x32_bf16 v[66:69], v[164:167], v[242:245], v[66:69]
	v_mfma_f32_16x16x32_bf16 v[118:121], v[160:163], v[176:179], v[118:121]
	v_mfma_f32_16x16x32_bf16 v[114:117], v[168:171], v[176:179], v[114:117]
	v_mfma_f32_16x16x32_bf16 v[102:105], v[160:163], v[184:187], v[102:105]
	v_mfma_f32_16x16x32_bf16 v[98:101], v[168:171], v[184:187], v[98:101]
	v_mfma_f32_16x16x32_bf16 v[86:89], v[160:163], v[224:227], v[86:89]
	v_mfma_f32_16x16x32_bf16 v[82:85], v[168:171], v[224:227], v[82:85]
	v_mfma_f32_16x16x32_bf16 v[70:73], v[160:163], v[246:249], v[70:73]
	v_mfma_f32_16x16x32_bf16 v[66:69], v[168:171], v[246:249], v[66:69]
	s_setprio 0
	s_barrier
	s_mov_b32 m0, s38
	v_lshl_add_u64 v[196:197], s[82:83], 0, v[0:1]
	ds_read_b128 v[172:175], v155 offset:16384
	ds_read_b128 v[176:179], v155 offset:17408
	ds_read_b128 v[180:183], v155 offset:18432
	ds_read_b128 v[184:187], v155 offset:19456
	ds_read_b128 v[220:223], v155 offset:20480
	ds_read_b128 v[224:227], v155 offset:21504
	ds_read_b128 v[242:245], v155 offset:22528
	ds_read_b128 v[246:249], v155 offset:23552
	global_load_lds_dwordx4 v[196:197], off
	v_lshl_add_u64 v[228:229], s[82:83], 0, v[134:135]
	s_mov_b32 m0, s58
	global_load_lds_dwordx4 v[228:229], off
	s_mov_b32 m0, s39
	v_lshl_add_u64 v[232:233], s[52:53], 0, v[132:133]
	global_load_lds_dwordx4 v0, s[90:91]
	s_mov_b32 m0, s55
	s_nop 0
	global_load_lds_dwordx4 v134, s[90:91]
	v_lshl_add_u64 v[230:231], s[52:53], 0, v[130:131]
	s_mov_b32 m0, s61
	s_nop 0
	global_load_lds_dwordx4 v[230:231], off
	s_mov_b32 m0, s94
	s_nop 0
	global_load_lds_dwordx4 v[232:233], off
	s_waitcnt vmcnt(8)
	s_waitcnt lgkmcnt(0)
	s_barrier
; #define PG8_STAGE(bufoff, gbase, voff) do { _Pragma("unroll") for (int _i = 0; _i < 2; ++_i) \
;         __builtin_amdgcn_global_load_lds((const unsigned*)((const char*)(gbase) + (voff)[_i]), (PG8_LAS unsigned*)(lds + (bufoff) + ldsw + _i * 8192), 16, 0, 0); } while (0)
; #define PG8_LDA(dst, b, h) do { _Pragma("unroll") for (int m = 0; m < 4; ++m) _Pragma("unroll") for (int k = 0; k < 2; ++k) dst[m][k] = *(const PG8_LAS bf16x8*)(lds + PG8_SA(b, h) + aoff + m * 2048 + k * 1024); } while (0)
; #define PG8_LDB(dst, b, h) do { _Pragma("unroll") for (int n = 0; n < 2; ++n) _Pragma("unroll") for (int k = 0; k < 2; ++k) dst[n][k] = *(const PG8_LAS bf16x8*)(lds + PG8_SB(b, h) + boff + n * 2048 + k * 1024); } while (0)
; #define PG8_MMA(ai, bj, At, Bt) do { __builtin_amdgcn_s_setprio(1); _Pragma("unroll") for (int m = 0; m < 4; ++m) _Pragma("unroll") for (int n = 0; n < 2; ++n) _Pragma("unroll") for (int k = 0; k < 2; ++k) \
;         acc[ai][bj][m][n] = __builtin_amdgcn_mfma_f32_16x16x32_bf16(Bt[n][k], At[m][k], acc[ai][bj][m][n], 0, 0, 0); __builtin_amdgcn_s_setprio(0); } while (0)
; #define PG8_WAIT_V(n) asm volatile("s_waitcnt vmcnt(" #n ")" ::: "memory")
; #define PG8_WAIT_L(n) asm volatile("s_waitcnt lgkmcnt(" #n ")" ::: "memory")
; #define PG8_BAR __builtin_amdgcn_s_barrier()
; #define PG8_SCHED __builtin_amdgcn_sched_barrier(0)
; template <class Epi, class Sched, bool ALIGN_EPI = false, bool SP2 = false>
; __device__ __forceinline__ void gemm_phase(PG8_LAS unsigned char* lds, const Gemm g, const Sched& S, const Epi& E, int wv) {
;     ...
;             PG8_WAIT_V(8); PG8_WAIT_L(0); PG8_BAR; PG8_MMA(1, 0, At, B0); PG8_MMA(1, 1, At, B1); PG8_BAR; PG8_SCHED;
;             PG8_LDB(B0, 1, 0); PG8_LDB(B1, 1, 1); PG8_SCHED; PG8_LDA(At, 1, 0); PG8_STAGE(PG8_SA(0, 1), a2 + hstepA, voffA);
;             PG8_WAIT_V(8); PG8_WAIT_L(0); PG8_BAR; PG8_MMA(0, 0, At, B0); PG8_MMA(0, 1, At, B1); PG8_BAR; PG8_SCHED;
	s_setprio 1
	s_waitcnt lgkmcnt(0)
	v_mfma_f32_16x16x32_bf16 v[62:65], v[136:139], v[172:175], v[62:65]
	v_mfma_f32_16x16x32_bf16 v[58:61], v[144:147], v[172:175], v[58:61]
	v_mfma_f32_16x16x32_bf16 v[46:49], v[136:139], v[180:183], v[46:49]
	v_mfma_f32_16x16x32_bf16 v[42:45], v[144:147], v[180:183], v[42:45]
	v_mfma_f32_16x16x32_bf16 v[30:33], v[136:139], v[220:223], v[30:33]
	v_mfma_f32_16x16x32_bf16 v[26:29], v[144:147], v[220:223], v[26:29]
	v_mfma_f32_16x16x32_bf16 v[14:17], v[136:139], v[242:245], v[14:17]
	v_mfma_f32_16x16x32_bf16 v[10:13], v[144:147], v[242:245], v[10:13]
	v_mfma_f32_16x16x32_bf16 v[62:65], v[140:143], v[176:179], v[62:65]
	v_mfma_f32_16x16x32_bf16 v[58:61], v[148:151], v[176:179], v[58:61]
	v_mfma_f32_16x16x32_bf16 v[46:49], v[140:143], v[184:187], v[46:49]
	v_mfma_f32_16x16x32_bf16 v[42:45], v[148:151], v[184:187], v[42:45]
	v_mfma_f32_16x16x32_bf16 v[30:33], v[140:143], v[224:227], v[30:33]
	v_mfma_f32_16x16x32_bf16 v[26:29], v[148:151], v[224:227], v[26:29]
	v_mfma_f32_16x16x32_bf16 v[14:17], v[140:143], v[246:249], v[14:17]
	v_mfma_f32_16x16x32_bf16 v[10:13], v[148:151], v[246:249], v[10:13]
	s_setprio 0
	s_setprio 1
	v_mfma_f32_16x16x32_bf16 v[54:57], v[156:159], v[172:175], v[54:57]
	v_mfma_f32_16x16x32_bf16 v[50:53], v[164:167], v[172:175], v[50:53]
	v_mfma_f32_16x16x32_bf16 v[38:41], v[156:159], v[180:183], v[38:41]
	v_mfma_f32_16x16x32_bf16 v[34:37], v[164:167], v[180:183], v[34:37]
	v_mfma_f32_16x16x32_bf16 v[22:25], v[156:159], v[220:223], v[22:25]
	v_mfma_f32_16x16x32_bf16 v[18:21], v[164:167], v[220:223], v[18:21]
	v_mfma_f32_16x16x32_bf16 v[6:9], v[156:159], v[242:245], v[6:9]
	v_mfma_f32_16x16x32_bf16 v[2:5], v[164:167], v[242:245], v[2:5]
	v_mfma_f32_16x16x32_bf16 v[54:57], v[160:163], v[176:179], v[54:57]
	v_mfma_f32_16x16x32_bf16 v[50:53], v[168:171], v[176:179], v[50:53]
	v_mfma_f32_16x16x32_bf16 v[38:41], v[160:163], v[184:187], v[38:41]
	v_mfma_f32_16x16x32_bf16 v[34:37], v[168:171], v[184:187], v[34:37]
	v_mfma_f32_16x16x32_bf16 v[22:25], v[160:163], v[224:227], v[22:25]
	v_mfma_f32_16x16x32_bf16 v[18:21], v[168:171], v[224:227], v[18:21]
	v_mfma_f32_16x16x32_bf16 v[6:9], v[160:163], v[246:249], v[6:9]
	v_mfma_f32_16x16x32_bf16 v[2:5], v[168:171], v[246:249], v[2:5]
	s_setprio 0
	s_barrier
	v_add_u32_e32 v148, s37, v154
	v_add_u32_e32 v168, s36, v154
	ds_read_b128 v[136:139], v148
	ds_read_b128 v[140:143], v148 offset:1024
	ds_read_b128 v[144:147], v148 offset:2048
	ds_read_b128 v[148:151], v148 offset:3072
	ds_read_b128 v[156:159], v168
	ds_read_b128 v[160:163], v168 offset:1024
	ds_read_b128 v[164:167], v168 offset:2048
	ds_read_b128 v[168:171], v168 offset:3072
	s_mov_b32 m0, s95
	ds_read_b128 v[172:175], v155 offset:32768
	ds_read_b128 v[176:179], v155 offset:33792
	ds_read_b128 v[180:183], v155 offset:34816
	ds_read_b128 v[184:187], v155 offset:35840
	ds_read_b128 v[220:223], v155 offset:36864
	ds_read_b128 v[224:227], v155 offset:37888
	ds_read_b128 v[242:245], v155 offset:38912
	ds_read_b128 v[246:249], v155 offset:39936
	global_load_lds_dwordx4 v130, s[50:51]
	v_lshl_add_u64 v[234:235], s[50:51], 0, v[132:133]
	s_mov_b32 m0, s97
	s_nop 0
	global_load_lds_dwordx4 v[234:235], off
	s_waitcnt vmcnt(8)
	s_waitcnt lgkmcnt(0)
	s_barrier
	s_setprio 1
	s_waitcnt lgkmcnt(0)
	v_mfma_f32_16x16x32_bf16 v[126:129], v[136:139], v[172:175], v[126:129]
	v_mfma_f32_16x16x32_bf16 v[122:125], v[144:147], v[172:175], v[122:125]
	v_mfma_f32_16x16x32_bf16 v[110:113], v[136:139], v[180:183], v[110:113]
	v_mfma_f32_16x16x32_bf16 v[106:109], v[144:147], v[180:183], v[106:109]
	v_mfma_f32_16x16x32_bf16 v[94:97], v[136:139], v[220:223], v[94:97]
	v_mfma_f32_16x16x32_bf16 v[90:93], v[144:147], v[220:223], v[90:93]
	v_mfma_f32_16x16x32_bf16 v[78:81], v[136:139], v[242:245], v[78:81]
	v_mfma_f32_16x16x32_bf16 v[74:77], v[144:147], v[242:245], v[74:77]
	v_mfma_f32_16x16x32_bf16 v[126:129], v[140:143], v[176:179], v[126:129]
	v_mfma_f32_16x16x32_bf16 v[122:125], v[148:151], v[176:179], v[122:125]
	v_mfma_f32_16x16x32_bf16 v[110:113], v[140:143], v[184:187], v[110:113]
	v_mfma_f32_16x16x32_bf16 v[106:109], v[148:151], v[184:187], v[106:109]
	v_mfma_f32_16x16x32_bf16 v[94:97], v[140:143], v[224:227], v[94:97]
	v_mfma_f32_16x16x32_bf16 v[90:93], v[148:151], v[224:227], v[90:93]
	v_mfma_f32_16x16x32_bf16 v[78:81], v[140:143], v[246:249], v[78:81]
	v_mfma_f32_16x16x32_bf16 v[74:77], v[148:151], v[246:249], v[74:77]
	s_setprio 0
	s_setprio 1
	v_mfma_f32_16x16x32_bf16 v[118:121], v[156:159], v[172:175], v[118:121]
	v_mfma_f32_16x16x32_bf16 v[114:117], v[164:167], v[172:175], v[114:117]
	v_mfma_f32_16x16x32_bf16 v[102:105], v[156:159], v[180:183], v[102:105]
	v_mfma_f32_16x16x32_bf16 v[98:101], v[164:167], v[180:183], v[98:101]
	v_mfma_f32_16x16x32_bf16 v[86:89], v[156:159], v[220:223], v[86:89]
	v_mfma_f32_16x16x32_bf16 v[82:85], v[164:167], v[220:223], v[82:85]
	v_mfma_f32_16x16x32_bf16 v[70:73], v[156:159], v[242:245], v[70:73]
	v_mfma_f32_16x16x32_bf16 v[66:69], v[164:167], v[242:245], v[66:69]
	v_mfma_f32_16x16x32_bf16 v[118:121], v[160:163], v[176:179], v[118:121]
	v_mfma_f32_16x16x32_bf16 v[114:117], v[168:171], v[176:179], v[114:117]
	v_mfma_f32_16x16x32_bf16 v[102:105], v[160:163], v[184:187], v[102:105]
	v_mfma_f32_16x16x32_bf16 v[98:101], v[168:171], v[184:187], v[98:101]
	v_mfma_f32_16x16x32_bf16 v[86:89], v[160:163], v[224:227], v[86:89]
	v_mfma_f32_16x16x32_bf16 v[82:85], v[168:171], v[224:227], v[82:85]
	v_mfma_f32_16x16x32_bf16 v[70:73], v[160:163], v[246:249], v[70:73]
	v_mfma_f32_16x16x32_bf16 v[66:69], v[168:171], v[246:249], v[66:69]
	s_setprio 0
	s_barrier
; #define PG8_STAGE(bufoff, gbase, voff) do { _Pragma("unroll") for (int _i = 0; _i < 2; ++_i) \
;         __builtin_amdgcn_global_load_lds((const unsigned*)((const char*)(gbase) + (voff)[_i]), (PG8_LAS unsigned*)(lds + (bufoff) + ldsw + _i * 8192), 16, 0, 0); } while (0)
; #define PG8_LDA(dst, b, h) do { _Pragma("unroll") for (int m = 0; m < 4; ++m) _Pragma("unroll") for (int k = 0; k < 2; ++k) dst[m][k] = *(const PG8_LAS bf16x8*)(lds + PG8_SA(b, h) + aoff + m * 2048 + k * 1024); } while (0)
; #define PG8_MMA(ai, bj, At, Bt) do { __builtin_amdgcn_s_setprio(1); _Pragma("unroll") for (int m = 0; m < 4; ++m) _Pragma("unroll") for (int n = 0; n < 2; ++n) _Pragma("unroll") for (int k = 0; k < 2; ++k) \
;         acc[ai][bj][m][n] = __builtin_amdgcn_mfma_f32_16x16x32_bf16(Bt[n][k], At[m][k], acc[ai][bj][m][n], 0, 0, 0); __builtin_amdgcn_s_setprio(0); } while (0)
; #define PG8_WAIT_V(n) asm volatile("s_waitcnt vmcnt(" #n ")" ::: "memory")
; #define PG8_WAIT_L(n) asm volatile("s_waitcnt lgkmcnt(" #n ")" ::: "memory")
; #define PG8_BAR __builtin_amdgcn_s_barrier()
; #define PG8_SCHED __builtin_amdgcn_sched_barrier(0)
; template <class Epi, class Sched, bool ALIGN_EPI = false, bool SP2 = false>
; __device__ __forceinline__ void gemm_phase(PG8_LAS unsigned char* lds, const Gemm g, const Sched& S, const Epi& E, int wv) {
;     ...
;         for (int t = 0; t < nt; t += 2) {
;     ...
;             PG8_WAIT_V(8); PG8_WAIT_L(0); PG8_BAR; PG8_MMA(0, 0, At, B0); PG8_MMA(0, 1, At, B1); PG8_BAR; PG8_SCHED;
;             PG8_LDA(At, 1, 1); PG8_STAGE(PG8_SB(1, 0), b3, voffB); PG8_STAGE(PG8_SB(1, 1), b3 + hstepB, voffB); PG8_STAGE(PG8_SA(1, 0), a3, voffA);
;             PG8_WAIT_V(8); PG8_WAIT_L(0); PG8_BAR; PG8_MMA(1, 0, At, B0); PG8_MMA(1, 1, At, B1); PG8_BAR; PG8_SCHED;
	s_mov_b32 m0, vcc_hi
	v_lshl_add_u64 v[196:197], v[196:197], 0, s[62:63]
	ds_read_b128 v[172:175], v155 offset:49152
	ds_read_b128 v[176:179], v155 offset:50176
	ds_read_b128 v[180:183], v155 offset:51200
	ds_read_b128 v[184:187], v155 offset:52224
	ds_read_b128 v[220:223], v155 offset:53248
	ds_read_b128 v[224:227], v155 offset:54272
	ds_read_b128 v[242:245], v155 offset:55296
	ds_read_b128 v[246:249], v155 offset:56320
	global_load_lds_dwordx4 v[196:197], off
	v_lshl_add_u64 v[196:197], v[228:229], 0, s[62:63]
	s_mov_b32 m0, vcc_lo
	s_nop 0
	global_load_lds_dwordx4 v[196:197], off
	s_mov_b32 m0, s88
	s_nop 0
	global_load_lds_dwordx4 v0, s[2:3]
	s_mov_b32 m0, s7
	s_nop 0
	global_load_lds_dwordx4 v134, s[2:3]
	v_lshl_add_u64 v[196:197], v[230:231], 0, s[62:63]
	s_mov_b32 m0, s25
	s_nop 0
	global_load_lds_dwordx4 v[196:197], off
	v_lshl_add_u64 v[196:197], v[232:233], 0, s[62:63]
	s_mov_b32 m0, s13
	s_nop 0
	global_load_lds_dwordx4 v[196:197], off
	s_waitcnt vmcnt(8)
	s_waitcnt lgkmcnt(0)
	s_barrier
	s_setprio 1
	s_waitcnt lgkmcnt(0)
	v_mfma_f32_16x16x32_bf16 v[62:65], v[136:139], v[172:175], v[62:65]
	v_mfma_f32_16x16x32_bf16 v[58:61], v[144:147], v[172:175], v[58:61]
	v_mfma_f32_16x16x32_bf16 v[46:49], v[136:139], v[180:183], v[46:49]
	v_mfma_f32_16x16x32_bf16 v[42:45], v[144:147], v[180:183], v[42:45]
	v_mfma_f32_16x16x32_bf16 v[30:33], v[136:139], v[220:223], v[30:33]
	v_mfma_f32_16x16x32_bf16 v[26:29], v[144:147], v[220:223], v[26:29]
	v_mfma_f32_16x16x32_bf16 v[14:17], v[136:139], v[242:245], v[14:17]
	v_mfma_f32_16x16x32_bf16 v[10:13], v[144:147], v[242:245], v[10:13]
	v_mfma_f32_16x16x32_bf16 v[62:65], v[140:143], v[176:179], v[62:65]
	v_mfma_f32_16x16x32_bf16 v[58:61], v[148:151], v[176:179], v[58:61]
	v_mfma_f32_16x16x32_bf16 v[46:49], v[140:143], v[184:187], v[46:49]
	v_mfma_f32_16x16x32_bf16 v[42:45], v[148:151], v[184:187], v[42:45]
	v_mfma_f32_16x16x32_bf16 v[30:33], v[140:143], v[224:227], v[30:33]
	v_mfma_f32_16x16x32_bf16 v[26:29], v[148:151], v[224:227], v[26:29]
	v_mfma_f32_16x16x32_bf16 v[14:17], v[140:143], v[246:249], v[14:17]
	v_mfma_f32_16x16x32_bf16 v[10:13], v[148:151], v[246:249], v[10:13]
	s_setprio 0
	s_setprio 1
	v_mfma_f32_16x16x32_bf16 v[54:57], v[156:159], v[172:175], v[54:57]
	v_mfma_f32_16x16x32_bf16 v[50:53], v[164:167], v[172:175], v[50:53]
	v_mfma_f32_16x16x32_bf16 v[38:41], v[156:159], v[180:183], v[38:41]
	v_mfma_f32_16x16x32_bf16 v[34:37], v[164:167], v[180:183], v[34:37]
	v_mfma_f32_16x16x32_bf16 v[22:25], v[156:159], v[220:223], v[22:25]
	v_mfma_f32_16x16x32_bf16 v[18:21], v[164:167], v[220:223], v[18:21]
	v_mfma_f32_16x16x32_bf16 v[6:9], v[156:159], v[242:245], v[6:9]
	v_mfma_f32_16x16x32_bf16 v[2:5], v[164:167], v[242:245], v[2:5]
	v_mfma_f32_16x16x32_bf16 v[54:57], v[160:163], v[176:179], v[54:57]
	v_mfma_f32_16x16x32_bf16 v[50:53], v[168:171], v[176:179], v[50:53]
	v_mfma_f32_16x16x32_bf16 v[38:41], v[160:163], v[184:187], v[38:41]
	v_mfma_f32_16x16x32_bf16 v[34:37], v[168:171], v[184:187], v[34:37]
	v_mfma_f32_16x16x32_bf16 v[22:25], v[160:163], v[224:227], v[22:25]
	v_mfma_f32_16x16x32_bf16 v[18:21], v[168:171], v[224:227], v[18:21]
	v_mfma_f32_16x16x32_bf16 v[6:9], v[160:163], v[246:249], v[6:9]
	v_mfma_f32_16x16x32_bf16 v[2:5], v[168:171], v[246:249], v[2:5]
	s_setprio 0
	s_barrier
	s_andn2_b64 vcc, exec, s[18:19]
	s_mov_b64 s[2:3], -1
	s_mov_b64 s[18:19], 0
	s_mov_b64 s[50:51], 0x100
	s_cbranch_vccz .LBB0_888
	v_readlane_b32 s2, v255, 8
	v_readlane_b32 s3, v255, 9
	s_and_b64 vcc, exec, s[2:3]
	s_cbranch_vccz .LBB0_891
	s_barrier

; #define PG8_STAGE(bufoff, gbase, voff) do { _Pragma("unroll") for (int _i = 0; _i < 2; ++_i) \
;         __builtin_amdgcn_global_load_lds((const unsigned*)((const char*)(gbase) + (voff)[_i]), (PG8_LAS unsigned*)(lds + (bufoff) + ldsw + _i * 8192), 16, 0, 0); } while (0)
; #define PG8_WAIT_V(n) asm volatile("s_waitcnt vmcnt(" #n ")" ::: "memory")
; #define PG8_BAR __builtin_amdgcn_s_barrier()
; template <class Epi, class Sched, bool ALIGN_EPI = false, bool SP2 = false>
; __device__ __forceinline__ void gemm_phase(PG8_LAS unsigned char* lds, const Gemm g, const Sched& S, const Epi& E, int wv) {
;     ...
;     for (int i = 0; i < 2; ++i) { int R, C; stage_rc(tid * 16 + i * 8192, R, C); const int Rb = Epi::PERM ? ((R & ~31) + perm32(R & 31)) : R;
;         voffA[i] = (unsigned)(R * g.lda + C) * 2u; voffB[i] = (unsigned)(Rb * K + C) * 2u; }
;     const size_t kstep = (size_t)(BK * 2);
;     const size_t hstepA = (size_t)HALF * g.lda * 2, hstepB = (size_t)HALF * K * 2;
;     const size_t tstepA = 2 * hstepA, tstepB = 2 * hstepB;
;     const unsigned ldsw = (unsigned)wid * 1024u;
;     const int aoff = lds_byte(wr * 64 + fr, fq * 8), boff = lds_byte(wc * 32 + fr, fq * 8);
;     ...
;         PG8_STAGE(PG8_SB(0, 0), cB, voffB); PG8_STAGE(PG8_SB(0, 1), cB + hstepB, voffB); PG8_STAGE(PG8_SA(0, 0), cA, voffA); PG8_STAGE(PG8_SA(0, 1), cA + hstepA, voffA);
;         if (wr == 1) PG8_BAR;
;         PG8_WAIT_V(2); PG8_BAR;
;         PG8_STAGE(PG8_SB(1, 0), cB + kstep, voffB); PG8_STAGE(PG8_SA(1, 0), cA + kstep, voffA); PG8_STAGE(PG8_SB(1, 1), cB + hstepB + kstep, voffB);
;         PG8_WAIT_V(6); PG8_BAR;
.LBB0_1259:
	s_add_u32 s36, s22, 0x2580000
	s_addc_u32 s37, s23, 0
	s_add_u32 s38, s22, 0x1b00000
	s_addc_u32 s39, s23, 0
	s_and_b32 s2, s2, 3
	s_lshl_b32 s14, s3, 6
	v_writelane_b32 v254, s14, 58
	s_lshl_b32 s14, s3, 13
	s_lshl_b32 s3, s2, 5
	s_lshl_b32 s16, s2, 12
	s_add_u32 s2, s22, 0x1980080
	v_mov_b32_e32 v131, v1
	v_writelane_b32 v254, s3, 60
	s_addc_u32 s3, s23, 0
	v_mov_b32_e32 v135, v1
	s_add_i32 m0, s29, 0x18000
	s_waitcnt vmcnt(2)
	s_barrier
	global_load_lds_dwordx4 v130, s[2:3]
	v_lshl_add_u64 v[8:9], s[2:3], 0, v[134:135]
	s_add_i32 m0, s29, 0x1a000
	s_add_i32 s45, s29, 0x8000
	s_add_i32 s26, s29, 0xa000
	global_load_lds_dwordx4 v[8:9], off
	v_lshl_add_u64 v[2:3], v[2:3], 0, s[62:63]
	s_mov_b32 m0, s45
	s_add_u32 s2, s22, 0x1990080
	global_load_lds_dwordx4 v[2:3], off
	v_lshl_add_u64 v[2:3], v[4:5], 0, s[62:63]
	s_mov_b32 m0, s26
	s_addc_u32 s3, s23, 0
	global_load_lds_dwordx4 v[2:3], off
	s_add_i32 m0, s29, 0x1c000
	s_nop 0
	global_load_lds_dwordx4 v130, s[2:3]
	v_lshl_add_u64 v[2:3], s[2:3], 0, v[134:135]
	s_add_i32 m0, s29, 0x1e000
	s_cmpk_lt_u32 s13, 0x100
	global_load_lds_dwordx4 v[2:3], off
	s_cselect_b64 s[2:3], -1, 0
	v_writelane_b32 v254, s2, 61
	s_bitcmp1_b32 s13, 6
	v_bfe_u32 v147, v6, 4, 2
	v_writelane_b32 v254, s3, 62
	s_cselect_b64 s[2:3], -1, 0
	v_and_b32_e32 v146, 15, v6
	v_lshlrev_b32_e32 v2, 4, v147
	v_lshlrev_b32_e32 v3, 2, v6
	v_writelane_b32 v255, s2, 5
	v_lshl_or_b32 v2, v146, 6, v2
	v_and_b32_e32 v3, 32, v3
	s_waitcnt vmcnt(6)
	v_writelane_b32 v255, s3, 6
	s_ashr_i32 s2, s7, 31
	v_bitop3_b32 v4, v2, s14, v3 bitop3:0xde
	v_writelane_b32 v255, s2, 7
	s_ashr_i32 s2, s12, 31
	v_bitop3_b32 v148, v2, s16, v3 bitop3:0xde
	v_writelane_b32 v255, s2, 8
	s_mov_b32 s14, 0
	v_add_u32_e32 v149, 0, v4
	s_mov_b64 s[40:41], s[24:25]
	s_barrier
	s_branch .LBB0_1262

; #define PG8_STAGE(bufoff, gbase, voff) do { _Pragma("unroll") for (int _i = 0; _i < 2; ++_i) \
;         __builtin_amdgcn_global_load_lds((const unsigned*)((const char*)(gbase) + (voff)[_i]), (PG8_LAS unsigned*)(lds + (bufoff) + ldsw + _i * 8192), 16, 0, 0); } while (0)
; #define PG8_LDA(dst, b, h) do { _Pragma("unroll") for (int m = 0; m < 4; ++m) _Pragma("unroll") for (int k = 0; k < 2; ++k) dst[m][k] = *(const PG8_LAS bf16x8*)(lds + PG8_SA(b, h) + aoff + m * 2048 + k * 1024); } while (0)
; #define PG8_LDB(dst, b, h) do { _Pragma("unroll") for (int n = 0; n < 2; ++n) _Pragma("unroll") for (int k = 0; k < 2; ++k) dst[n][k] = *(const PG8_LAS bf16x8*)(lds + PG8_SB(b, h) + boff + n * 2048 + k * 1024); } while (0)
; #define PG8_MMA(ai, bj, At, Bt) do { __builtin_amdgcn_s_setprio(1); _Pragma("unroll") for (int m = 0; m < 4; ++m) _Pragma("unroll") for (int n = 0; n < 2; ++n) _Pragma("unroll") for (int k = 0; k < 2; ++k) \
;         acc[ai][bj][m][n] = __builtin_amdgcn_mfma_f32_16x16x32_bf16(Bt[n][k], At[m][k], acc[ai][bj][m][n], 0, 0, 0); __builtin_amdgcn_s_setprio(0); } while (0)
; template <class Epi, class Sched, bool ALIGN_EPI = false, bool SP2 = false>
; __device__ __forceinline__ void gemm_phase(PG8_LAS unsigned char* lds, const Gemm g, const Sched& S, const Epi& E, int wv) {
;     ...
;         const bool has_next = S.next(ui + 1, nxt);
;         const char* nA = has_next ? (const char*)g.A + (size_t)nxt.pm * tstepA : cA; const char* nB = has_next ? (const char*)g.Bt + (size_t)nxt.pn * tstepB : cB;
; #pragma unroll 1
;         for (int t = 0; t < nt; t += 2) {
;             const bool last = (t == nt - 2);
;             const char* a1 = cA + (size_t)(t + 1) * kstep;
;             const char* a2 = last ? nA : cA + (size_t)(t + 2) * kstep; const char* b2 = last ? nB : cB + (size_t)(t + 2) * kstep;
;             const char* a3 = a2 + kstep; const char* b3 = b2 + kstep;
;             if (last && has_next) S.a_ready(nxt);
;             if constexpr (SP2) {
;             PG8_LDB(B0, 0, 0); PG8_LDB(B1, 0, 1); PG8_SCHED; PG8_LDA(At, 0, 0); PG8_STAGE(PG8_SA(1, 1), a1 + hstepA, voffA);
;             PG8_WAIT_V(8); PG8_WAIT_L(0); PG8_BAR; PG8_MMA(0, 0, At, B0); PG8_MMA(0, 1, At, B1); PG8_BAR; PG8_SCHED;
;             PG8_LDA(At, 0, 1); PG8_STAGE(PG8_SB(0, 0), b2, voffB); PG8_STAGE(PG8_SB(0, 1), b2 + hstepB, voffB); PG8_STAGE(PG8_SA(0, 0), a2, voffA);
.LBB0_1271:
	s_add_u32 s13, s34, s42
	s_addc_u32 s27, s35, s43
	s_add_u32 s48, s13, 0x100
	s_addc_u32 s49, s27, 0
	s_and_b64 s[22:23], s[2:3], exec
	s_cselect_b32 s53, s95, s49
	s_cselect_b32 s52, s94, s48
	s_add_u32 s22, s40, s42
	s_addc_u32 s23, s41, s43
	s_add_u32 s22, s22, 0x100
	s_addc_u32 s23, s23, 0
	s_add_i32 s60, 0, 0x10000
	s_and_b64 s[2:3], s[2:3], exec
	s_cselect_b32 s83, s51, s23
	s_cselect_b32 s82, s44, s22
	s_add_i32 s3, 0, 0x14000
	s_add_u32 s92, s13, 0xc0080
	s_addc_u32 s93, s27, 0
	s_add_i32 s48, s60, s28
	s_add_i32 m0, s29, 0xc000
	s_add_i32 s61, s29, 0xe000
	s_add_i32 s13, s48, 0x2000
	v_add_u32_e32 v144, s60, v148
	s_add_u32 s90, s82, 0x10000
	ds_read_b128 v[136:139], v144
	ds_read_b128 v[140:143], v144 offset:1024
	ds_read_b128 v[150:153], v144 offset:2048
	ds_read_b128 v[154:157], v144 offset:3072
	v_add_u32_e32 v144, s3, v148
	s_addc_u32 s91, s83, 0
	s_add_i32 s49, s3, s28
	ds_read_b128 v[158:161], v144
	ds_read_b128 v[162:165], v144 offset:1024
	ds_read_b128 v[166:169], v144 offset:2048
	ds_read_b128 v[170:173], v144 offset:3072
	s_add_i32 s27, s49, 0x2000
	s_add_i32 s23, 0, 0x18000
	s_add_i32 s22, 0, 0x1c000
	s_add_u32 s42, s52, 0xc0000
	s_addc_u32 s43, s53, 0
	s_add_i32 vcc_hi, s23, s28
	s_add_i32 vcc_lo, vcc_hi, 0x2000
	s_add_u32 s2, s82, 0x10080
	s_addc_u32 s3, s83, 0
	s_add_i32 s88, s22, s28
	s_add_i32 s60, s88, 0x2000
	ds_read_b128 v[174:177], v149
	ds_read_b128 v[178:181], v149 offset:1024
	ds_read_b128 v[182:185], v149 offset:2048
	ds_read_b128 v[220:223], v149 offset:3072
	ds_read_b128 v[224:227], v149 offset:4096
	ds_read_b128 v[242:245], v149 offset:5120
	ds_read_b128 v[246:249], v149 offset:6144
	ds_read_b128 v[250:253], v149 offset:7168
	global_load_lds_dwordx4 v0, s[92:93]
	s_mov_b32 m0, s61
	s_nop 0
	global_load_lds_dwordx4 v132, s[92:93]
	s_waitcnt vmcnt(8)
	s_waitcnt lgkmcnt(0)
	s_barrier
	s_setprio 1
	s_waitcnt lgkmcnt(0)
	v_mfma_f32_16x16x32_bf16 v[126:129], v[136:139], v[174:177], v[126:129]
	v_mfma_f32_16x16x32_bf16 v[122:125], v[150:153], v[174:177], v[122:125]
	v_mfma_f32_16x16x32_bf16 v[110:113], v[136:139], v[182:185], v[110:113]
	v_mfma_f32_16x16x32_bf16 v[106:109], v[150:153], v[182:185], v[106:109]
	v_mfma_f32_16x16x32_bf16 v[94:97], v[136:139], v[224:227], v[94:97]
	v_mfma_f32_16x16x32_bf16 v[90:93], v[150:153], v[224:227], v[90:93]
	v_mfma_f32_16x16x32_bf16 v[78:81], v[136:139], v[246:249], v[78:81]
	v_mfma_f32_16x16x32_bf16 v[74:77], v[150:153], v[246:249], v[74:77]
	v_mfma_f32_16x16x32_bf16 v[126:129], v[140:143], v[178:181], v[126:129]
	v_mfma_f32_16x16x32_bf16 v[122:125], v[154:157], v[178:181], v[122:125]
	v_mfma_f32_16x16x32_bf16 v[110:113], v[140:143], v[220:223], v[110:113]
	v_mfma_f32_16x16x32_bf16 v[106:109], v[154:157], v[220:223], v[106:109]
	v_mfma_f32_16x16x32_bf16 v[94:97], v[140:143], v[242:245], v[94:97]
	v_mfma_f32_16x16x32_bf16 v[90:93], v[154:157], v[242:245], v[90:93]
	v_mfma_f32_16x16x32_bf16 v[78:81], v[140:143], v[250:253], v[78:81]
	v_mfma_f32_16x16x32_bf16 v[74:77], v[154:157], v[250:253], v[74:77]
	s_setprio 0
	s_setprio 1
	v_mfma_f32_16x16x32_bf16 v[118:121], v[158:161], v[174:177], v[118:121]
	v_mfma_f32_16x16x32_bf16 v[114:117], v[166:169], v[174:177], v[114:117]
	v_mfma_f32_16x16x32_bf16 v[102:105], v[158:161], v[182:185], v[102:105]
	v_mfma_f32_16x16x32_bf16 v[98:101], v[166:169], v[182:185], v[98:101]
	v_mfma_f32_16x16x32_bf16 v[86:89], v[158:161], v[224:227], v[86:89]
	v_mfma_f32_16x16x32_bf16 v[82:85], v[166:169], v[224:227], v[82:85]
	v_mfma_f32_16x16x32_bf16 v[70:73], v[158:161], v[246:249], v[70:73]
	v_mfma_f32_16x16x32_bf16 v[66:69], v[166:169], v[246:249], v[66:69]
	v_mfma_f32_16x16x32_bf16 v[118:121], v[162:165], v[178:181], v[118:121]
	v_mfma_f32_16x16x32_bf16 v[114:117], v[170:173], v[178:181], v[114:117]
	v_mfma_f32_16x16x32_bf16 v[102:105], v[162:165], v[220:223], v[102:105]
	v_mfma_f32_16x16x32_bf16 v[98:101], v[170:173], v[220:223], v[98:101]
	v_mfma_f32_16x16x32_bf16 v[86:89], v[162:165], v[242:245], v[86:89]
	v_mfma_f32_16x16x32_bf16 v[82:85], v[170:173], v[242:245], v[82:85]
	v_mfma_f32_16x16x32_bf16 v[70:73], v[162:165], v[250:253], v[70:73]
	v_mfma_f32_16x16x32_bf16 v[66:69], v[170:173], v[250:253], v[66:69]
	s_setprio 0
	s_barrier
	s_mov_b32 m0, s48
	v_lshl_add_u64 v[144:145], s[82:83], 0, v[130:131]
	ds_read_b128 v[174:177], v149 offset:16384
	ds_read_b128 v[178:181], v149 offset:17408
	ds_read_b128 v[182:185], v149 offset:18432
	ds_read_b128 v[220:223], v149 offset:19456
	ds_read_b128 v[224:227], v149 offset:20480
	ds_read_b128 v[242:245], v149 offset:21504
	ds_read_b128 v[246:249], v149 offset:22528
	ds_read_b128 v[250:253], v149 offset:23552
	global_load_lds_dwordx4 v[144:145], off
	v_lshl_add_u64 v[186:187], s[82:83], 0, v[134:135]
	s_mov_b32 m0, s13
	global_load_lds_dwordx4 v[186:187], off
	s_mov_b32 m0, s49
	v_lshl_add_u64 v[228:229], s[52:53], 0, v[132:133]
	global_load_lds_dwordx4 v130, s[90:91]
	s_mov_b32 m0, s27
	s_nop 0
	global_load_lds_dwordx4 v134, s[90:91]
	v_lshl_add_u64 v[196:197], s[52:53], 0, v[0:1]
	s_mov_b32 m0, s29
	s_nop 0
	global_load_lds_dwordx4 v[196:197], off
	s_mov_b32 m0, s46
	s_nop 0
	global_load_lds_dwordx4 v[228:229], off
	s_waitcnt vmcnt(8)
	s_waitcnt lgkmcnt(0)
	s_barrier
; #define PG8_STAGE(bufoff, gbase, voff) do { _Pragma("unroll") for (int _i = 0; _i < 2; ++_i) \
;         __builtin_amdgcn_global_load_lds((const unsigned*)((const char*)(gbase) + (voff)[_i]), (PG8_LAS unsigned*)(lds + (bufoff) + ldsw + _i * 8192), 16, 0, 0); } while (0)
; #define PG8_LDA(dst, b, h) do { _Pragma("unroll") for (int m = 0; m < 4; ++m) _Pragma("unroll") for (int k = 0; k < 2; ++k) dst[m][k] = *(const PG8_LAS bf16x8*)(lds + PG8_SA(b, h) + aoff + m * 2048 + k * 1024); } while (0)
; #define PG8_LDB(dst, b, h) do { _Pragma("unroll") for (int n = 0; n < 2; ++n) _Pragma("unroll") for (int k = 0; k < 2; ++k) dst[n][k] = *(const PG8_LAS bf16x8*)(lds + PG8_SB(b, h) + boff + n * 2048 + k * 1024); } while (0)
; #define PG8_MMA(ai, bj, At, Bt) do { __builtin_amdgcn_s_setprio(1); _Pragma("unroll") for (int m = 0; m < 4; ++m) _Pragma("unroll") for (int n = 0; n < 2; ++n) _Pragma("unroll") for (int k = 0; k < 2; ++k) \
;         acc[ai][bj][m][n] = __builtin_amdgcn_mfma_f32_16x16x32_bf16(Bt[n][k], At[m][k], acc[ai][bj][m][n], 0, 0, 0); __builtin_amdgcn_s_setprio(0); } while (0)
; #define PG8_WAIT_V(n) asm volatile("s_waitcnt vmcnt(" #n ")" ::: "memory")
; #define PG8_WAIT_L(n) asm volatile("s_waitcnt lgkmcnt(" #n ")" ::: "memory")
; #define PG8_BAR __builtin_amdgcn_s_barrier()
; #define PG8_SCHED __builtin_amdgcn_sched_barrier(0)
; template <class Epi, class Sched, bool ALIGN_EPI = false, bool SP2 = false>
; __device__ __forceinline__ void gemm_phase(PG8_LAS unsigned char* lds, const Gemm g, const Sched& S, const Epi& E, int wv) {
;     ...
;             PG8_WAIT_V(8); PG8_WAIT_L(0); PG8_BAR; PG8_MMA(1, 0, At, B0); PG8_MMA(1, 1, At, B1); PG8_BAR; PG8_SCHED;
;             PG8_LDB(B0, 1, 0); PG8_LDB(B1, 1, 1); PG8_SCHED; PG8_LDA(At, 1, 0); PG8_STAGE(PG8_SA(0, 1), a2 + hstepA, voffA);
;             PG8_WAIT_V(8); PG8_WAIT_L(0); PG8_BAR; PG8_MMA(0, 0, At, B0); PG8_MMA(0, 1, At, B1); PG8_BAR; PG8_SCHED;
	s_setprio 1
	s_waitcnt lgkmcnt(0)
	v_mfma_f32_16x16x32_bf16 v[62:65], v[136:139], v[174:177], v[62:65]
	v_mfma_f32_16x16x32_bf16 v[58:61], v[150:153], v[174:177], v[58:61]
	v_mfma_f32_16x16x32_bf16 v[46:49], v[136:139], v[182:185], v[46:49]
	v_mfma_f32_16x16x32_bf16 v[42:45], v[150:153], v[182:185], v[42:45]
	v_mfma_f32_16x16x32_bf16 v[30:33], v[136:139], v[224:227], v[30:33]
	v_mfma_f32_16x16x32_bf16 v[26:29], v[150:153], v[224:227], v[26:29]
	v_mfma_f32_16x16x32_bf16 v[14:17], v[136:139], v[246:249], v[14:17]
	v_mfma_f32_16x16x32_bf16 v[10:13], v[150:153], v[246:249], v[10:13]
	v_mfma_f32_16x16x32_bf16 v[62:65], v[140:143], v[178:181], v[62:65]
	v_mfma_f32_16x16x32_bf16 v[58:61], v[154:157], v[178:181], v[58:61]
	v_mfma_f32_16x16x32_bf16 v[46:49], v[140:143], v[220:223], v[46:49]
	v_mfma_f32_16x16x32_bf16 v[42:45], v[154:157], v[220:223], v[42:45]
	v_mfma_f32_16x16x32_bf16 v[30:33], v[140:143], v[242:245], v[30:33]
	v_mfma_f32_16x16x32_bf16 v[26:29], v[154:157], v[242:245], v[26:29]
	v_mfma_f32_16x16x32_bf16 v[14:17], v[140:143], v[250:253], v[14:17]
	v_mfma_f32_16x16x32_bf16 v[10:13], v[154:157], v[250:253], v[10:13]
	s_setprio 0
	s_setprio 1
	v_mfma_f32_16x16x32_bf16 v[54:57], v[158:161], v[174:177], v[54:57]
	v_mfma_f32_16x16x32_bf16 v[50:53], v[166:169], v[174:177], v[50:53]
	v_mfma_f32_16x16x32_bf16 v[38:41], v[158:161], v[182:185], v[38:41]
	v_mfma_f32_16x16x32_bf16 v[34:37], v[166:169], v[182:185], v[34:37]
	v_mfma_f32_16x16x32_bf16 v[22:25], v[158:161], v[224:227], v[22:25]
	v_mfma_f32_16x16x32_bf16 v[18:21], v[166:169], v[224:227], v[18:21]
	v_mfma_f32_16x16x32_bf16 v[6:9], v[158:161], v[246:249], v[6:9]
	v_mfma_f32_16x16x32_bf16 v[2:5], v[166:169], v[246:249], v[2:5]
	v_mfma_f32_16x16x32_bf16 v[54:57], v[162:165], v[178:181], v[54:57]
	v_mfma_f32_16x16x32_bf16 v[50:53], v[170:173], v[178:181], v[50:53]
	v_mfma_f32_16x16x32_bf16 v[38:41], v[162:165], v[220:223], v[38:41]
	v_mfma_f32_16x16x32_bf16 v[34:37], v[170:173], v[220:223], v[34:37]
	v_mfma_f32_16x16x32_bf16 v[22:25], v[162:165], v[242:245], v[22:25]
	v_mfma_f32_16x16x32_bf16 v[18:21], v[170:173], v[242:245], v[18:21]
	v_mfma_f32_16x16x32_bf16 v[6:9], v[162:165], v[250:253], v[6:9]
	v_mfma_f32_16x16x32_bf16 v[2:5], v[170:173], v[250:253], v[2:5]
	s_setprio 0
	s_barrier
	v_add_u32_e32 v154, s23, v148
	v_add_u32_e32 v170, s22, v148
	ds_read_b128 v[136:139], v154
	ds_read_b128 v[140:143], v154 offset:1024
	ds_read_b128 v[150:153], v154 offset:2048
	ds_read_b128 v[154:157], v154 offset:3072
	ds_read_b128 v[158:161], v170
	ds_read_b128 v[162:165], v170 offset:1024
	ds_read_b128 v[166:169], v170 offset:2048
	ds_read_b128 v[170:173], v170 offset:3072
	s_mov_b32 m0, s47
	ds_read_b128 v[174:177], v149 offset:32768
	ds_read_b128 v[178:181], v149 offset:33792
	ds_read_b128 v[182:185], v149 offset:34816
	ds_read_b128 v[220:223], v149 offset:35840
	ds_read_b128 v[224:227], v149 offset:36864
	ds_read_b128 v[242:245], v149 offset:37888
	ds_read_b128 v[246:249], v149 offset:38912
	ds_read_b128 v[250:253], v149 offset:39936
	global_load_lds_dwordx4 v0, s[42:43]
	v_lshl_add_u64 v[230:231], s[42:43], 0, v[132:133]
	s_mov_b32 m0, s55
	s_nop 0
	global_load_lds_dwordx4 v[230:231], off
	s_waitcnt vmcnt(8)
	s_waitcnt lgkmcnt(0)
	s_barrier
	s_setprio 1
	s_waitcnt lgkmcnt(0)
	v_mfma_f32_16x16x32_bf16 v[126:129], v[136:139], v[174:177], v[126:129]
	v_mfma_f32_16x16x32_bf16 v[122:125], v[150:153], v[174:177], v[122:125]
	v_mfma_f32_16x16x32_bf16 v[110:113], v[136:139], v[182:185], v[110:113]
	v_mfma_f32_16x16x32_bf16 v[106:109], v[150:153], v[182:185], v[106:109]
	v_mfma_f32_16x16x32_bf16 v[94:97], v[136:139], v[224:227], v[94:97]
	v_mfma_f32_16x16x32_bf16 v[90:93], v[150:153], v[224:227], v[90:93]
	v_mfma_f32_16x16x32_bf16 v[78:81], v[136:139], v[246:249], v[78:81]
	v_mfma_f32_16x16x32_bf16 v[74:77], v[150:153], v[246:249], v[74:77]
	v_mfma_f32_16x16x32_bf16 v[126:129], v[140:143], v[178:181], v[126:129]
	v_mfma_f32_16x16x32_bf16 v[122:125], v[154:157], v[178:181], v[122:125]
	v_mfma_f32_16x16x32_bf16 v[110:113], v[140:143], v[220:223], v[110:113]
	v_mfma_f32_16x16x32_bf16 v[106:109], v[154:157], v[220:223], v[106:109]
	v_mfma_f32_16x16x32_bf16 v[94:97], v[140:143], v[242:245], v[94:97]
	v_mfma_f32_16x16x32_bf16 v[90:93], v[154:157], v[242:245], v[90:93]
	v_mfma_f32_16x16x32_bf16 v[78:81], v[140:143], v[250:253], v[78:81]
	v_mfma_f32_16x16x32_bf16 v[74:77], v[154:157], v[250:253], v[74:77]
	s_setprio 0
	s_setprio 1
	v_mfma_f32_16x16x32_bf16 v[118:121], v[158:161], v[174:177], v[118:121]
	v_mfma_f32_16x16x32_bf16 v[114:117], v[166:169], v[174:177], v[114:117]
	v_mfma_f32_16x16x32_bf16 v[102:105], v[158:161], v[182:185], v[102:105]
	v_mfma_f32_16x16x32_bf16 v[98:101], v[166:169], v[182:185], v[98:101]
	v_mfma_f32_16x16x32_bf16 v[86:89], v[158:161], v[224:227], v[86:89]
	v_mfma_f32_16x16x32_bf16 v[82:85], v[166:169], v[224:227], v[82:85]
	v_mfma_f32_16x16x32_bf16 v[70:73], v[158:161], v[246:249], v[70:73]
	v_mfma_f32_16x16x32_bf16 v[66:69], v[166:169], v[246:249], v[66:69]
	v_mfma_f32_16x16x32_bf16 v[118:121], v[162:165], v[178:181], v[118:121]
	v_mfma_f32_16x16x32_bf16 v[114:117], v[170:173], v[178:181], v[114:117]
	v_mfma_f32_16x16x32_bf16 v[102:105], v[162:165], v[220:223], v[102:105]
	v_mfma_f32_16x16x32_bf16 v[98:101], v[170:173], v[220:223], v[98:101]
	v_mfma_f32_16x16x32_bf16 v[86:89], v[162:165], v[242:245], v[86:89]
	v_mfma_f32_16x16x32_bf16 v[82:85], v[170:173], v[242:245], v[82:85]
	v_mfma_f32_16x16x32_bf16 v[70:73], v[162:165], v[250:253], v[70:73]
	v_mfma_f32_16x16x32_bf16 v[66:69], v[170:173], v[250:253], v[66:69]
	s_setprio 0
	s_barrier
; #define PG8_STAGE(bufoff, gbase, voff) do { _Pragma("unroll") for (int _i = 0; _i < 2; ++_i) \
;         __builtin_amdgcn_global_load_lds((const unsigned*)((const char*)(gbase) + (voff)[_i]), (PG8_LAS unsigned*)(lds + (bufoff) + ldsw + _i * 8192), 16, 0, 0); } while (0)
; #define PG8_LDA(dst, b, h) do { _Pragma("unroll") for (int m = 0; m < 4; ++m) _Pragma("unroll") for (int k = 0; k < 2; ++k) dst[m][k] = *(const PG8_LAS bf16x8*)(lds + PG8_SA(b, h) + aoff + m * 2048 + k * 1024); } while (0)
; #define PG8_MMA(ai, bj, At, Bt) do { __builtin_amdgcn_s_setprio(1); _Pragma("unroll") for (int m = 0; m < 4; ++m) _Pragma("unroll") for (int n = 0; n < 2; ++n) _Pragma("unroll") for (int k = 0; k < 2; ++k) \
;         acc[ai][bj][m][n] = __builtin_amdgcn_mfma_f32_16x16x32_bf16(Bt[n][k], At[m][k], acc[ai][bj][m][n], 0, 0, 0); __builtin_amdgcn_s_setprio(0); } while (0)
; #define PG8_WAIT_V(n) asm volatile("s_waitcnt vmcnt(" #n ")" ::: "memory")
; #define PG8_WAIT_L(n) asm volatile("s_waitcnt lgkmcnt(" #n ")" ::: "memory")
; #define PG8_BAR __builtin_amdgcn_s_barrier()
; #define PG8_SCHED __builtin_amdgcn_sched_barrier(0)
; template <class Epi, class Sched, bool ALIGN_EPI = false, bool SP2 = false>
; __device__ __forceinline__ void gemm_phase(PG8_LAS unsigned char* lds, const Gemm g, const Sched& S, const Epi& E, int wv) {
;     ...
;         for (int t = 0; t < nt; t += 2) {
;             const bool last = (t == nt - 2);
;     ...
;             PG8_LDA(At, 1, 1); PG8_STAGE(PG8_SB(1, 0), b3, voffB); PG8_STAGE(PG8_SB(1, 1), b3 + hstepB, voffB); PG8_STAGE(PG8_SA(1, 0), a3, voffA);
;             PG8_WAIT_V(8); PG8_WAIT_L(0); PG8_BAR; PG8_MMA(1, 0, At, B0); PG8_MMA(1, 1, At, B1); PG8_BAR; PG8_SCHED;
	s_mov_b32 m0, vcc_hi
	v_lshl_add_u64 v[144:145], v[144:145], 0, s[62:63]
	ds_read_b128 v[174:177], v149 offset:49152
	ds_read_b128 v[178:181], v149 offset:50176
	ds_read_b128 v[182:185], v149 offset:51200
	ds_read_b128 v[220:223], v149 offset:52224
	ds_read_b128 v[224:227], v149 offset:53248
	ds_read_b128 v[242:245], v149 offset:54272
	ds_read_b128 v[246:249], v149 offset:55296
	ds_read_b128 v[250:253], v149 offset:56320
	global_load_lds_dwordx4 v[144:145], off
	v_lshl_add_u64 v[144:145], v[186:187], 0, s[62:63]
	s_mov_b32 m0, vcc_lo
	s_nop 0
	global_load_lds_dwordx4 v[144:145], off
	s_mov_b32 m0, s88
	s_nop 0
	global_load_lds_dwordx4 v130, s[2:3]
	s_mov_b32 m0, s60
	s_nop 0
	global_load_lds_dwordx4 v134, s[2:3]
	v_lshl_add_u64 v[144:145], v[196:197], 0, s[62:63]
	s_mov_b32 m0, s45
	s_nop 0
	global_load_lds_dwordx4 v[144:145], off
	v_lshl_add_u64 v[144:145], v[228:229], 0, s[62:63]
	s_mov_b32 m0, s26
	s_nop 0
	global_load_lds_dwordx4 v[144:145], off
	s_waitcnt vmcnt(8)
	s_waitcnt lgkmcnt(0)
	s_barrier
	s_setprio 1
	s_waitcnt lgkmcnt(0)
	v_mfma_f32_16x16x32_bf16 v[62:65], v[136:139], v[174:177], v[62:65]
	v_mfma_f32_16x16x32_bf16 v[58:61], v[150:153], v[174:177], v[58:61]
	v_mfma_f32_16x16x32_bf16 v[46:49], v[136:139], v[182:185], v[46:49]
	v_mfma_f32_16x16x32_bf16 v[42:45], v[150:153], v[182:185], v[42:45]
	v_mfma_f32_16x16x32_bf16 v[30:33], v[136:139], v[224:227], v[30:33]
	v_mfma_f32_16x16x32_bf16 v[26:29], v[150:153], v[224:227], v[26:29]
	v_mfma_f32_16x16x32_bf16 v[14:17], v[136:139], v[246:249], v[14:17]
	v_mfma_f32_16x16x32_bf16 v[10:13], v[150:153], v[246:249], v[10:13]
	v_mfma_f32_16x16x32_bf16 v[62:65], v[140:143], v[178:181], v[62:65]
	v_mfma_f32_16x16x32_bf16 v[58:61], v[154:157], v[178:181], v[58:61]
	v_mfma_f32_16x16x32_bf16 v[46:49], v[140:143], v[220:223], v[46:49]
	v_mfma_f32_16x16x32_bf16 v[42:45], v[154:157], v[220:223], v[42:45]
	v_mfma_f32_16x16x32_bf16 v[30:33], v[140:143], v[242:245], v[30:33]
	v_mfma_f32_16x16x32_bf16 v[26:29], v[154:157], v[242:245], v[26:29]
	v_mfma_f32_16x16x32_bf16 v[14:17], v[140:143], v[250:253], v[14:17]
	v_mfma_f32_16x16x32_bf16 v[10:13], v[154:157], v[250:253], v[10:13]
	s_setprio 0
	s_setprio 1
	v_mfma_f32_16x16x32_bf16 v[54:57], v[158:161], v[174:177], v[54:57]
	v_mfma_f32_16x16x32_bf16 v[50:53], v[166:169], v[174:177], v[50:53]
	v_mfma_f32_16x16x32_bf16 v[38:41], v[158:161], v[182:185], v[38:41]
	v_mfma_f32_16x16x32_bf16 v[34:37], v[166:169], v[182:185], v[34:37]
	v_mfma_f32_16x16x32_bf16 v[22:25], v[158:161], v[224:227], v[22:25]
	v_mfma_f32_16x16x32_bf16 v[18:21], v[166:169], v[224:227], v[18:21]
	v_mfma_f32_16x16x32_bf16 v[6:9], v[158:161], v[246:249], v[6:9]
	v_mfma_f32_16x16x32_bf16 v[2:5], v[166:169], v[246:249], v[2:5]
	v_mfma_f32_16x16x32_bf16 v[54:57], v[162:165], v[178:181], v[54:57]
	v_mfma_f32_16x16x32_bf16 v[50:53], v[170:173], v[178:181], v[50:53]
	v_mfma_f32_16x16x32_bf16 v[38:41], v[162:165], v[220:223], v[38:41]
	v_mfma_f32_16x16x32_bf16 v[34:37], v[170:173], v[220:223], v[34:37]
	v_mfma_f32_16x16x32_bf16 v[22:25], v[162:165], v[242:245], v[22:25]
	v_mfma_f32_16x16x32_bf16 v[18:21], v[170:173], v[242:245], v[18:21]
	v_mfma_f32_16x16x32_bf16 v[6:9], v[162:165], v[250:253], v[6:9]
	v_mfma_f32_16x16x32_bf16 v[2:5], v[170:173], v[250:253], v[2:5]
	s_setprio 0
	s_barrier
	s_andn2_b64 vcc, exec, s[18:19]
	s_mov_b64 s[2:3], -1
	s_mov_b64 s[18:19], 0
	s_mov_b64 s[42:43], 0x100
	s_cbranch_vccz .LBB0_1271
	v_readlane_b32 s2, v254, 61
	v_readlane_b32 s3, v254, 62
	s_and_b64 vcc, exec, s[2:3]
	s_cbranch_vccz .LBB0_1274
	s_barrier

; #define PG8_STAGE(bufoff, gbase, voff) do { _Pragma("unroll") for (int _i = 0; _i < 2; ++_i) \
;         __builtin_amdgcn_global_load_lds((const unsigned*)((const char*)(gbase) + (voff)[_i]), (PG8_LAS unsigned*)(lds + (bufoff) + ldsw + _i * 8192), 16, 0, 0); } while (0)
; #define PG8_WAIT_V(n) asm volatile("s_waitcnt vmcnt(" #n ")" ::: "memory")
; #define PG8_BAR __builtin_amdgcn_s_barrier()
; template <class Epi, class Sched, bool ALIGN_EPI = false, bool SP2 = false>
; __device__ __forceinline__ void gemm_phase(PG8_LAS unsigned char* lds, const Gemm g, const Sched& S, const Epi& E, int wv) {
;     ...
;     for (int i = 0; i < 2; ++i) { int R, C; stage_rc(tid * 16 + i * 8192, R, C); const int Rb = Epi::PERM ? ((R & ~31) + perm32(R & 31)) : R;
;         voffA[i] = (unsigned)(R * g.lda + C) * 2u; voffB[i] = (unsigned)(Rb * K + C) * 2u; }
;     const size_t kstep = (size_t)(BK * 2);
;     const size_t hstepA = (size_t)HALF * g.lda * 2, hstepB = (size_t)HALF * K * 2;
;     const size_t tstepA = 2 * hstepA, tstepB = 2 * hstepB;
;     const unsigned ldsw = (unsigned)wid * 1024u;
;     const int aoff = lds_byte(wr * 64 + fr, fq * 8), boff = lds_byte(wc * 32 + fr, fq * 8);
;     ...
;         PG8_STAGE(PG8_SB(0, 0), cB, voffB); PG8_STAGE(PG8_SB(0, 1), cB + hstepB, voffB); PG8_STAGE(PG8_SA(0, 0), cA, voffA); PG8_STAGE(PG8_SA(0, 1), cA + hstepA, voffA);
;         if (wr == 1) PG8_BAR;
;         PG8_WAIT_V(2); PG8_BAR;
;         PG8_STAGE(PG8_SB(1, 0), cB + kstep, voffB); PG8_STAGE(PG8_SA(1, 0), cA + kstep, voffA); PG8_STAGE(PG8_SB(1, 1), cB + hstepB + kstep, voffB);
;         PG8_WAIT_V(6); PG8_BAR;
.LBB0_1733:
	s_add_u32 s24, s16, 0x2800000
	v_readlane_b32 s28, v254, 50
	s_addc_u32 s25, s17, 0
	v_readlane_b32 s29, v254, 51
	s_and_b64 s[28:29], s[28:29], exec
	s_cselect_b32 s27, s27, 0
	s_cselect_b32 s26, s26, 0
	s_add_u32 s28, s16, 0x1e800000
	s_addc_u32 s29, s17, 0
	s_and_b32 s19, s34, 3
	s_add_i32 m0, s43, 0x18000
	v_lshl_add_u64 v[8:9], v[8:9], 0, s[62:63]
	s_lshl_b32 s58, s35, 6
	s_lshl_b32 s34, s35, 13
	s_lshl_b32 s82, s19, 5
	s_lshl_b32 s35, s19, 12
	s_waitcnt vmcnt(2)
	s_barrier
	global_load_lds_dwordx4 v[8:9], off
	v_lshl_add_u64 v[6:7], v[6:7], 0, s[62:63]
	s_add_i32 m0, s43, 0x1a000
	s_add_i32 s83, s43, 0x8000
	s_add_i32 s87, s43, 0xa000
	global_load_lds_dwordx4 v[6:7], off
	v_lshl_add_u64 v[2:3], v[2:3], 0, s[62:63]
	s_mov_b32 m0, s83
	s_add_u32 s16, s2, 0x40080
	global_load_lds_dwordx4 v[2:3], off
	v_lshl_add_u64 v[2:3], v[4:5], 0, s[62:63]
	s_mov_b32 m0, s87
	s_addc_u32 s17, s3, 0
	global_load_lds_dwordx4 v[2:3], off
	s_add_i32 m0, s43, 0x1c000
	s_nop 0
	global_load_lds_dwordx4 v0, s[16:17]
	v_lshl_add_u64 v[2:3], s[16:17], 0, v[142:143]
	s_add_i32 m0, s43, 0x1e000
	v_bfe_u32 v159, v10, 4, 2
	global_load_lds_dwordx4 v[2:3], off
	v_and_b32_e32 v158, 15, v10
	v_lshlrev_b32_e32 v2, 4, v159
	v_lshlrev_b32_e32 v3, 2, v10
	v_lshl_or_b32 v2, v158, 6, v2
	v_and_b32_e32 v3, 32, v3
	v_bitop3_b32 v4, v2, s34, v3 bitop3:0xde
	v_bitop3_b32 v160, v2, s35, v3 bitop3:0xde
	v_lshlrev_b32_e32 v2, 14, v11
	v_and_b32_e32 v2, 0xffff8000, v2
	v_lshl_add_u32 v2, v12, 11, v2
	v_and_b32_e32 v3, 1, v11
	v_lshl_or_b32 v2, v3, 6, v2
	v_lshl_add_u32 v144, v13, 1, v2
	v_lshlrev_b32_e32 v2, 14, v14
	s_cmpk_lt_u32 s15, 0x100
	v_and_b32_e32 v2, 0xffff8000, v2
	s_waitcnt vmcnt(6)
	s_cselect_b64 s[36:37], -1, 0
	s_lshl_b32 s92, s19, 1
	s_ashr_i32 s93, s12, 31
	s_ashr_i32 s96, s7, 31
	v_lshl_add_u32 v2, v15, 11, v2
	v_and_b32_e32 v3, 1, v14
	s_cmp_lg_u64 s[26:27], 0
	v_lshl_or_b32 v2, v3, 6, v2
	s_mov_b32 s91, 0
	s_cselect_b64 s[38:39], -1, 0
	v_mov_b32_e32 v145, v1
	v_lshl_add_u32 v146, v16, 1, v2
	v_mov_b32_e32 v147, v1
	v_add_u32_e32 v161, 0, v4
	s_barrier
	s_branch .LBB0_1736

; #define PG8_STAGE(bufoff, gbase, voff) do { _Pragma("unroll") for (int _i = 0; _i < 2; ++_i) \
;         __builtin_amdgcn_global_load_lds((const unsigned*)((const char*)(gbase) + (voff)[_i]), (PG8_LAS unsigned*)(lds + (bufoff) + ldsw + _i * 8192), 16, 0, 0); } while (0)
; #define PG8_LDA(dst, b, h) do { _Pragma("unroll") for (int m = 0; m < 4; ++m) _Pragma("unroll") for (int k = 0; k < 2; ++k) dst[m][k] = *(const PG8_LAS bf16x8*)(lds + PG8_SA(b, h) + aoff + m * 2048 + k * 1024); } while (0)
; #define PG8_LDB(dst, b, h) do { _Pragma("unroll") for (int n = 0; n < 2; ++n) _Pragma("unroll") for (int k = 0; k < 2; ++k) dst[n][k] = *(const PG8_LAS bf16x8*)(lds + PG8_SB(b, h) + boff + n * 2048 + k * 1024); } while (0)
; #define PG8_MMA(ai, bj, At, Bt) do { __builtin_amdgcn_s_setprio(1); _Pragma("unroll") for (int m = 0; m < 4; ++m) _Pragma("unroll") for (int n = 0; n < 2; ++n) _Pragma("unroll") for (int k = 0; k < 2; ++k) \
;         acc[ai][bj][m][n] = __builtin_amdgcn_mfma_f32_16x16x32_bf16(Bt[n][k], At[m][k], acc[ai][bj][m][n], 0, 0, 0); __builtin_amdgcn_s_setprio(0); } while (0)
; template <class Epi, class Sched, bool ALIGN_EPI = false, bool SP2 = false>
; __device__ __forceinline__ void gemm_phase(PG8_LAS unsigned char* lds, const Gemm g, const Sched& S, const Epi& E, int wv) {
;     ...
;         const bool has_next = S.next(ui + 1, nxt);
;         const char* nA = has_next ? (const char*)g.A + (size_t)nxt.pm * tstepA : cA; const char* nB = has_next ? (const char*)g.Bt + (size_t)nxt.pn * tstepB : cB;
; #pragma unroll 1
;         for (int t = 0; t < nt; t += 2) {
;             const bool last = (t == nt - 2);
;             const char* a1 = cA + (size_t)(t + 1) * kstep;
;             const char* a2 = last ? nA : cA + (size_t)(t + 2) * kstep; const char* b2 = last ? nB : cB + (size_t)(t + 2) * kstep;
;             const char* a3 = a2 + kstep; const char* b3 = b2 + kstep;
;             if (last && has_next) S.a_ready(nxt);
;             if constexpr (SP2) {
;             PG8_LDB(B0, 0, 0); PG8_LDB(B1, 0, 1); PG8_SCHED; PG8_LDA(At, 0, 0); PG8_STAGE(PG8_SA(1, 1), a1 + hstepA, voffA);
;             PG8_WAIT_V(8); PG8_WAIT_L(0); PG8_BAR; PG8_MMA(0, 0, At, B0); PG8_MMA(0, 1, At, B1); PG8_BAR; PG8_SCHED;
;             PG8_LDA(At, 0, 1); PG8_STAGE(PG8_SB(0, 0), b2, voffB); PG8_STAGE(PG8_SB(0, 1), b2 + hstepB, voffB); PG8_STAGE(PG8_SA(0, 0), a2, voffA);
.LBB0_1743:
	s_add_u32 s2, s20, 0xfffc0080
	s_addc_u32 s3, s21, -1
	s_add_i32 s60, 0, 0x10000
	s_cmp_eq_u32 s97, 12
	s_cselect_b32 s35, s15, s3
	s_cselect_b32 s34, s19, s2
	s_cselect_b32 s3, s45, s95
	s_cselect_b32 s2, s47, s94
	s_add_i32 s61, 0, 0x14000
	v_add_u32_e32 v152, s60, v160
	v_add_u32_e32 v156, s61, v160
	ds_read_b128 v[130:133], v152
	ds_read_b128 v[134:137], v152 offset:1024
	ds_read_b128 v[148:151], v152 offset:2048
	ds_read_b128 v[152:155], v152 offset:3072
	ds_read_b128 v[162:165], v156
	ds_read_b128 v[166:169], v156 offset:1024
	ds_read_b128 v[170:173], v156 offset:2048
	ds_read_b128 v[174:177], v156 offset:3072
	s_add_i32 m0, s43, 0xc000
	ds_read_b128 v[178:181], v161
	ds_read_b128 v[182:185], v161 offset:1024
	ds_read_b128 v[220:223], v161 offset:2048
	ds_read_b128 v[224:227], v161 offset:3072
	ds_read_b128 v[242:245], v161 offset:4096
	ds_read_b128 v[246:249], v161 offset:5120
	ds_read_b128 v[250:253], v161 offset:6144
	ds_read_b128 v[228:231], v161 offset:7168
	global_load_lds_dwordx4 v144, s[20:21]
	s_add_i32 m0, s43, 0xe000
	s_nop 0
	global_load_lds_dwordx4 v146, s[20:21]
	s_waitcnt vmcnt(8)
	s_waitcnt lgkmcnt(0)
	s_barrier
	s_setprio 1
	s_waitcnt lgkmcnt(0)
	v_mfma_f32_16x16x32_bf16 v[126:129], v[130:133], v[178:181], v[126:129]
	v_mfma_f32_16x16x32_bf16 v[122:125], v[148:151], v[178:181], v[122:125]
	v_mfma_f32_16x16x32_bf16 v[110:113], v[130:133], v[220:223], v[110:113]
	v_mfma_f32_16x16x32_bf16 v[106:109], v[148:151], v[220:223], v[106:109]
	v_mfma_f32_16x16x32_bf16 v[94:97], v[130:133], v[242:245], v[94:97]
	v_mfma_f32_16x16x32_bf16 v[90:93], v[148:151], v[242:245], v[90:93]
	v_mfma_f32_16x16x32_bf16 v[78:81], v[130:133], v[250:253], v[78:81]
	v_mfma_f32_16x16x32_bf16 v[74:77], v[148:151], v[250:253], v[74:77]
	v_mfma_f32_16x16x32_bf16 v[126:129], v[134:137], v[182:185], v[126:129]
	v_mfma_f32_16x16x32_bf16 v[122:125], v[152:155], v[182:185], v[122:125]
	v_mfma_f32_16x16x32_bf16 v[110:113], v[134:137], v[224:227], v[110:113]
	v_mfma_f32_16x16x32_bf16 v[106:109], v[152:155], v[224:227], v[106:109]
	v_mfma_f32_16x16x32_bf16 v[94:97], v[134:137], v[246:249], v[94:97]
	v_mfma_f32_16x16x32_bf16 v[90:93], v[152:155], v[246:249], v[90:93]
	v_mfma_f32_16x16x32_bf16 v[78:81], v[134:137], v[228:231], v[78:81]
	v_mfma_f32_16x16x32_bf16 v[74:77], v[152:155], v[228:231], v[74:77]
	s_setprio 0
	s_setprio 1
	v_mfma_f32_16x16x32_bf16 v[118:121], v[162:165], v[178:181], v[118:121]
	v_mfma_f32_16x16x32_bf16 v[114:117], v[170:173], v[178:181], v[114:117]
	v_mfma_f32_16x16x32_bf16 v[102:105], v[162:165], v[220:223], v[102:105]
	v_mfma_f32_16x16x32_bf16 v[98:101], v[170:173], v[220:223], v[98:101]
	v_mfma_f32_16x16x32_bf16 v[86:89], v[162:165], v[242:245], v[86:89]
	v_mfma_f32_16x16x32_bf16 v[82:85], v[170:173], v[242:245], v[82:85]
	v_mfma_f32_16x16x32_bf16 v[70:73], v[162:165], v[250:253], v[70:73]
	v_mfma_f32_16x16x32_bf16 v[66:69], v[170:173], v[250:253], v[66:69]
	v_mfma_f32_16x16x32_bf16 v[118:121], v[166:169], v[182:185], v[118:121]
	v_mfma_f32_16x16x32_bf16 v[114:117], v[174:177], v[182:185], v[114:117]
	v_mfma_f32_16x16x32_bf16 v[102:105], v[166:169], v[224:227], v[102:105]
	v_mfma_f32_16x16x32_bf16 v[98:101], v[174:177], v[224:227], v[98:101]
	v_mfma_f32_16x16x32_bf16 v[86:89], v[166:169], v[246:249], v[86:89]
	v_mfma_f32_16x16x32_bf16 v[82:85], v[174:177], v[246:249], v[82:85]
	v_mfma_f32_16x16x32_bf16 v[70:73], v[166:169], v[228:231], v[70:73]
	v_mfma_f32_16x16x32_bf16 v[66:69], v[174:177], v[228:231], v[66:69]
	s_setprio 0
	s_barrier
	s_add_i32 s60, s60, s42
	v_lshl_add_u64 v[156:157], s[2:3], 0, v[0:1]
	s_mov_b32 m0, s60
	ds_read_b128 v[178:181], v161 offset:16384
	ds_read_b128 v[182:185], v161 offset:17408
	ds_read_b128 v[220:223], v161 offset:18432
	ds_read_b128 v[224:227], v161 offset:19456
	ds_read_b128 v[228:231], v161 offset:20480
	ds_read_b128 v[242:245], v161 offset:21504
	ds_read_b128 v[246:249], v161 offset:22528
	ds_read_b128 v[250:253], v161 offset:23552
	global_load_lds_dwordx4 v[156:157], off
	s_add_i32 m0, s60, 0x2000
	s_add_u32 vcc_lo, s2, 0x40000
	v_lshl_add_u64 v[186:187], s[2:3], 0, v[142:143]
	s_addc_u32 vcc_hi, s3, 0
	s_add_i32 s60, s61, s42
	global_load_lds_dwordx4 v[186:187], off
	v_lshl_add_u64 v[196:197], vcc, 0, v[0:1]
	s_mov_b32 m0, s60
	v_lshl_add_u64 v[232:233], s[34:35], 0, v[140:141]
	global_load_lds_dwordx4 v[196:197], off
	v_lshl_add_u64 v[196:197], vcc, 0, v[142:143]
	s_add_i32 m0, s60, 0x2000
	s_nop 0
	global_load_lds_dwordx4 v[196:197], off
	v_lshl_add_u64 v[196:197], s[34:35], 0, v[138:139]
	s_mov_b32 m0, s43
	s_nop 0
	global_load_lds_dwordx4 v[196:197], off
	s_mov_b32 m0, s52
	s_nop 0
	global_load_lds_dwordx4 v[232:233], off
	s_waitcnt vmcnt(8)
	s_waitcnt lgkmcnt(0)
	s_barrier
; #define PG8_STAGE(bufoff, gbase, voff) do { _Pragma("unroll") for (int _i = 0; _i < 2; ++_i) \
;         __builtin_amdgcn_global_load_lds((const unsigned*)((const char*)(gbase) + (voff)[_i]), (PG8_LAS unsigned*)(lds + (bufoff) + ldsw + _i * 8192), 16, 0, 0); } while (0)
; #define PG8_LDA(dst, b, h) do { _Pragma("unroll") for (int m = 0; m < 4; ++m) _Pragma("unroll") for (int k = 0; k < 2; ++k) dst[m][k] = *(const PG8_LAS bf16x8*)(lds + PG8_SA(b, h) + aoff + m * 2048 + k * 1024); } while (0)
; #define PG8_LDB(dst, b, h) do { _Pragma("unroll") for (int n = 0; n < 2; ++n) _Pragma("unroll") for (int k = 0; k < 2; ++k) dst[n][k] = *(const PG8_LAS bf16x8*)(lds + PG8_SB(b, h) + boff + n * 2048 + k * 1024); } while (0)
; #define PG8_MMA(ai, bj, At, Bt) do { __builtin_amdgcn_s_setprio(1); _Pragma("unroll") for (int m = 0; m < 4; ++m) _Pragma("unroll") for (int n = 0; n < 2; ++n) _Pragma("unroll") for (int k = 0; k < 2; ++k) \
;         acc[ai][bj][m][n] = __builtin_amdgcn_mfma_f32_16x16x32_bf16(Bt[n][k], At[m][k], acc[ai][bj][m][n], 0, 0, 0); __builtin_amdgcn_s_setprio(0); } while (0)
; #define PG8_WAIT_V(n) asm volatile("s_waitcnt vmcnt(" #n ")" ::: "memory")
; #define PG8_WAIT_L(n) asm volatile("s_waitcnt lgkmcnt(" #n ")" ::: "memory")
; #define PG8_BAR __builtin_amdgcn_s_barrier()
; #define PG8_SCHED __builtin_amdgcn_sched_barrier(0)
; template <class Epi, class Sched, bool ALIGN_EPI = false, bool SP2 = false>
; __device__ __forceinline__ void gemm_phase(PG8_LAS unsigned char* lds, const Gemm g, const Sched& S, const Epi& E, int wv) {
;     ...
;             PG8_WAIT_V(8); PG8_WAIT_L(0); PG8_BAR; PG8_MMA(1, 0, At, B0); PG8_MMA(1, 1, At, B1); PG8_BAR; PG8_SCHED;
;             PG8_LDB(B0, 1, 0); PG8_LDB(B1, 1, 1); PG8_SCHED; PG8_LDA(At, 1, 0); PG8_STAGE(PG8_SA(0, 1), a2 + hstepA, voffA);
;             PG8_WAIT_V(8); PG8_WAIT_L(0); PG8_BAR; PG8_MMA(0, 0, At, B0); PG8_MMA(0, 1, At, B1); PG8_BAR; PG8_SCHED;
	s_setprio 1
	s_waitcnt lgkmcnt(0)
	v_mfma_f32_16x16x32_bf16 v[62:65], v[130:133], v[178:181], v[62:65]
	v_mfma_f32_16x16x32_bf16 v[58:61], v[148:151], v[178:181], v[58:61]
	v_mfma_f32_16x16x32_bf16 v[46:49], v[130:133], v[220:223], v[46:49]
	v_mfma_f32_16x16x32_bf16 v[42:45], v[148:151], v[220:223], v[42:45]
	v_mfma_f32_16x16x32_bf16 v[30:33], v[130:133], v[228:231], v[30:33]
	v_mfma_f32_16x16x32_bf16 v[26:29], v[148:151], v[228:231], v[26:29]
	v_mfma_f32_16x16x32_bf16 v[14:17], v[130:133], v[246:249], v[14:17]
	v_mfma_f32_16x16x32_bf16 v[10:13], v[148:151], v[246:249], v[10:13]
	v_mfma_f32_16x16x32_bf16 v[62:65], v[134:137], v[182:185], v[62:65]
	v_mfma_f32_16x16x32_bf16 v[58:61], v[152:155], v[182:185], v[58:61]
	v_mfma_f32_16x16x32_bf16 v[46:49], v[134:137], v[224:227], v[46:49]
	v_mfma_f32_16x16x32_bf16 v[42:45], v[152:155], v[224:227], v[42:45]
	v_mfma_f32_16x16x32_bf16 v[30:33], v[134:137], v[242:245], v[30:33]
	v_mfma_f32_16x16x32_bf16 v[26:29], v[152:155], v[242:245], v[26:29]
	v_mfma_f32_16x16x32_bf16 v[14:17], v[134:137], v[250:253], v[14:17]
	v_mfma_f32_16x16x32_bf16 v[10:13], v[152:155], v[250:253], v[10:13]
	s_setprio 0
	s_setprio 1
	v_mfma_f32_16x16x32_bf16 v[54:57], v[162:165], v[178:181], v[54:57]
	v_mfma_f32_16x16x32_bf16 v[50:53], v[170:173], v[178:181], v[50:53]
	v_mfma_f32_16x16x32_bf16 v[38:41], v[162:165], v[220:223], v[38:41]
	v_mfma_f32_16x16x32_bf16 v[34:37], v[170:173], v[220:223], v[34:37]
	v_mfma_f32_16x16x32_bf16 v[22:25], v[162:165], v[228:231], v[22:25]
	v_mfma_f32_16x16x32_bf16 v[18:21], v[170:173], v[228:231], v[18:21]
	v_mfma_f32_16x16x32_bf16 v[6:9], v[162:165], v[246:249], v[6:9]
	v_mfma_f32_16x16x32_bf16 v[2:5], v[170:173], v[246:249], v[2:5]
	v_mfma_f32_16x16x32_bf16 v[54:57], v[166:169], v[182:185], v[54:57]
	v_mfma_f32_16x16x32_bf16 v[50:53], v[174:177], v[182:185], v[50:53]
	v_mfma_f32_16x16x32_bf16 v[38:41], v[166:169], v[224:227], v[38:41]
	v_mfma_f32_16x16x32_bf16 v[34:37], v[174:177], v[224:227], v[34:37]
	v_mfma_f32_16x16x32_bf16 v[22:25], v[166:169], v[242:245], v[22:25]
	v_mfma_f32_16x16x32_bf16 v[18:21], v[174:177], v[242:245], v[18:21]
	v_mfma_f32_16x16x32_bf16 v[6:9], v[166:169], v[250:253], v[6:9]
	v_mfma_f32_16x16x32_bf16 v[2:5], v[174:177], v[250:253], v[2:5]
	s_setprio 0
	s_barrier
	s_add_i32 s60, 0, 0x18000
	s_add_i32 s61, 0, 0x1c000
	v_add_u32_e32 v152, s60, v160
	v_add_u32_e32 v174, s61, v160
	ds_read_b128 v[130:133], v152
	ds_read_b128 v[134:137], v152 offset:1024
	ds_read_b128 v[148:151], v152 offset:2048
	ds_read_b128 v[152:155], v152 offset:3072
	ds_read_b128 v[162:165], v174
	ds_read_b128 v[166:169], v174 offset:1024
	ds_read_b128 v[170:173], v174 offset:2048
	ds_read_b128 v[174:177], v174 offset:3072
	s_add_u32 s34, s34, 0x40000
	s_addc_u32 s35, s35, 0
	s_mov_b32 m0, s53
	ds_read_b128 v[178:181], v161 offset:32768
	ds_read_b128 v[182:185], v161 offset:33792
	ds_read_b128 v[220:223], v161 offset:34816
	ds_read_b128 v[224:227], v161 offset:35840
	ds_read_b128 v[228:231], v161 offset:36864
	ds_read_b128 v[242:245], v161 offset:37888
	ds_read_b128 v[246:249], v161 offset:38912
	ds_read_b128 v[250:253], v161 offset:39936
	global_load_lds_dwordx4 v138, s[34:35]
	v_lshl_add_u64 v[234:235], s[34:35], 0, v[140:141]
	s_mov_b32 m0, s55
	s_nop 0
	global_load_lds_dwordx4 v[234:235], off
	s_waitcnt vmcnt(8)
	s_waitcnt lgkmcnt(0)
	s_barrier
	s_setprio 1
	s_waitcnt lgkmcnt(0)
	v_mfma_f32_16x16x32_bf16 v[126:129], v[130:133], v[178:181], v[126:129]
	v_mfma_f32_16x16x32_bf16 v[122:125], v[148:151], v[178:181], v[122:125]
	v_mfma_f32_16x16x32_bf16 v[110:113], v[130:133], v[220:223], v[110:113]
	v_mfma_f32_16x16x32_bf16 v[106:109], v[148:151], v[220:223], v[106:109]
	v_mfma_f32_16x16x32_bf16 v[94:97], v[130:133], v[228:231], v[94:97]
	v_mfma_f32_16x16x32_bf16 v[90:93], v[148:151], v[228:231], v[90:93]
	v_mfma_f32_16x16x32_bf16 v[78:81], v[130:133], v[246:249], v[78:81]
	v_mfma_f32_16x16x32_bf16 v[74:77], v[148:151], v[246:249], v[74:77]
	v_mfma_f32_16x16x32_bf16 v[126:129], v[134:137], v[182:185], v[126:129]
	v_mfma_f32_16x16x32_bf16 v[122:125], v[152:155], v[182:185], v[122:125]
	v_mfma_f32_16x16x32_bf16 v[110:113], v[134:137], v[224:227], v[110:113]
	v_mfma_f32_16x16x32_bf16 v[106:109], v[152:155], v[224:227], v[106:109]
	v_mfma_f32_16x16x32_bf16 v[94:97], v[134:137], v[242:245], v[94:97]
	v_mfma_f32_16x16x32_bf16 v[90:93], v[152:155], v[242:245], v[90:93]
	v_mfma_f32_16x16x32_bf16 v[78:81], v[134:137], v[250:253], v[78:81]
	v_mfma_f32_16x16x32_bf16 v[74:77], v[152:155], v[250:253], v[74:77]
	s_setprio 0
	s_setprio 1
	v_mfma_f32_16x16x32_bf16 v[118:121], v[162:165], v[178:181], v[118:121]
	v_mfma_f32_16x16x32_bf16 v[114:117], v[170:173], v[178:181], v[114:117]
	v_mfma_f32_16x16x32_bf16 v[102:105], v[162:165], v[220:223], v[102:105]
	v_mfma_f32_16x16x32_bf16 v[98:101], v[170:173], v[220:223], v[98:101]
	v_mfma_f32_16x16x32_bf16 v[86:89], v[162:165], v[228:231], v[86:89]
	v_mfma_f32_16x16x32_bf16 v[82:85], v[170:173], v[228:231], v[82:85]
	v_mfma_f32_16x16x32_bf16 v[70:73], v[162:165], v[246:249], v[70:73]
	v_mfma_f32_16x16x32_bf16 v[66:69], v[170:173], v[246:249], v[66:69]
	v_mfma_f32_16x16x32_bf16 v[118:121], v[166:169], v[182:185], v[118:121]
	v_mfma_f32_16x16x32_bf16 v[114:117], v[174:177], v[182:185], v[114:117]
	v_mfma_f32_16x16x32_bf16 v[102:105], v[166:169], v[224:227], v[102:105]
	v_mfma_f32_16x16x32_bf16 v[98:101], v[174:177], v[224:227], v[98:101]
	v_mfma_f32_16x16x32_bf16 v[86:89], v[166:169], v[242:245], v[86:89]
	v_mfma_f32_16x16x32_bf16 v[82:85], v[174:177], v[242:245], v[82:85]
	v_mfma_f32_16x16x32_bf16 v[70:73], v[166:169], v[250:253], v[70:73]
	v_mfma_f32_16x16x32_bf16 v[66:69], v[174:177], v[250:253], v[66:69]
	s_setprio 0
	s_barrier
; #define PG8_STAGE(bufoff, gbase, voff) do { _Pragma("unroll") for (int _i = 0; _i < 2; ++_i) \
;         __builtin_amdgcn_global_load_lds((const unsigned*)((const char*)(gbase) + (voff)[_i]), (PG8_LAS unsigned*)(lds + (bufoff) + ldsw + _i * 8192), 16, 0, 0); } while (0)
; #define PG8_LDA(dst, b, h) do { _Pragma("unroll") for (int m = 0; m < 4; ++m) _Pragma("unroll") for (int k = 0; k < 2; ++k) dst[m][k] = *(const PG8_LAS bf16x8*)(lds + PG8_SA(b, h) + aoff + m * 2048 + k * 1024); } while (0)
; #define PG8_MMA(ai, bj, At, Bt) do { __builtin_amdgcn_s_setprio(1); _Pragma("unroll") for (int m = 0; m < 4; ++m) _Pragma("unroll") for (int n = 0; n < 2; ++n) _Pragma("unroll") for (int k = 0; k < 2; ++k) \
;         acc[ai][bj][m][n] = __builtin_amdgcn_mfma_f32_16x16x32_bf16(Bt[n][k], At[m][k], acc[ai][bj][m][n], 0, 0, 0); __builtin_amdgcn_s_setprio(0); } while (0)
; #define PG8_WAIT_V(n) asm volatile("s_waitcnt vmcnt(" #n ")" ::: "memory")
; #define PG8_WAIT_L(n) asm volatile("s_waitcnt lgkmcnt(" #n ")" ::: "memory")
; #define PG8_BAR __builtin_amdgcn_s_barrier()
; #define PG8_SCHED __builtin_amdgcn_sched_barrier(0)
; template <class Epi, class Sched, bool ALIGN_EPI = false, bool SP2 = false>
; __device__ __forceinline__ void gemm_phase(PG8_LAS unsigned char* lds, const Gemm g, const Sched& S, const Epi& E, int wv) {
;     ...
;         for (int t = 0; t < nt; t += 2) {
;     ...
;             PG8_LDA(At, 1, 1); PG8_STAGE(PG8_SB(1, 0), b3, voffB); PG8_STAGE(PG8_SB(1, 1), b3 + hstepB, voffB); PG8_STAGE(PG8_SA(1, 0), a3, voffA);
;             PG8_WAIT_V(8); PG8_WAIT_L(0); PG8_BAR; PG8_MMA(1, 0, At, B0); PG8_MMA(1, 1, At, B1); PG8_BAR; PG8_SCHED;
	s_add_i32 s34, s60, s42
	v_lshl_add_u64 v[156:157], v[156:157], 0, s[62:63]
	s_mov_b32 m0, s34
	ds_read_b128 v[178:181], v161 offset:49152
	ds_read_b128 v[182:185], v161 offset:50176
	ds_read_b128 v[220:223], v161 offset:51200
	ds_read_b128 v[224:227], v161 offset:52224
	ds_read_b128 v[228:231], v161 offset:53248
	ds_read_b128 v[242:245], v161 offset:54272
	ds_read_b128 v[246:249], v161 offset:55296
	ds_read_b128 v[250:253], v161 offset:56320
	global_load_lds_dwordx4 v[156:157], off
	s_add_i32 m0, s34, 0x2000
	s_add_u32 s2, s2, 0x40080
	v_lshl_add_u64 v[156:157], v[186:187], 0, s[62:63]
	s_addc_u32 s3, s3, 0
	s_add_i32 s34, s61, s42
	global_load_lds_dwordx4 v[156:157], off
	s_mov_b32 m0, s34
	s_nop 0
	global_load_lds_dwordx4 v0, s[2:3]
	s_add_i32 m0, s34, 0x2000
	s_nop 0
	global_load_lds_dwordx4 v142, s[2:3]
	v_lshl_add_u64 v[156:157], v[196:197], 0, s[62:63]
	s_mov_b32 m0, s83
	s_nop 0
	global_load_lds_dwordx4 v[156:157], off
	v_lshl_add_u64 v[156:157], v[232:233], 0, s[62:63]
	s_mov_b32 m0, s87
	s_nop 0
	global_load_lds_dwordx4 v[156:157], off
	s_waitcnt vmcnt(8)
	s_waitcnt lgkmcnt(0)
	s_barrier
	s_setprio 1
	s_waitcnt lgkmcnt(0)
	v_mfma_f32_16x16x32_bf16 v[62:65], v[130:133], v[178:181], v[62:65]
	v_mfma_f32_16x16x32_bf16 v[58:61], v[148:151], v[178:181], v[58:61]
	v_mfma_f32_16x16x32_bf16 v[46:49], v[130:133], v[220:223], v[46:49]
	v_mfma_f32_16x16x32_bf16 v[42:45], v[148:151], v[220:223], v[42:45]
	v_mfma_f32_16x16x32_bf16 v[30:33], v[130:133], v[228:231], v[30:33]
	v_mfma_f32_16x16x32_bf16 v[26:29], v[148:151], v[228:231], v[26:29]
	v_mfma_f32_16x16x32_bf16 v[14:17], v[130:133], v[246:249], v[14:17]
	v_mfma_f32_16x16x32_bf16 v[10:13], v[148:151], v[246:249], v[10:13]
	v_mfma_f32_16x16x32_bf16 v[62:65], v[134:137], v[182:185], v[62:65]
	v_mfma_f32_16x16x32_bf16 v[58:61], v[152:155], v[182:185], v[58:61]
	v_mfma_f32_16x16x32_bf16 v[46:49], v[134:137], v[224:227], v[46:49]
	v_mfma_f32_16x16x32_bf16 v[42:45], v[152:155], v[224:227], v[42:45]
	v_mfma_f32_16x16x32_bf16 v[30:33], v[134:137], v[242:245], v[30:33]
	v_mfma_f32_16x16x32_bf16 v[26:29], v[152:155], v[242:245], v[26:29]
	v_mfma_f32_16x16x32_bf16 v[14:17], v[134:137], v[250:253], v[14:17]
	v_mfma_f32_16x16x32_bf16 v[10:13], v[152:155], v[250:253], v[10:13]
	s_setprio 0
	s_setprio 1
	v_mfma_f32_16x16x32_bf16 v[54:57], v[162:165], v[178:181], v[54:57]
	v_mfma_f32_16x16x32_bf16 v[50:53], v[170:173], v[178:181], v[50:53]
	v_mfma_f32_16x16x32_bf16 v[38:41], v[162:165], v[220:223], v[38:41]
	v_mfma_f32_16x16x32_bf16 v[34:37], v[170:173], v[220:223], v[34:37]
	v_mfma_f32_16x16x32_bf16 v[22:25], v[162:165], v[228:231], v[22:25]
	v_mfma_f32_16x16x32_bf16 v[18:21], v[170:173], v[228:231], v[18:21]
	v_mfma_f32_16x16x32_bf16 v[6:9], v[162:165], v[246:249], v[6:9]
	v_mfma_f32_16x16x32_bf16 v[2:5], v[170:173], v[246:249], v[2:5]
	v_mfma_f32_16x16x32_bf16 v[54:57], v[166:169], v[182:185], v[54:57]
	v_mfma_f32_16x16x32_bf16 v[50:53], v[174:177], v[182:185], v[50:53]
	v_mfma_f32_16x16x32_bf16 v[38:41], v[166:169], v[224:227], v[38:41]
	v_mfma_f32_16x16x32_bf16 v[34:37], v[174:177], v[224:227], v[34:37]
	v_mfma_f32_16x16x32_bf16 v[22:25], v[166:169], v[242:245], v[22:25]
	v_mfma_f32_16x16x32_bf16 v[18:21], v[174:177], v[242:245], v[18:21]
	v_mfma_f32_16x16x32_bf16 v[6:9], v[166:169], v[250:253], v[6:9]
	v_mfma_f32_16x16x32_bf16 v[2:5], v[174:177], v[250:253], v[2:5]
	s_setprio 0
	s_barrier
	s_add_i32 s97, s97, 2
	s_add_u32 s20, s20, 0x100
	s_addc_u32 s21, s21, 0
	s_add_u32 s94, s94, 0x100
	s_addc_u32 s95, s95, 0
	s_cmp_gt_u32 s97, 13
	s_cbranch_scc0 .LBB0_1743
	s_and_b64 vcc, exec, s[36:37]
	s_cbranch_vccz .LBB0_1746
	s_barrier

; #define PG8_STAGE(bufoff, gbase, voff) do { _Pragma("unroll") for (int _i = 0; _i < 2; ++_i) \
;         __builtin_amdgcn_global_load_lds((const unsigned*)((const char*)(gbase) + (voff)[_i]), (PG8_LAS unsigned*)(lds + (bufoff) + ldsw + _i * 8192), 16, 0, 0); } while (0)
; #define PG8_WAIT_V(n) asm volatile("s_waitcnt vmcnt(" #n ")" ::: "memory")
; #define PG8_BAR __builtin_amdgcn_s_barrier()
; template <class Epi, class Sched, bool ALIGN_EPI = false, bool SP2 = false>
; __device__ __forceinline__ void gemm_phase(PG8_LAS unsigned char* lds, const Gemm g, const Sched& S, const Epi& E, int wv) {
;     ...
;     for (int i = 0; i < 2; ++i) { int R, C; stage_rc(tid * 16 + i * 8192, R, C); const int Rb = Epi::PERM ? ((R & ~31) + perm32(R & 31)) : R;
;         voffA[i] = (unsigned)(R * g.lda + C) * 2u; voffB[i] = (unsigned)(Rb * K + C) * 2u; }
;     const size_t kstep = (size_t)(BK * 2);
;     const size_t hstepA = (size_t)HALF * g.lda * 2, hstepB = (size_t)HALF * K * 2;
;     const size_t tstepA = 2 * hstepA, tstepB = 2 * hstepB;
;     const unsigned ldsw = (unsigned)wid * 1024u;
;     const int aoff = lds_byte(wr * 64 + fr, fq * 8), boff = lds_byte(wc * 32 + fr, fq * 8);
;     ...
;         PG8_STAGE(PG8_SB(0, 0), cB, voffB); PG8_STAGE(PG8_SB(0, 1), cB + hstepB, voffB); PG8_STAGE(PG8_SA(0, 0), cA, voffA); PG8_STAGE(PG8_SA(0, 1), cA + hstepA, voffA);
;         if (wr == 1) PG8_BAR;
;         PG8_WAIT_V(2); PG8_BAR;
;         PG8_STAGE(PG8_SB(1, 0), cB + kstep, voffB); PG8_STAGE(PG8_SA(1, 0), cA + kstep, voffA); PG8_STAGE(PG8_SB(1, 1), cB + hstepB + kstep, voffB);
;         PG8_WAIT_V(6); PG8_BAR;
.LBB0_1887:
	s_add_u32 s20, s16, 0x6800000
	s_addc_u32 s21, s17, 0
	s_add_u32 s22, s16, 0x1e800000
	s_addc_u32 s23, s17, 0
	s_add_u32 s24, s16, 0x1ac0000
	s_addc_u32 s25, s17, 0
	s_add_u32 s26, s16, 0x1ac8000
	s_addc_u32 s27, s17, 0
	s_lshl_b32 s15, s15, 5
	s_and_b32 s82, s15, 0x60
	s_add_i32 m0, s35, 0x18000
	v_lshl_add_u64 v[8:9], v[8:9], 0, s[62:63]
	s_lshl_b32 s58, s36, 6
	s_lshl_b32 s36, s36, 13
	s_lshl_b32 s37, s82, 7
	s_waitcnt vmcnt(2)
	s_barrier
	global_load_lds_dwordx4 v[8:9], off
	v_lshl_add_u64 v[6:7], v[6:7], 0, s[62:63]
	s_add_i32 m0, s35, 0x1a000
	s_add_i32 s83, s35, 0x8000
	s_add_i32 s87, s35, 0xa000
	global_load_lds_dwordx4 v[6:7], off
	v_lshl_add_u64 v[2:3], v[2:3], 0, s[62:63]
	s_mov_b32 m0, s83
	s_add_u32 s16, s2, 0x40080
	global_load_lds_dwordx4 v[2:3], off
	v_lshl_add_u64 v[2:3], v[4:5], 0, s[62:63]
	s_mov_b32 m0, s87
	s_addc_u32 s17, s3, 0
	global_load_lds_dwordx4 v[2:3], off
	s_add_i32 m0, s35, 0x1c000
	s_nop 0
	global_load_lds_dwordx4 v0, s[16:17]
	v_lshl_add_u64 v[2:3], s[16:17], 0, v[162:163]
	s_add_i32 m0, s35, 0x1e000
	v_bfe_u32 v179, v10, 4, 2
	global_load_lds_dwordx4 v[2:3], off
	v_and_b32_e32 v178, 15, v10
	v_lshlrev_b32_e32 v2, 4, v179
	v_lshlrev_b32_e32 v3, 2, v10
	v_lshl_or_b32 v2, v178, 6, v2
	v_and_b32_e32 v3, 32, v3
	v_bitop3_b32 v4, v2, s36, v3 bitop3:0xde
	v_bitop3_b32 v180, s37, v2, v3 bitop3:0xf6
	v_lshlrev_b32_e32 v2, 14, v15
	v_and_b32_e32 v2, 0xffff8000, v2
	v_lshl_add_u32 v2, v14, 11, v2
	v_and_b32_e32 v3, 1, v15
	v_lshl_or_b32 v2, v3, 6, v2
	v_lshl_add_u32 v168, v16, 1, v2
	v_lshlrev_b32_e32 v2, 14, v11
	v_and_b32_e32 v2, 0xffff8000, v2
	s_waitcnt vmcnt(6)
	v_lshl_add_u32 v2, v12, 11, v2
	v_and_b32_e32 v3, 1, v11
	s_cmpk_lt_u32 s29, 0x100
	v_lshl_or_b32 v2, v3, 6, v2
	s_sext_i32_i16 s15, s28
	s_cselect_b64 s[28:29], -1, 0
	s_ashr_i32 s90, s12, 31
	v_mov_b32_e32 v169, v1
	v_lshl_add_u32 v170, v13, 1, v2
	v_mov_b32_e32 v171, v1
	s_mov_b32 s91, 0
	v_add_u32_e32 v181, 0, v4
	s_barrier
	s_branch .LBB0_1890

; #define PG8_STAGE(bufoff, gbase, voff) do { _Pragma("unroll") for (int _i = 0; _i < 2; ++_i) \
;         __builtin_amdgcn_global_load_lds((const unsigned*)((const char*)(gbase) + (voff)[_i]), (PG8_LAS unsigned*)(lds + (bufoff) + ldsw + _i * 8192), 16, 0, 0); } while (0)
; #define PG8_LDA(dst, b, h) do { _Pragma("unroll") for (int m = 0; m < 4; ++m) _Pragma("unroll") for (int k = 0; k < 2; ++k) dst[m][k] = *(const PG8_LAS bf16x8*)(lds + PG8_SA(b, h) + aoff + m * 2048 + k * 1024); } while (0)
; #define PG8_LDB(dst, b, h) do { _Pragma("unroll") for (int n = 0; n < 2; ++n) _Pragma("unroll") for (int k = 0; k < 2; ++k) dst[n][k] = *(const PG8_LAS bf16x8*)(lds + PG8_SB(b, h) + boff + n * 2048 + k * 1024); } while (0)
; #define PG8_MMA(ai, bj, At, Bt) do { __builtin_amdgcn_s_setprio(1); _Pragma("unroll") for (int m = 0; m < 4; ++m) _Pragma("unroll") for (int n = 0; n < 2; ++n) _Pragma("unroll") for (int k = 0; k < 2; ++k) \
;         acc[ai][bj][m][n] = __builtin_amdgcn_mfma_f32_16x16x32_bf16(Bt[n][k], At[m][k], acc[ai][bj][m][n], 0, 0, 0); __builtin_amdgcn_s_setprio(0); } while (0)
; template <class Epi, class Sched, bool ALIGN_EPI = false, bool SP2 = false>
; __device__ __forceinline__ void gemm_phase(PG8_LAS unsigned char* lds, const Gemm g, const Sched& S, const Epi& E, int wv) {
;     ...
;         const bool has_next = S.next(ui + 1, nxt);
;         const char* nA = has_next ? (const char*)g.A + (size_t)nxt.pm * tstepA : cA; const char* nB = has_next ? (const char*)g.Bt + (size_t)nxt.pn * tstepB : cB;
; #pragma unroll 1
;         for (int t = 0; t < nt; t += 2) {
;             const bool last = (t == nt - 2);
;             const char* a1 = cA + (size_t)(t + 1) * kstep;
;             const char* a2 = last ? nA : cA + (size_t)(t + 2) * kstep; const char* b2 = last ? nB : cB + (size_t)(t + 2) * kstep;
;             const char* a3 = a2 + kstep; const char* b3 = b2 + kstep;
;             if (last && has_next) S.a_ready(nxt);
;             if constexpr (SP2) {
;             PG8_LDB(B0, 0, 0); PG8_LDB(B1, 0, 1); PG8_SCHED; PG8_LDA(At, 0, 0); PG8_STAGE(PG8_SA(1, 1), a1 + hstepA, voffA);
;             PG8_WAIT_V(8); PG8_WAIT_L(0); PG8_BAR; PG8_MMA(0, 0, At, B0); PG8_MMA(0, 1, At, B1); PG8_BAR; PG8_SCHED;
;             PG8_LDA(At, 0, 1); PG8_STAGE(PG8_SB(0, 0), b2, voffB); PG8_STAGE(PG8_SB(0, 1), b2 + hstepB, voffB); PG8_STAGE(PG8_SA(0, 0), a2, voffA);
.LBB0_1893:
	s_add_u32 s2, s40, 0xfffc0080
	s_addc_u32 s3, s41, -1
	s_add_i32 s60, 0, 0x10000
	s_cmp_eq_u32 s96, 12
	s_cselect_b32 s43, s39, s3
	s_cselect_b32 s42, s92, s2
	s_cselect_b32 s3, s37, s95
	s_cselect_b32 s2, s93, s94
	s_add_i32 s61, 0, 0x14000
	v_add_u32_e32 v46, s60, v180
	v_add_u32_e32 v62, s61, v180
	ds_read_b128 v[34:37], v46
	ds_read_b128 v[38:41], v46 offset:1024
	ds_read_b128 v[42:45], v46 offset:2048
	ds_read_b128 v[46:49], v46 offset:3072
	ds_read_b128 v[50:53], v62
	ds_read_b128 v[54:57], v62 offset:1024
	ds_read_b128 v[58:61], v62 offset:2048
	ds_read_b128 v[62:65], v62 offset:3072
	s_add_i32 m0, s35, 0xc000
	ds_read_b128 v[172:175], v181
	ds_read_b128 v[182:185], v181 offset:1024
	ds_read_b128 v[220:223], v181 offset:2048
	ds_read_b128 v[224:227], v181 offset:3072
	ds_read_b128 v[228:231], v181 offset:4096
	ds_read_b128 v[242:245], v181 offset:5120
	ds_read_b128 v[246:249], v181 offset:6144
	ds_read_b128 v[250:253], v181 offset:7168
	global_load_lds_dwordx4 v168, s[40:41]
	s_add_i32 m0, s35, 0xe000
	s_nop 0
	global_load_lds_dwordx4 v170, s[40:41]
	s_waitcnt vmcnt(8)
	s_waitcnt lgkmcnt(0)
	s_barrier
	s_setprio 1
	s_waitcnt lgkmcnt(0)
	v_mfma_f32_16x16x32_bf16 v[158:161], v[34:37], v[172:175], v[158:161]
	v_mfma_f32_16x16x32_bf16 v[154:157], v[42:45], v[172:175], v[154:157]
	v_mfma_f32_16x16x32_bf16 v[142:145], v[34:37], v[220:223], v[142:145]
	v_mfma_f32_16x16x32_bf16 v[138:141], v[42:45], v[220:223], v[138:141]
	v_mfma_f32_16x16x32_bf16 v[126:129], v[34:37], v[228:231], v[126:129]
	v_mfma_f32_16x16x32_bf16 v[122:125], v[42:45], v[228:231], v[122:125]
	v_mfma_f32_16x16x32_bf16 v[110:113], v[34:37], v[246:249], v[110:113]
	v_mfma_f32_16x16x32_bf16 v[106:109], v[42:45], v[246:249], v[106:109]
	v_mfma_f32_16x16x32_bf16 v[158:161], v[38:41], v[182:185], v[158:161]
	v_mfma_f32_16x16x32_bf16 v[154:157], v[46:49], v[182:185], v[154:157]
	v_mfma_f32_16x16x32_bf16 v[142:145], v[38:41], v[224:227], v[142:145]
	v_mfma_f32_16x16x32_bf16 v[138:141], v[46:49], v[224:227], v[138:141]
	v_mfma_f32_16x16x32_bf16 v[126:129], v[38:41], v[242:245], v[126:129]
	v_mfma_f32_16x16x32_bf16 v[122:125], v[46:49], v[242:245], v[122:125]
	v_mfma_f32_16x16x32_bf16 v[110:113], v[38:41], v[250:253], v[110:113]
	v_mfma_f32_16x16x32_bf16 v[106:109], v[46:49], v[250:253], v[106:109]
	s_setprio 0
	s_setprio 1
	v_mfma_f32_16x16x32_bf16 v[150:153], v[50:53], v[172:175], v[150:153]
	v_mfma_f32_16x16x32_bf16 v[146:149], v[58:61], v[172:175], v[146:149]
	v_mfma_f32_16x16x32_bf16 v[134:137], v[50:53], v[220:223], v[134:137]
	v_mfma_f32_16x16x32_bf16 v[130:133], v[58:61], v[220:223], v[130:133]
	v_mfma_f32_16x16x32_bf16 v[118:121], v[50:53], v[228:231], v[118:121]
	v_mfma_f32_16x16x32_bf16 v[114:117], v[58:61], v[228:231], v[114:117]
	v_mfma_f32_16x16x32_bf16 v[102:105], v[50:53], v[246:249], v[102:105]
	v_mfma_f32_16x16x32_bf16 v[98:101], v[58:61], v[246:249], v[98:101]
	v_mfma_f32_16x16x32_bf16 v[150:153], v[54:57], v[182:185], v[150:153]
	v_mfma_f32_16x16x32_bf16 v[146:149], v[62:65], v[182:185], v[146:149]
	v_mfma_f32_16x16x32_bf16 v[134:137], v[54:57], v[224:227], v[134:137]
	v_mfma_f32_16x16x32_bf16 v[130:133], v[62:65], v[224:227], v[130:133]
	v_mfma_f32_16x16x32_bf16 v[118:121], v[54:57], v[242:245], v[118:121]
	v_mfma_f32_16x16x32_bf16 v[114:117], v[62:65], v[242:245], v[114:117]
	v_mfma_f32_16x16x32_bf16 v[102:105], v[54:57], v[250:253], v[102:105]
	v_mfma_f32_16x16x32_bf16 v[98:101], v[62:65], v[250:253], v[98:101]
	s_setprio 0
	s_barrier
	s_add_i32 s60, s60, s50
	v_lshl_add_u64 v[176:177], s[2:3], 0, v[0:1]
	s_mov_b32 m0, s60
	ds_read_b128 v[172:175], v181 offset:16384
	ds_read_b128 v[182:185], v181 offset:17408
	ds_read_b128 v[220:223], v181 offset:18432
	ds_read_b128 v[224:227], v181 offset:19456
	ds_read_b128 v[228:231], v181 offset:20480
	ds_read_b128 v[242:245], v181 offset:21504
	ds_read_b128 v[246:249], v181 offset:22528
	ds_read_b128 v[250:253], v181 offset:23552
	global_load_lds_dwordx4 v[176:177], off
	s_add_i32 m0, s60, 0x2000
	s_add_u32 vcc_lo, s2, 0x40000
	v_lshl_add_u64 v[186:187], s[2:3], 0, v[162:163]
	s_addc_u32 vcc_hi, s3, 0
	s_add_i32 s60, s61, s50
	global_load_lds_dwordx4 v[186:187], off
	v_lshl_add_u64 v[196:197], vcc, 0, v[0:1]
	s_mov_b32 m0, s60
	v_lshl_add_u64 v[240:241], s[42:43], 0, v[164:165]
	global_load_lds_dwordx4 v[196:197], off
	v_lshl_add_u64 v[196:197], vcc, 0, v[162:163]
	s_add_i32 m0, s60, 0x2000
	s_nop 0
	global_load_lds_dwordx4 v[196:197], off
	v_lshl_add_u64 v[196:197], s[42:43], 0, v[166:167]
	s_mov_b32 m0, s35
	s_nop 0
	global_load_lds_dwordx4 v[196:197], off
	s_mov_b32 m0, s52
	s_nop 0
	global_load_lds_dwordx4 v[240:241], off
	s_waitcnt vmcnt(8)
	s_waitcnt lgkmcnt(0)
	s_barrier
; #define PG8_STAGE(bufoff, gbase, voff) do { _Pragma("unroll") for (int _i = 0; _i < 2; ++_i) \
;         __builtin_amdgcn_global_load_lds((const unsigned*)((const char*)(gbase) + (voff)[_i]), (PG8_LAS unsigned*)(lds + (bufoff) + ldsw + _i * 8192), 16, 0, 0); } while (0)
; #define PG8_LDA(dst, b, h) do { _Pragma("unroll") for (int m = 0; m < 4; ++m) _Pragma("unroll") for (int k = 0; k < 2; ++k) dst[m][k] = *(const PG8_LAS bf16x8*)(lds + PG8_SA(b, h) + aoff + m * 2048 + k * 1024); } while (0)
; #define PG8_LDB(dst, b, h) do { _Pragma("unroll") for (int n = 0; n < 2; ++n) _Pragma("unroll") for (int k = 0; k < 2; ++k) dst[n][k] = *(const PG8_LAS bf16x8*)(lds + PG8_SB(b, h) + boff + n * 2048 + k * 1024); } while (0)
; #define PG8_MMA(ai, bj, At, Bt) do { __builtin_amdgcn_s_setprio(1); _Pragma("unroll") for (int m = 0; m < 4; ++m) _Pragma("unroll") for (int n = 0; n < 2; ++n) _Pragma("unroll") for (int k = 0; k < 2; ++k) \
;         acc[ai][bj][m][n] = __builtin_amdgcn_mfma_f32_16x16x32_bf16(Bt[n][k], At[m][k], acc[ai][bj][m][n], 0, 0, 0); __builtin_amdgcn_s_setprio(0); } while (0)
; #define PG8_WAIT_V(n) asm volatile("s_waitcnt vmcnt(" #n ")" ::: "memory")
; #define PG8_WAIT_L(n) asm volatile("s_waitcnt lgkmcnt(" #n ")" ::: "memory")
; #define PG8_BAR __builtin_amdgcn_s_barrier()
; #define PG8_SCHED __builtin_amdgcn_sched_barrier(0)
; template <class Epi, class Sched, bool ALIGN_EPI = false, bool SP2 = false>
; __device__ __forceinline__ void gemm_phase(PG8_LAS unsigned char* lds, const Gemm g, const Sched& S, const Epi& E, int wv) {
;     ...
;             PG8_WAIT_V(8); PG8_WAIT_L(0); PG8_BAR; PG8_MMA(1, 0, At, B0); PG8_MMA(1, 1, At, B1); PG8_BAR; PG8_SCHED;
;             PG8_LDB(B0, 1, 0); PG8_LDB(B1, 1, 1); PG8_SCHED; PG8_LDA(At, 1, 0); PG8_STAGE(PG8_SA(0, 1), a2 + hstepA, voffA);
;             PG8_WAIT_V(8); PG8_WAIT_L(0); PG8_BAR; PG8_MMA(0, 0, At, B0); PG8_MMA(0, 1, At, B1); PG8_BAR; PG8_SCHED;
	s_setprio 1
	s_waitcnt lgkmcnt(0)
	v_mfma_f32_16x16x32_bf16 v[94:97], v[34:37], v[172:175], v[94:97]
	v_mfma_f32_16x16x32_bf16 v[90:93], v[42:45], v[172:175], v[90:93]
	v_mfma_f32_16x16x32_bf16 v[78:81], v[34:37], v[220:223], v[78:81]
	v_mfma_f32_16x16x32_bf16 v[74:77], v[42:45], v[220:223], v[74:77]
	v_mfma_f32_16x16x32_bf16 v[30:33], v[34:37], v[228:231], v[30:33]
	v_mfma_f32_16x16x32_bf16 v[26:29], v[42:45], v[228:231], v[26:29]
	v_mfma_f32_16x16x32_bf16 v[14:17], v[34:37], v[246:249], v[14:17]
	v_mfma_f32_16x16x32_bf16 v[10:13], v[42:45], v[246:249], v[10:13]
	v_mfma_f32_16x16x32_bf16 v[94:97], v[38:41], v[182:185], v[94:97]
	v_mfma_f32_16x16x32_bf16 v[90:93], v[46:49], v[182:185], v[90:93]
	v_mfma_f32_16x16x32_bf16 v[78:81], v[38:41], v[224:227], v[78:81]
	v_mfma_f32_16x16x32_bf16 v[74:77], v[46:49], v[224:227], v[74:77]
	v_mfma_f32_16x16x32_bf16 v[30:33], v[38:41], v[242:245], v[30:33]
	v_mfma_f32_16x16x32_bf16 v[26:29], v[46:49], v[242:245], v[26:29]
	v_mfma_f32_16x16x32_bf16 v[14:17], v[38:41], v[250:253], v[14:17]
	v_mfma_f32_16x16x32_bf16 v[10:13], v[46:49], v[250:253], v[10:13]
	s_setprio 0
	s_setprio 1
	v_mfma_f32_16x16x32_bf16 v[22:25], v[50:53], v[228:231], v[22:25]
	v_mfma_f32_16x16x32_bf16 v[18:21], v[58:61], v[228:231], v[18:21]
	v_mfma_f32_16x16x32_bf16 v[6:9], v[50:53], v[246:249], v[6:9]
	v_mfma_f32_16x16x32_bf16 v[2:5], v[58:61], v[246:249], v[2:5]
	v_mfma_f32_16x16x32_bf16 v[34:37], v[50:53], v[172:175], v[86:89]
	v_mfma_f32_16x16x32_bf16 v[38:41], v[58:61], v[172:175], v[82:85]
	v_mfma_f32_16x16x32_bf16 v[42:45], v[50:53], v[220:223], v[70:73]
	v_mfma_f32_16x16x32_bf16 v[46:49], v[58:61], v[220:223], v[66:69]
	v_mfma_f32_16x16x32_bf16 v[22:25], v[54:57], v[242:245], v[22:25]
	v_mfma_f32_16x16x32_bf16 v[18:21], v[62:65], v[242:245], v[18:21]
	v_mfma_f32_16x16x32_bf16 v[6:9], v[54:57], v[250:253], v[6:9]
	v_mfma_f32_16x16x32_bf16 v[2:5], v[62:65], v[250:253], v[2:5]
	v_mfma_f32_16x16x32_bf16 v[34:37], v[54:57], v[182:185], v[34:37]
	v_mfma_f32_16x16x32_bf16 v[38:41], v[62:65], v[182:185], v[38:41]
	v_mfma_f32_16x16x32_bf16 v[42:45], v[54:57], v[224:227], v[42:45]
	v_mfma_f32_16x16x32_bf16 v[46:49], v[62:65], v[224:227], v[46:49]
	s_setprio 0
	s_barrier
	s_add_i32 s60, 0, 0x18000
	s_add_i32 s61, 0, 0x1c000
	v_add_u32_e32 v62, s60, v180
	v_add_u32_e32 v66, s61, v180
	ds_read_b128 v[50:53], v62
	ds_read_b128 v[54:57], v62 offset:1024
	ds_read_b128 v[58:61], v62 offset:2048
	ds_read_b128 v[62:65], v62 offset:3072
	ds_read_b128 v[172:175], v66
	ds_read_b128 v[182:185], v66 offset:1024
	ds_read_b128 v[220:223], v66 offset:2048
	ds_read_b128 v[224:227], v66 offset:3072
	s_add_u32 s42, s42, 0x40000
	s_addc_u32 s43, s43, 0
	s_mov_b32 m0, s53
	ds_read_b128 v[66:69], v181 offset:32768
	ds_read_b128 v[70:73], v181 offset:33792
	ds_read_b128 v[82:85], v181 offset:34816
	ds_read_b128 v[86:89], v181 offset:35840
	ds_read_b128 v[228:231], v181 offset:36864
	ds_read_b128 v[242:245], v181 offset:37888
	ds_read_b128 v[246:249], v181 offset:38912
	ds_read_b128 v[250:253], v181 offset:39936
	global_load_lds_dwordx4 v166, s[42:43]
	s_mov_b32 m0, s55
	s_nop 0
	global_load_lds_dwordx4 v164, s[42:43]
	s_waitcnt vmcnt(8)
	s_waitcnt lgkmcnt(0)
	s_barrier
	s_setprio 1
	s_waitcnt lgkmcnt(0)
	v_mfma_f32_16x16x32_bf16 v[158:161], v[50:53], v[66:69], v[158:161]
	v_mfma_f32_16x16x32_bf16 v[154:157], v[58:61], v[66:69], v[154:157]
	v_mfma_f32_16x16x32_bf16 v[142:145], v[50:53], v[82:85], v[142:145]
	v_mfma_f32_16x16x32_bf16 v[138:141], v[58:61], v[82:85], v[138:141]
	v_mfma_f32_16x16x32_bf16 v[126:129], v[50:53], v[228:231], v[126:129]
	v_mfma_f32_16x16x32_bf16 v[122:125], v[58:61], v[228:231], v[122:125]
	v_mfma_f32_16x16x32_bf16 v[110:113], v[50:53], v[246:249], v[110:113]
	v_mfma_f32_16x16x32_bf16 v[106:109], v[58:61], v[246:249], v[106:109]
	v_mfma_f32_16x16x32_bf16 v[158:161], v[54:57], v[70:73], v[158:161]
	v_mfma_f32_16x16x32_bf16 v[154:157], v[62:65], v[70:73], v[154:157]
	v_mfma_f32_16x16x32_bf16 v[142:145], v[54:57], v[86:89], v[142:145]
	v_mfma_f32_16x16x32_bf16 v[138:141], v[62:65], v[86:89], v[138:141]
	v_mfma_f32_16x16x32_bf16 v[126:129], v[54:57], v[242:245], v[126:129]
	v_mfma_f32_16x16x32_bf16 v[122:125], v[62:65], v[242:245], v[122:125]
	v_mfma_f32_16x16x32_bf16 v[110:113], v[54:57], v[250:253], v[110:113]
	v_mfma_f32_16x16x32_bf16 v[106:109], v[62:65], v[250:253], v[106:109]
	s_setprio 0
	s_setprio 1
	v_mfma_f32_16x16x32_bf16 v[150:153], v[172:175], v[66:69], v[150:153]
	v_mfma_f32_16x16x32_bf16 v[66:69], v[220:223], v[66:69], v[146:149]
	v_mfma_f32_16x16x32_bf16 v[146:149], v[224:227], v[70:73], v[66:69]
	v_mfma_f32_16x16x32_bf16 v[66:69], v[172:175], v[82:85], v[134:137]
	v_mfma_f32_16x16x32_bf16 v[134:137], v[182:185], v[86:89], v[66:69]
	v_mfma_f32_16x16x32_bf16 v[66:69], v[220:223], v[82:85], v[130:133]
	v_mfma_f32_16x16x32_bf16 v[130:133], v[224:227], v[86:89], v[66:69]
	v_mfma_f32_16x16x32_bf16 v[66:69], v[172:175], v[228:231], v[118:121]
	v_mfma_f32_16x16x32_bf16 v[118:121], v[182:185], v[242:245], v[66:69]
	v_mfma_f32_16x16x32_bf16 v[66:69], v[220:223], v[228:231], v[114:117]
	v_mfma_f32_16x16x32_bf16 v[114:117], v[224:227], v[242:245], v[66:69]
	v_mfma_f32_16x16x32_bf16 v[66:69], v[172:175], v[246:249], v[102:105]
	v_mfma_f32_16x16x32_bf16 v[102:105], v[182:185], v[250:253], v[66:69]
	v_mfma_f32_16x16x32_bf16 v[66:69], v[220:223], v[246:249], v[98:101]
	v_mfma_f32_16x16x32_bf16 v[150:153], v[182:185], v[70:73], v[150:153]
	v_mfma_f32_16x16x32_bf16 v[98:101], v[224:227], v[250:253], v[66:69]
	s_setprio 0
	s_barrier
; #define PG8_STAGE(bufoff, gbase, voff) do { _Pragma("unroll") for (int _i = 0; _i < 2; ++_i) \
;         __builtin_amdgcn_global_load_lds((const unsigned*)((const char*)(gbase) + (voff)[_i]), (PG8_LAS unsigned*)(lds + (bufoff) + ldsw + _i * 8192), 16, 0, 0); } while (0)
; #define PG8_LDA(dst, b, h) do { _Pragma("unroll") for (int m = 0; m < 4; ++m) _Pragma("unroll") for (int k = 0; k < 2; ++k) dst[m][k] = *(const PG8_LAS bf16x8*)(lds + PG8_SA(b, h) + aoff + m * 2048 + k * 1024); } while (0)
; #define PG8_MMA(ai, bj, At, Bt) do { __builtin_amdgcn_s_setprio(1); _Pragma("unroll") for (int m = 0; m < 4; ++m) _Pragma("unroll") for (int n = 0; n < 2; ++n) _Pragma("unroll") for (int k = 0; k < 2; ++k) \
;         acc[ai][bj][m][n] = __builtin_amdgcn_mfma_f32_16x16x32_bf16(Bt[n][k], At[m][k], acc[ai][bj][m][n], 0, 0, 0); __builtin_amdgcn_s_setprio(0); } while (0)
; #define PG8_WAIT_V(n) asm volatile("s_waitcnt vmcnt(" #n ")" ::: "memory")
; #define PG8_WAIT_L(n) asm volatile("s_waitcnt lgkmcnt(" #n ")" ::: "memory")
; #define PG8_BAR __builtin_amdgcn_s_barrier()
; #define PG8_SCHED __builtin_amdgcn_sched_barrier(0)
; template <class Epi, class Sched, bool ALIGN_EPI = false, bool SP2 = false>
; __device__ __forceinline__ void gemm_phase(PG8_LAS unsigned char* lds, const Gemm g, const Sched& S, const Epi& E, int wv) {
;     ...
;         for (int t = 0; t < nt; t += 2) {
;     ...
;             PG8_LDA(At, 1, 1); PG8_STAGE(PG8_SB(1, 0), b3, voffB); PG8_STAGE(PG8_SB(1, 1), b3 + hstepB, voffB); PG8_STAGE(PG8_SA(1, 0), a3, voffA);
;             PG8_WAIT_V(8); PG8_WAIT_L(0); PG8_BAR; PG8_MMA(1, 0, At, B0); PG8_MMA(1, 1, At, B1); PG8_BAR; PG8_SCHED;
	s_add_i32 s42, s60, s50
	v_lshl_add_u64 v[82:83], v[176:177], 0, s[62:63]
	s_mov_b32 m0, s42
	s_nop 0
	ds_read_b128 v[66:69], v181 offset:49152
	ds_read_b128 v[70:73], v181 offset:50176
	ds_read_b128 v[228:231], v181 offset:51200
	ds_read_b128 v[242:245], v181 offset:52224
	ds_read_b128 v[246:249], v181 offset:53248
	ds_read_b128 v[250:253], v181 offset:54272
	ds_read_b128 v[232:235], v181 offset:55296
	ds_read_b128 v[236:239], v181 offset:56320
	global_load_lds_dwordx4 v[82:83], off
	s_add_i32 m0, s42, 0x2000
	s_add_u32 s2, s2, 0x40080
	v_lshl_add_u64 v[82:83], v[186:187], 0, s[62:63]
	s_addc_u32 s3, s3, 0
	s_add_i32 s42, s61, s50
	global_load_lds_dwordx4 v[82:83], off
	s_mov_b32 m0, s42
	s_nop 0
	global_load_lds_dwordx4 v0, s[2:3]
	s_add_i32 m0, s42, 0x2000
	s_nop 0
	global_load_lds_dwordx4 v162, s[2:3]
	v_lshl_add_u64 v[82:83], v[196:197], 0, s[62:63]
	s_mov_b32 m0, s83
	s_nop 0
	global_load_lds_dwordx4 v[82:83], off
	v_lshl_add_u64 v[82:83], v[240:241], 0, s[62:63]
	s_mov_b32 m0, s87
	s_nop 0
	global_load_lds_dwordx4 v[82:83], off
	s_waitcnt vmcnt(8)
	s_waitcnt lgkmcnt(0)
	s_barrier
	s_setprio 1
	s_waitcnt lgkmcnt(0)
	v_mfma_f32_16x16x32_bf16 v[82:85], v[50:53], v[66:69], v[94:97]
	v_mfma_f32_16x16x32_bf16 v[94:97], v[54:57], v[70:73], v[82:85]
	v_mfma_f32_16x16x32_bf16 v[82:85], v[58:61], v[66:69], v[90:93]
	v_mfma_f32_16x16x32_bf16 v[78:81], v[50:53], v[228:231], v[78:81]
	v_mfma_f32_16x16x32_bf16 v[74:77], v[58:61], v[228:231], v[74:77]
	v_mfma_f32_16x16x32_bf16 v[30:33], v[50:53], v[246:249], v[30:33]
	v_mfma_f32_16x16x32_bf16 v[26:29], v[58:61], v[246:249], v[26:29]
	v_mfma_f32_16x16x32_bf16 v[14:17], v[50:53], v[232:235], v[14:17]
	v_mfma_f32_16x16x32_bf16 v[10:13], v[58:61], v[232:235], v[10:13]
	v_mfma_f32_16x16x32_bf16 v[90:93], v[62:65], v[70:73], v[82:85]
	v_mfma_f32_16x16x32_bf16 v[78:81], v[54:57], v[242:245], v[78:81]
	v_mfma_f32_16x16x32_bf16 v[74:77], v[62:65], v[242:245], v[74:77]
	v_mfma_f32_16x16x32_bf16 v[30:33], v[54:57], v[250:253], v[30:33]
	v_mfma_f32_16x16x32_bf16 v[26:29], v[62:65], v[250:253], v[26:29]
	v_mfma_f32_16x16x32_bf16 v[14:17], v[54:57], v[236:239], v[14:17]
	v_mfma_f32_16x16x32_bf16 v[10:13], v[62:65], v[236:239], v[10:13]
	s_setprio 0
	s_setprio 1
	v_mfma_f32_16x16x32_bf16 v[34:37], v[172:175], v[66:69], v[34:37]
	v_mfma_f32_16x16x32_bf16 v[86:89], v[182:185], v[70:73], v[34:37]
	v_mfma_f32_16x16x32_bf16 v[34:37], v[220:223], v[66:69], v[38:41]
	v_mfma_f32_16x16x32_bf16 v[82:85], v[224:227], v[70:73], v[34:37]
	v_mfma_f32_16x16x32_bf16 v[34:37], v[172:175], v[228:231], v[42:45]
	v_mfma_f32_16x16x32_bf16 v[70:73], v[182:185], v[242:245], v[34:37]
	v_mfma_f32_16x16x32_bf16 v[34:37], v[220:223], v[228:231], v[46:49]
	v_mfma_f32_16x16x32_bf16 v[22:25], v[172:175], v[246:249], v[22:25]
	v_mfma_f32_16x16x32_bf16 v[18:21], v[220:223], v[246:249], v[18:21]
	v_mfma_f32_16x16x32_bf16 v[6:9], v[172:175], v[232:235], v[6:9]
	v_mfma_f32_16x16x32_bf16 v[2:5], v[220:223], v[232:235], v[2:5]
	v_mfma_f32_16x16x32_bf16 v[66:69], v[224:227], v[242:245], v[34:37]
	v_mfma_f32_16x16x32_bf16 v[22:25], v[182:185], v[250:253], v[22:25]
	v_mfma_f32_16x16x32_bf16 v[18:21], v[224:227], v[250:253], v[18:21]
	v_mfma_f32_16x16x32_bf16 v[6:9], v[182:185], v[236:239], v[6:9]
	v_mfma_f32_16x16x32_bf16 v[2:5], v[224:227], v[236:239], v[2:5]
	s_setprio 0
	s_barrier
	s_add_i32 s96, s96, 2
	s_add_u32 s40, s40, 0x100
	s_addc_u32 s41, s41, 0
	s_add_u32 s94, s94, 0x100
	s_addc_u32 s95, s95, 0
	s_cmp_gt_u32 s96, 13
	s_cbranch_scc0 .LBB0_1893
	s_and_b64 vcc, exec, s[28:29]
	s_cbranch_vccz .LBB0_1896
	s_barrier

; #define PG8_STAGE(bufoff, gbase, voff) do { _Pragma("unroll") for (int _i = 0; _i < 2; ++_i) \
;         __builtin_amdgcn_global_load_lds((const unsigned*)((const char*)(gbase) + (voff)[_i]), (PG8_LAS unsigned*)(lds + (bufoff) + ldsw + _i * 8192), 16, 0, 0); } while (0)
; #define PG8_WAIT_V(n) asm volatile("s_waitcnt vmcnt(" #n ")" ::: "memory")
; #define PG8_BAR __builtin_amdgcn_s_barrier()
; template <class Epi, class Sched, bool ALIGN_EPI = false, bool SP2 = false>
; __device__ __forceinline__ void gemm_phase(PG8_LAS unsigned char* lds, const Gemm g, const Sched& S, const Epi& E, int wv) {
;     ...
;     for (int i = 0; i < 2; ++i) { int R, C; stage_rc(tid * 16 + i * 8192, R, C); const int Rb = Epi::PERM ? ((R & ~31) + perm32(R & 31)) : R;
;         voffA[i] = (unsigned)(R * g.lda + C) * 2u; voffB[i] = (unsigned)(Rb * K + C) * 2u; }
;     ...
;         PG8_STAGE(PG8_SB(0, 0), cB, voffB); PG8_STAGE(PG8_SB(0, 1), cB + hstepB, voffB); PG8_STAGE(PG8_SA(0, 0), cA, voffA); PG8_STAGE(PG8_SA(0, 1), cA + hstepA, voffA);
;         if (wr == 1) PG8_BAR;
;         PG8_WAIT_V(2); PG8_BAR;
;         PG8_STAGE(PG8_SB(1, 0), cB + kstep, voffB); PG8_STAGE(PG8_SA(1, 0), cA + kstep, voffA); PG8_STAGE(PG8_SB(1, 1), cB + hstepB + kstep, voffB);
;         PG8_WAIT_V(6); PG8_BAR;
.LBB0_1962:
	v_readlane_b32 s28, v254, 63
	s_add_u32 s26, s18, 0x2800000
	v_readlane_b32 s29, v255, 0
	s_addc_u32 s27, s19, 0
	s_lshl_b64 s[28:29], s[28:29], 2
	s_add_u32 s20, s20, s28
	s_addc_u32 s21, s21, s29
	s_add_u32 s22, s22, s28
	s_addc_u32 s23, s23, s29
	v_readlane_b32 s28, v254, 50
	v_readlane_b32 s29, v254, 51
	s_and_b64 s[28:29], s[28:29], exec
	s_cselect_b32 s29, 0, s17
	s_cselect_b32 s28, 0, s16
	s_add_u32 s36, s18, 0x1e800000
	s_addc_u32 s37, s19, 0
	s_lshl_b32 s16, s40, 5
	s_and_b32 s82, s16, 0x60
	s_add_i32 m0, s51, 0x18000
	v_lshl_add_u64 v[8:9], v[8:9], 0, s[62:63]
	s_lshl_b32 s58, s39, 6
	s_lshl_b32 s18, s39, 13
	s_lshl_b32 s19, s82, 7
	s_waitcnt vmcnt(2)
	s_barrier
	global_load_lds_dwordx4 v[8:9], off
	v_lshl_add_u64 v[6:7], v[6:7], 0, s[62:63]
	s_add_i32 m0, s51, 0x1a000
	s_add_i32 s83, s51, 0x8000
	s_add_i32 s87, s51, 0xa000
	global_load_lds_dwordx4 v[6:7], off
	v_lshl_add_u64 v[2:3], v[2:3], 0, s[62:63]
	s_mov_b32 m0, s83
	s_add_u32 s16, s2, 0xb0080
	global_load_lds_dwordx4 v[2:3], off
	v_lshl_add_u64 v[2:3], v[4:5], 0, s[62:63]
	s_mov_b32 m0, s87
	s_addc_u32 s17, s3, 0
	global_load_lds_dwordx4 v[2:3], off
	s_add_i32 m0, s51, 0x1c000
	s_nop 0
	global_load_lds_dwordx4 v0, s[16:17]
	v_lshl_add_u64 v[2:3], s[16:17], 0, v[134:135]
	s_add_i32 m0, s51, 0x1e000
	v_bfe_u32 v159, v10, 4, 2
	global_load_lds_dwordx4 v[2:3], off
	v_and_b32_e32 v158, 15, v10
	v_lshlrev_b32_e32 v2, 4, v159
	v_lshlrev_b32_e32 v3, 2, v10
	v_lshl_or_b32 v2, v158, 6, v2
	v_and_b32_e32 v3, 32, v3
	v_bitop3_b32 v160, s19, v2, v3 bitop3:0xf6
	s_movk_i32 s19, 0xb00
	v_bitop3_b32 v4, v2, s18, v3 bitop3:0xde
	v_lshrrev_b32_e32 v3, 1, v11
	v_mul_lo_u32 v2, v13, s19
	s_mov_b32 s18, 0xb000
	v_mad_u64_u32 v[2:3], s[16:17], v3, s18, v[2:3]
	v_or_b32_e32 v2, v2, v12
	v_add_lshl_u32 v2, v2, v14, 1
	v_mov_b32_e32 v3, v1
	s_mov_b64 s[40:41], 0xb0080
	v_lshl_add_u64 v[136:137], v[2:3], 0, s[40:41]
	v_lshrrev_b32_e32 v3, 1, v15
	v_mul_lo_u32 v2, v17, s19
	s_cmpk_lt_u32 s38, 0x100
	v_mad_u64_u32 v[2:3], s[16:17], v3, s18, v[2:3]
	s_waitcnt vmcnt(6)
	s_cselect_b64 s[38:39], -1, 0
	s_ashr_i32 s91, s12, 31
	s_ashr_i32 s92, s7, 31
	v_or_b32_e32 v2, v2, v16
	s_cmp_lg_u64 s[28:29], 0
	v_add_lshl_u32 v2, v2, v18, 1
	v_mov_b32_e32 v3, v1
	s_mov_b32 s90, 0
	s_cselect_b64 s[44:45], -1, 0
	v_lshl_add_u64 v[138:139], v[2:3], 0, s[40:41]
	v_add_u32_e32 v161, 0, v4
	s_barrier
	s_branch .LBB0_1965

; #define PG8_STAGE(bufoff, gbase, voff) do { _Pragma("unroll") for (int _i = 0; _i < 2; ++_i) \
;         __builtin_amdgcn_global_load_lds((const unsigned*)((const char*)(gbase) + (voff)[_i]), (PG8_LAS unsigned*)(lds + (bufoff) + ldsw + _i * 8192), 16, 0, 0); } while (0)
; #define PG8_LDA(dst, b, h) do { _Pragma("unroll") for (int m = 0; m < 4; ++m) _Pragma("unroll") for (int k = 0; k < 2; ++k) dst[m][k] = *(const PG8_LAS bf16x8*)(lds + PG8_SA(b, h) + aoff + m * 2048 + k * 1024); } while (0)
; #define PG8_LDB(dst, b, h) do { _Pragma("unroll") for (int n = 0; n < 2; ++n) _Pragma("unroll") for (int k = 0; k < 2; ++k) dst[n][k] = *(const PG8_LAS bf16x8*)(lds + PG8_SB(b, h) + boff + n * 2048 + k * 1024); } while (0)
; #define PG8_MMA(ai, bj, At, Bt) do { __builtin_amdgcn_s_setprio(1); _Pragma("unroll") for (int m = 0; m < 4; ++m) _Pragma("unroll") for (int n = 0; n < 2; ++n) _Pragma("unroll") for (int k = 0; k < 2; ++k) \
;         acc[ai][bj][m][n] = __builtin_amdgcn_mfma_f32_16x16x32_bf16(Bt[n][k], At[m][k], acc[ai][bj][m][n], 0, 0, 0); __builtin_amdgcn_s_setprio(0); } while (0)
; template <class Epi, class Sched, bool ALIGN_EPI = false, bool SP2 = false>
; __device__ __forceinline__ void gemm_phase(PG8_LAS unsigned char* lds, const Gemm g, const Sched& S, const Epi& E, int wv) {
;     ...
;         const bool has_next = S.next(ui + 1, nxt);
;         const char* nA = has_next ? (const char*)g.A + (size_t)nxt.pm * tstepA : cA; const char* nB = has_next ? (const char*)g.Bt + (size_t)nxt.pn * tstepB : cB;
; #pragma unroll 1
;         for (int t = 0; t < nt; t += 2) {
;             const bool last = (t == nt - 2);
;             const char* a1 = cA + (size_t)(t + 1) * kstep;
;             const char* a2 = last ? nA : cA + (size_t)(t + 2) * kstep; const char* b2 = last ? nB : cB + (size_t)(t + 2) * kstep;
;             const char* a3 = a2 + kstep; const char* b3 = b2 + kstep;
;             if (last && has_next) S.a_ready(nxt);
;             if constexpr (SP2) {
;             PG8_LDB(B0, 0, 0); PG8_LDB(B1, 0, 1); PG8_SCHED; PG8_LDA(At, 0, 0); PG8_STAGE(PG8_SA(1, 1), a1 + hstepA, voffA);
;             PG8_WAIT_V(8); PG8_WAIT_L(0); PG8_BAR; PG8_MMA(0, 0, At, B0); PG8_MMA(0, 1, At, B1); PG8_BAR; PG8_SCHED;
;             PG8_LDA(At, 0, 1); PG8_STAGE(PG8_SB(0, 0), b2, voffB); PG8_STAGE(PG8_SB(0, 1), b2 + hstepB, voffB); PG8_STAGE(PG8_SA(0, 0), a2, voffA);
.LBB0_1976:
	s_add_u32 s2, s34, 0x100
	s_addc_u32 s3, s35, 0
	s_add_i32 s60, 0, 0x10000
	s_cmp_eq_u32 vcc_lo, 40
	s_cselect_b32 s41, s47, s3
	s_cselect_b32 s40, s46, s2
	s_cselect_b32 s19, s49, s97
	s_cselect_b32 s18, s48, s96
	s_add_i32 s61, 0, 0x14000
	v_add_u32_e32 v152, s60, v160
	v_add_u32_e32 v156, s61, v160
	ds_read_b128 v[140:143], v152
	ds_read_b128 v[144:147], v152 offset:1024
	ds_read_b128 v[148:151], v152 offset:2048
	ds_read_b128 v[152:155], v152 offset:3072
	ds_read_b128 v[162:165], v156
	ds_read_b128 v[166:169], v156 offset:1024
	ds_read_b128 v[170:173], v156 offset:2048
	ds_read_b128 v[174:177], v156 offset:3072
	v_lshl_add_u64 v[156:157], s[34:35], 0, v[136:137]
	s_add_i32 m0, s51, 0xc000
	ds_read_b128 v[178:181], v161
	ds_read_b128 v[182:185], v161 offset:1024
	ds_read_b128 v[220:223], v161 offset:2048
	ds_read_b128 v[224:227], v161 offset:3072
	ds_read_b128 v[228:231], v161 offset:4096
	ds_read_b128 v[242:245], v161 offset:5120
	ds_read_b128 v[246:249], v161 offset:6144
	ds_read_b128 v[250:253], v161 offset:7168
	global_load_lds_dwordx4 v[156:157], off
	v_lshl_add_u64 v[156:157], s[34:35], 0, v[138:139]
	s_add_i32 m0, s51, 0xe000
	s_nop 0
	global_load_lds_dwordx4 v[156:157], off
	s_waitcnt vmcnt(8)
	s_waitcnt lgkmcnt(0)
	s_barrier
	s_setprio 1
	s_waitcnt lgkmcnt(0)
	v_mfma_f32_16x16x32_bf16 v[126:129], v[140:143], v[178:181], v[126:129]
	v_mfma_f32_16x16x32_bf16 v[122:125], v[148:151], v[178:181], v[122:125]
	v_mfma_f32_16x16x32_bf16 v[110:113], v[140:143], v[220:223], v[110:113]
	v_mfma_f32_16x16x32_bf16 v[106:109], v[148:151], v[220:223], v[106:109]
	v_mfma_f32_16x16x32_bf16 v[94:97], v[140:143], v[228:231], v[94:97]
	v_mfma_f32_16x16x32_bf16 v[90:93], v[148:151], v[228:231], v[90:93]
	v_mfma_f32_16x16x32_bf16 v[78:81], v[140:143], v[246:249], v[78:81]
	v_mfma_f32_16x16x32_bf16 v[74:77], v[148:151], v[246:249], v[74:77]
	v_mfma_f32_16x16x32_bf16 v[126:129], v[144:147], v[182:185], v[126:129]
	v_mfma_f32_16x16x32_bf16 v[122:125], v[152:155], v[182:185], v[122:125]
	v_mfma_f32_16x16x32_bf16 v[110:113], v[144:147], v[224:227], v[110:113]
	v_mfma_f32_16x16x32_bf16 v[106:109], v[152:155], v[224:227], v[106:109]
	v_mfma_f32_16x16x32_bf16 v[94:97], v[144:147], v[242:245], v[94:97]
	v_mfma_f32_16x16x32_bf16 v[90:93], v[152:155], v[242:245], v[90:93]
	v_mfma_f32_16x16x32_bf16 v[78:81], v[144:147], v[250:253], v[78:81]
	v_mfma_f32_16x16x32_bf16 v[74:77], v[152:155], v[250:253], v[74:77]
	s_setprio 0
	s_setprio 1
	v_mfma_f32_16x16x32_bf16 v[118:121], v[162:165], v[178:181], v[118:121]
	v_mfma_f32_16x16x32_bf16 v[114:117], v[170:173], v[178:181], v[114:117]
	v_mfma_f32_16x16x32_bf16 v[102:105], v[162:165], v[220:223], v[102:105]
	v_mfma_f32_16x16x32_bf16 v[98:101], v[170:173], v[220:223], v[98:101]
	v_mfma_f32_16x16x32_bf16 v[86:89], v[162:165], v[228:231], v[86:89]
	v_mfma_f32_16x16x32_bf16 v[82:85], v[170:173], v[228:231], v[82:85]
	v_mfma_f32_16x16x32_bf16 v[70:73], v[162:165], v[246:249], v[70:73]
	v_mfma_f32_16x16x32_bf16 v[66:69], v[170:173], v[246:249], v[66:69]
	v_mfma_f32_16x16x32_bf16 v[118:121], v[166:169], v[182:185], v[118:121]
	v_mfma_f32_16x16x32_bf16 v[114:117], v[174:177], v[182:185], v[114:117]
	v_mfma_f32_16x16x32_bf16 v[102:105], v[166:169], v[224:227], v[102:105]
	v_mfma_f32_16x16x32_bf16 v[98:101], v[174:177], v[224:227], v[98:101]
	v_mfma_f32_16x16x32_bf16 v[86:89], v[166:169], v[242:245], v[86:89]
	v_mfma_f32_16x16x32_bf16 v[82:85], v[174:177], v[242:245], v[82:85]
	v_mfma_f32_16x16x32_bf16 v[70:73], v[166:169], v[250:253], v[70:73]
	v_mfma_f32_16x16x32_bf16 v[66:69], v[174:177], v[250:253], v[66:69]
	s_setprio 0
	s_barrier
	s_add_i32 s34, s60, s50
	v_lshl_add_u64 v[156:157], s[18:19], 0, v[0:1]
	s_mov_b32 m0, s34
	ds_read_b128 v[178:181], v161 offset:16384
	ds_read_b128 v[182:185], v161 offset:17408
	ds_read_b128 v[220:223], v161 offset:18432
	ds_read_b128 v[224:227], v161 offset:19456
	ds_read_b128 v[228:231], v161 offset:20480
	ds_read_b128 v[242:245], v161 offset:21504
	ds_read_b128 v[246:249], v161 offset:22528
	ds_read_b128 v[250:253], v161 offset:23552
	global_load_lds_dwordx4 v[156:157], off
	s_add_i32 m0, s34, 0x2000
	s_add_u32 s34, s18, 0xb0000
	v_lshl_add_u64 v[186:187], s[18:19], 0, v[134:135]
	s_addc_u32 s35, s19, 0
	s_add_i32 s60, s61, s50
	global_load_lds_dwordx4 v[186:187], off
	s_mov_b32 m0, s60
	v_lshl_add_u64 v[232:233], s[40:41], 0, v[132:133]
	global_load_lds_dwordx4 v0, s[34:35]
	s_add_i32 m0, s60, 0x2000
	s_nop 0
	global_load_lds_dwordx4 v134, s[34:35]
	v_lshl_add_u64 v[196:197], s[40:41], 0, v[130:131]
	s_mov_b32 m0, s51
	s_nop 0
	global_load_lds_dwordx4 v[196:197], off
	s_mov_b32 m0, s52
	s_nop 0
	global_load_lds_dwordx4 v[232:233], off
	s_waitcnt vmcnt(8)
	s_waitcnt lgkmcnt(0)
	s_barrier
; #define PG8_STAGE(bufoff, gbase, voff) do { _Pragma("unroll") for (int _i = 0; _i < 2; ++_i) \
;         __builtin_amdgcn_global_load_lds((const unsigned*)((const char*)(gbase) + (voff)[_i]), (PG8_LAS unsigned*)(lds + (bufoff) + ldsw + _i * 8192), 16, 0, 0); } while (0)
; #define PG8_LDA(dst, b, h) do { _Pragma("unroll") for (int m = 0; m < 4; ++m) _Pragma("unroll") for (int k = 0; k < 2; ++k) dst[m][k] = *(const PG8_LAS bf16x8*)(lds + PG8_SA(b, h) + aoff + m * 2048 + k * 1024); } while (0)
; #define PG8_LDB(dst, b, h) do { _Pragma("unroll") for (int n = 0; n < 2; ++n) _Pragma("unroll") for (int k = 0; k < 2; ++k) dst[n][k] = *(const PG8_LAS bf16x8*)(lds + PG8_SB(b, h) + boff + n * 2048 + k * 1024); } while (0)
; #define PG8_MMA(ai, bj, At, Bt) do { __builtin_amdgcn_s_setprio(1); _Pragma("unroll") for (int m = 0; m < 4; ++m) _Pragma("unroll") for (int n = 0; n < 2; ++n) _Pragma("unroll") for (int k = 0; k < 2; ++k) \
;         acc[ai][bj][m][n] = __builtin_amdgcn_mfma_f32_16x16x32_bf16(Bt[n][k], At[m][k], acc[ai][bj][m][n], 0, 0, 0); __builtin_amdgcn_s_setprio(0); } while (0)
; #define PG8_WAIT_V(n) asm volatile("s_waitcnt vmcnt(" #n ")" ::: "memory")
; #define PG8_WAIT_L(n) asm volatile("s_waitcnt lgkmcnt(" #n ")" ::: "memory")
; #define PG8_BAR __builtin_amdgcn_s_barrier()
; #define PG8_SCHED __builtin_amdgcn_sched_barrier(0)
; template <class Epi, class Sched, bool ALIGN_EPI = false, bool SP2 = false>
; __device__ __forceinline__ void gemm_phase(PG8_LAS unsigned char* lds, const Gemm g, const Sched& S, const Epi& E, int wv) {
;     ...
;             PG8_WAIT_V(8); PG8_WAIT_L(0); PG8_BAR; PG8_MMA(1, 0, At, B0); PG8_MMA(1, 1, At, B1); PG8_BAR; PG8_SCHED;
;             PG8_LDB(B0, 1, 0); PG8_LDB(B1, 1, 1); PG8_SCHED; PG8_LDA(At, 1, 0); PG8_STAGE(PG8_SA(0, 1), a2 + hstepA, voffA);
;             PG8_WAIT_V(8); PG8_WAIT_L(0); PG8_BAR; PG8_MMA(0, 0, At, B0); PG8_MMA(0, 1, At, B1); PG8_BAR; PG8_SCHED;
	s_setprio 1
	s_waitcnt lgkmcnt(0)
	v_mfma_f32_16x16x32_bf16 v[62:65], v[140:143], v[178:181], v[62:65]
	v_mfma_f32_16x16x32_bf16 v[58:61], v[148:151], v[178:181], v[58:61]
	v_mfma_f32_16x16x32_bf16 v[46:49], v[140:143], v[220:223], v[46:49]
	v_mfma_f32_16x16x32_bf16 v[42:45], v[148:151], v[220:223], v[42:45]
	v_mfma_f32_16x16x32_bf16 v[30:33], v[140:143], v[228:231], v[30:33]
	v_mfma_f32_16x16x32_bf16 v[26:29], v[148:151], v[228:231], v[26:29]
	v_mfma_f32_16x16x32_bf16 v[14:17], v[140:143], v[246:249], v[14:17]
	v_mfma_f32_16x16x32_bf16 v[10:13], v[148:151], v[246:249], v[10:13]
	v_mfma_f32_16x16x32_bf16 v[62:65], v[144:147], v[182:185], v[62:65]
	v_mfma_f32_16x16x32_bf16 v[58:61], v[152:155], v[182:185], v[58:61]
	v_mfma_f32_16x16x32_bf16 v[46:49], v[144:147], v[224:227], v[46:49]
	v_mfma_f32_16x16x32_bf16 v[42:45], v[152:155], v[224:227], v[42:45]
	v_mfma_f32_16x16x32_bf16 v[30:33], v[144:147], v[242:245], v[30:33]
	v_mfma_f32_16x16x32_bf16 v[26:29], v[152:155], v[242:245], v[26:29]
	v_mfma_f32_16x16x32_bf16 v[14:17], v[144:147], v[250:253], v[14:17]
	v_mfma_f32_16x16x32_bf16 v[10:13], v[152:155], v[250:253], v[10:13]
	s_setprio 0
	s_setprio 1
	v_mfma_f32_16x16x32_bf16 v[54:57], v[162:165], v[178:181], v[54:57]
	v_mfma_f32_16x16x32_bf16 v[50:53], v[170:173], v[178:181], v[50:53]
	v_mfma_f32_16x16x32_bf16 v[38:41], v[162:165], v[220:223], v[38:41]
	v_mfma_f32_16x16x32_bf16 v[34:37], v[170:173], v[220:223], v[34:37]
	v_mfma_f32_16x16x32_bf16 v[22:25], v[162:165], v[228:231], v[22:25]
	v_mfma_f32_16x16x32_bf16 v[18:21], v[170:173], v[228:231], v[18:21]
	v_mfma_f32_16x16x32_bf16 v[6:9], v[162:165], v[246:249], v[6:9]
	v_mfma_f32_16x16x32_bf16 v[2:5], v[170:173], v[246:249], v[2:5]
	v_mfma_f32_16x16x32_bf16 v[54:57], v[166:169], v[182:185], v[54:57]
	v_mfma_f32_16x16x32_bf16 v[50:53], v[174:177], v[182:185], v[50:53]
	v_mfma_f32_16x16x32_bf16 v[38:41], v[166:169], v[224:227], v[38:41]
	v_mfma_f32_16x16x32_bf16 v[34:37], v[174:177], v[224:227], v[34:37]
	v_mfma_f32_16x16x32_bf16 v[22:25], v[166:169], v[242:245], v[22:25]
	v_mfma_f32_16x16x32_bf16 v[18:21], v[174:177], v[242:245], v[18:21]
	v_mfma_f32_16x16x32_bf16 v[6:9], v[166:169], v[250:253], v[6:9]
	v_mfma_f32_16x16x32_bf16 v[2:5], v[174:177], v[250:253], v[2:5]
	s_setprio 0
	s_barrier
	s_add_i32 s60, 0, 0x18000
	s_add_i32 s61, 0, 0x1c000
	v_add_u32_e32 v152, s60, v160
	v_add_u32_e32 v174, s61, v160
	ds_read_b128 v[140:143], v152
	ds_read_b128 v[144:147], v152 offset:1024
	ds_read_b128 v[148:151], v152 offset:2048
	ds_read_b128 v[152:155], v152 offset:3072
	ds_read_b128 v[162:165], v174
	ds_read_b128 v[166:169], v174 offset:1024
	ds_read_b128 v[170:173], v174 offset:2048
	ds_read_b128 v[174:177], v174 offset:3072
	s_add_u32 s34, s40, 0xb0000
	s_addc_u32 s35, s41, 0
	s_mov_b32 m0, s53
	ds_read_b128 v[178:181], v161 offset:32768
	ds_read_b128 v[182:185], v161 offset:33792
	ds_read_b128 v[220:223], v161 offset:34816
	ds_read_b128 v[224:227], v161 offset:35840
	ds_read_b128 v[228:231], v161 offset:36864
	ds_read_b128 v[242:245], v161 offset:37888
	ds_read_b128 v[246:249], v161 offset:38912
	ds_read_b128 v[250:253], v161 offset:39936
	global_load_lds_dwordx4 v130, s[34:35]
	v_lshl_add_u64 v[234:235], s[34:35], 0, v[132:133]
	s_mov_b32 m0, s55
	s_nop 0
	global_load_lds_dwordx4 v[234:235], off
	s_waitcnt vmcnt(8)
	s_waitcnt lgkmcnt(0)
	s_barrier
	s_setprio 1
	s_waitcnt lgkmcnt(0)
	v_mfma_f32_16x16x32_bf16 v[126:129], v[140:143], v[178:181], v[126:129]
	v_mfma_f32_16x16x32_bf16 v[122:125], v[148:151], v[178:181], v[122:125]
	v_mfma_f32_16x16x32_bf16 v[110:113], v[140:143], v[220:223], v[110:113]
	v_mfma_f32_16x16x32_bf16 v[106:109], v[148:151], v[220:223], v[106:109]
	v_mfma_f32_16x16x32_bf16 v[94:97], v[140:143], v[228:231], v[94:97]
	v_mfma_f32_16x16x32_bf16 v[90:93], v[148:151], v[228:231], v[90:93]
	v_mfma_f32_16x16x32_bf16 v[78:81], v[140:143], v[246:249], v[78:81]
	v_mfma_f32_16x16x32_bf16 v[74:77], v[148:151], v[246:249], v[74:77]
	v_mfma_f32_16x16x32_bf16 v[126:129], v[144:147], v[182:185], v[126:129]
	v_mfma_f32_16x16x32_bf16 v[122:125], v[152:155], v[182:185], v[122:125]
	v_mfma_f32_16x16x32_bf16 v[110:113], v[144:147], v[224:227], v[110:113]
	v_mfma_f32_16x16x32_bf16 v[106:109], v[152:155], v[224:227], v[106:109]
	v_mfma_f32_16x16x32_bf16 v[94:97], v[144:147], v[242:245], v[94:97]
	v_mfma_f32_16x16x32_bf16 v[90:93], v[152:155], v[242:245], v[90:93]
	v_mfma_f32_16x16x32_bf16 v[78:81], v[144:147], v[250:253], v[78:81]
	v_mfma_f32_16x16x32_bf16 v[74:77], v[152:155], v[250:253], v[74:77]
	s_setprio 0
	s_setprio 1
	v_mfma_f32_16x16x32_bf16 v[118:121], v[162:165], v[178:181], v[118:121]
	v_mfma_f32_16x16x32_bf16 v[114:117], v[170:173], v[178:181], v[114:117]
	v_mfma_f32_16x16x32_bf16 v[102:105], v[162:165], v[220:223], v[102:105]
	v_mfma_f32_16x16x32_bf16 v[98:101], v[170:173], v[220:223], v[98:101]
	v_mfma_f32_16x16x32_bf16 v[86:89], v[162:165], v[228:231], v[86:89]
	v_mfma_f32_16x16x32_bf16 v[82:85], v[170:173], v[228:231], v[82:85]
	v_mfma_f32_16x16x32_bf16 v[70:73], v[162:165], v[246:249], v[70:73]
	v_mfma_f32_16x16x32_bf16 v[66:69], v[170:173], v[246:249], v[66:69]
	v_mfma_f32_16x16x32_bf16 v[118:121], v[166:169], v[182:185], v[118:121]
	v_mfma_f32_16x16x32_bf16 v[114:117], v[174:177], v[182:185], v[114:117]
	v_mfma_f32_16x16x32_bf16 v[102:105], v[166:169], v[224:227], v[102:105]
	v_mfma_f32_16x16x32_bf16 v[98:101], v[174:177], v[224:227], v[98:101]
	v_mfma_f32_16x16x32_bf16 v[86:89], v[166:169], v[242:245], v[86:89]
	v_mfma_f32_16x16x32_bf16 v[82:85], v[174:177], v[242:245], v[82:85]
	v_mfma_f32_16x16x32_bf16 v[70:73], v[166:169], v[250:253], v[70:73]
	v_mfma_f32_16x16x32_bf16 v[66:69], v[174:177], v[250:253], v[66:69]
	s_setprio 0
	s_barrier
; #define PG8_STAGE(bufoff, gbase, voff) do { _Pragma("unroll") for (int _i = 0; _i < 2; ++_i) \
;         __builtin_amdgcn_global_load_lds((const unsigned*)((const char*)(gbase) + (voff)[_i]), (PG8_LAS unsigned*)(lds + (bufoff) + ldsw + _i * 8192), 16, 0, 0); } while (0)
; #define PG8_LDA(dst, b, h) do { _Pragma("unroll") for (int m = 0; m < 4; ++m) _Pragma("unroll") for (int k = 0; k < 2; ++k) dst[m][k] = *(const PG8_LAS bf16x8*)(lds + PG8_SA(b, h) + aoff + m * 2048 + k * 1024); } while (0)
; #define PG8_MMA(ai, bj, At, Bt) do { __builtin_amdgcn_s_setprio(1); _Pragma("unroll") for (int m = 0; m < 4; ++m) _Pragma("unroll") for (int n = 0; n < 2; ++n) _Pragma("unroll") for (int k = 0; k < 2; ++k) \
;         acc[ai][bj][m][n] = __builtin_amdgcn_mfma_f32_16x16x32_bf16(Bt[n][k], At[m][k], acc[ai][bj][m][n], 0, 0, 0); __builtin_amdgcn_s_setprio(0); } while (0)
; #define PG8_WAIT_V(n) asm volatile("s_waitcnt vmcnt(" #n ")" ::: "memory")
; #define PG8_WAIT_L(n) asm volatile("s_waitcnt lgkmcnt(" #n ")" ::: "memory")
; #define PG8_BAR __builtin_amdgcn_s_barrier()
; #define PG8_SCHED __builtin_amdgcn_sched_barrier(0)
; template <class Epi, class Sched, bool ALIGN_EPI = false, bool SP2 = false>
; __device__ __forceinline__ void gemm_phase(PG8_LAS unsigned char* lds, const Gemm g, const Sched& S, const Epi& E, int wv) {
;     ...
;         for (int t = 0; t < nt; t += 2) {
;     ...
;             PG8_LDA(At, 1, 1); PG8_STAGE(PG8_SB(1, 0), b3, voffB); PG8_STAGE(PG8_SB(1, 1), b3 + hstepB, voffB); PG8_STAGE(PG8_SA(1, 0), a3, voffA);
;             PG8_WAIT_V(8); PG8_WAIT_L(0); PG8_BAR; PG8_MMA(1, 0, At, B0); PG8_MMA(1, 1, At, B1); PG8_BAR; PG8_SCHED;
	s_add_i32 s34, s60, s50
	v_lshl_add_u64 v[156:157], v[156:157], 0, s[62:63]
	s_mov_b32 m0, s34
	ds_read_b128 v[178:181], v161 offset:49152
	ds_read_b128 v[182:185], v161 offset:50176
	ds_read_b128 v[220:223], v161 offset:51200
	ds_read_b128 v[224:227], v161 offset:52224
	ds_read_b128 v[228:231], v161 offset:53248
	ds_read_b128 v[242:245], v161 offset:54272
	ds_read_b128 v[246:249], v161 offset:55296
	ds_read_b128 v[250:253], v161 offset:56320
	global_load_lds_dwordx4 v[156:157], off
	s_add_i32 m0, s34, 0x2000
	s_add_u32 s18, s18, 0xb0080
	v_lshl_add_u64 v[156:157], v[186:187], 0, s[62:63]
	s_addc_u32 s19, s19, 0
	s_add_i32 s34, s61, s50
	global_load_lds_dwordx4 v[156:157], off
	s_mov_b32 m0, s34
	s_nop 0
	global_load_lds_dwordx4 v0, s[18:19]
	s_add_i32 m0, s34, 0x2000
	s_nop 0
	global_load_lds_dwordx4 v134, s[18:19]
	v_lshl_add_u64 v[156:157], v[196:197], 0, s[62:63]
	s_mov_b32 m0, s83
	s_nop 0
	global_load_lds_dwordx4 v[156:157], off
	v_lshl_add_u64 v[156:157], v[232:233], 0, s[62:63]
	s_mov_b32 m0, s87
	s_nop 0
	global_load_lds_dwordx4 v[156:157], off
	s_waitcnt vmcnt(8)
	s_waitcnt lgkmcnt(0)
	s_barrier
	s_setprio 1
	s_waitcnt lgkmcnt(0)
	v_mfma_f32_16x16x32_bf16 v[62:65], v[140:143], v[178:181], v[62:65]
	v_mfma_f32_16x16x32_bf16 v[58:61], v[148:151], v[178:181], v[58:61]
	v_mfma_f32_16x16x32_bf16 v[46:49], v[140:143], v[220:223], v[46:49]
	v_mfma_f32_16x16x32_bf16 v[42:45], v[148:151], v[220:223], v[42:45]
	v_mfma_f32_16x16x32_bf16 v[30:33], v[140:143], v[228:231], v[30:33]
	v_mfma_f32_16x16x32_bf16 v[26:29], v[148:151], v[228:231], v[26:29]
	v_mfma_f32_16x16x32_bf16 v[14:17], v[140:143], v[246:249], v[14:17]
	v_mfma_f32_16x16x32_bf16 v[10:13], v[148:151], v[246:249], v[10:13]
	v_mfma_f32_16x16x32_bf16 v[62:65], v[144:147], v[182:185], v[62:65]
	v_mfma_f32_16x16x32_bf16 v[58:61], v[152:155], v[182:185], v[58:61]
	v_mfma_f32_16x16x32_bf16 v[46:49], v[144:147], v[224:227], v[46:49]
	v_mfma_f32_16x16x32_bf16 v[42:45], v[152:155], v[224:227], v[42:45]
	v_mfma_f32_16x16x32_bf16 v[30:33], v[144:147], v[242:245], v[30:33]
	v_mfma_f32_16x16x32_bf16 v[26:29], v[152:155], v[242:245], v[26:29]
	v_mfma_f32_16x16x32_bf16 v[14:17], v[144:147], v[250:253], v[14:17]
	v_mfma_f32_16x16x32_bf16 v[10:13], v[152:155], v[250:253], v[10:13]
	s_setprio 0
	s_setprio 1
	v_mfma_f32_16x16x32_bf16 v[54:57], v[162:165], v[178:181], v[54:57]
	v_mfma_f32_16x16x32_bf16 v[50:53], v[170:173], v[178:181], v[50:53]
	v_mfma_f32_16x16x32_bf16 v[38:41], v[162:165], v[220:223], v[38:41]
	v_mfma_f32_16x16x32_bf16 v[34:37], v[170:173], v[220:223], v[34:37]
	v_mfma_f32_16x16x32_bf16 v[22:25], v[162:165], v[228:231], v[22:25]
	v_mfma_f32_16x16x32_bf16 v[18:21], v[170:173], v[228:231], v[18:21]
	v_mfma_f32_16x16x32_bf16 v[6:9], v[162:165], v[246:249], v[6:9]
	v_mfma_f32_16x16x32_bf16 v[2:5], v[170:173], v[246:249], v[2:5]
	v_mfma_f32_16x16x32_bf16 v[54:57], v[166:169], v[182:185], v[54:57]
	v_mfma_f32_16x16x32_bf16 v[50:53], v[174:177], v[182:185], v[50:53]
	v_mfma_f32_16x16x32_bf16 v[38:41], v[166:169], v[224:227], v[38:41]
	v_mfma_f32_16x16x32_bf16 v[34:37], v[174:177], v[224:227], v[34:37]
	v_mfma_f32_16x16x32_bf16 v[22:25], v[166:169], v[242:245], v[22:25]
	v_mfma_f32_16x16x32_bf16 v[18:21], v[174:177], v[242:245], v[18:21]
	v_mfma_f32_16x16x32_bf16 v[6:9], v[166:169], v[250:253], v[6:9]
	v_mfma_f32_16x16x32_bf16 v[2:5], v[174:177], v[250:253], v[2:5]
	s_setprio 0
	s_barrier
	s_add_i32 vcc_lo, vcc_lo, 2
	s_add_u32 s96, s96, 0x100
	s_addc_u32 s97, s97, 0
	s_cmp_gt_u32 vcc_lo, 41
	s_mov_b64 s[34:35], s[2:3]
	s_cbranch_scc0 .LBB0_1976
	s_and_b64 vcc, exec, s[38:39]
	s_cbranch_vccz .LBB0_1979
	s_barrier
